# v47 + 16-byte epilogue stores of in-proj / up-proj(q,kv) / out-proj written through (sc1) so the grid-sync L2 write-back has less to flush
# baseline (speedup 1.0000x reference)
; __device__ __forceinline__ unsigned cvt_pk_bf16(float lo, float hi) { unsigned r; asm volatile("v_cvt_pk_bf16_f32 %0, %1, %2" : "=v"(r) : "v"(lo), "v"(hi)); return r; }
; DI float shx(float v, int mask, int lane) { return __int_as_float(__builtin_amdgcn_ds_bpermute((lane ^ mask) << 2, __float_as_int(v))); }
;     DI void operator()(const f32x4 (&acc)[2][2][4][2], const Unit& u, int wr, int wc, int fr, int fq) const {
;     ...
;         const int col0 = pn * 256 + wc * 32 + 8 * fq;
; #pragma unroll
;         for (int ai = 0; ai < 2; ++ai)
; #pragma unroll
;             for (int m = 0; m < 4; ++m) { const int row = row0 + ai * 128 + m * 16; const float s = rs[row]; bf16_t* rowp = O + (size_t)row * 2048 + col0;
;                 f32x4 v[2][2];
; #pragma unroll
;                 for (int bj = 0; bj < 2; ++bj) { v[bj][0] = acc[ai][bj][m][0] * s; v[bj][1] = acc[ai][bj][m][1] * s; u32x4 w;
;                     w.x = cvt_pk_bf16(v[bj][0][0], v[bj][0][1]); w.y = cvt_pk_bf16(v[bj][0][2], v[bj][0][3]); w.z = cvt_pk_bf16(v[bj][1][0], v[bj][1][1]); w.w = cvt_pk_bf16(v[bj][1][2], v[bj][1][3]);
;                     *(u32x4*)(rowp + bj * 128) = w; }
;                 if (pn < 2) {
;                     float s0 = 0.f, s1 = 0.f;
; #pragma unroll
;                     for (int n = 0; n < 2; ++n) { s0 += (v[0][n][0] * v[0][n][0] + v[0][n][1] * v[0][n][1]) + (v[0][n][2] * v[0][n][2] + v[0][n][3] * v[0][n][3]);
;                                                   s1 += (v[1][n][0] * v[1][n][0] + v[1][n][1] * v[1][n][1]) + (v[1][n][2] * v[1][n][2] + v[1][n][3] * v[1][n][3]); }
;                     if (pn == 0) { float ss = s0 + s1; ss += shx(ss, 16, ln); ss += shx(ss, 32, ln); if (fq == 0) ssq4[(size_t)row * 4 + wc] = ss; }
;                     else { s0 += shx(s0, 16, ln); s0 += shx(s0, 32, ln); if (fq == 0) sskv4[(size_t)row * 4 + wc] = s0;
;                         if (wc < 2) { s1 += shx(s1, 16, ln); s1 += shx(s1, 32, ln); if (fq == 0) sskr2[(size_t)row * 2 + wc] = s1;
.LBB0_1651:
	v_lshl_add_u64 v[158:159], v[154:155], 2, s[18:19]
	global_load_dword v136, v[158:159], off
	v_lshl_or_b32 v156, s48, 8, v181
	s_cmp_lt_i32 s48, 2
	v_lshlrev_b64 v[160:161], 12, v[154:155]
	v_ashrrev_i32_e32 v157, 31, v156
	s_cselect_b64 s[6:7], -1, 0
	s_cmp_lg_u32 s48, 0
	v_lshl_add_u64 v[160:161], s[14:15], 0, v[160:161]
	s_cselect_b64 s[8:9], -1, 0
	s_cmp_gt_i32 s48, 1
	v_lshl_add_u64 v[176:177], v[156:157], 1, v[160:161]
	s_waitcnt vmcnt(0)
	v_mul_f32_e32 v172, v126, v136
	v_mul_f32_e32 v173, v127, v136
	v_mul_f32_e32 v174, v124, v136
	v_mul_f32_e32 v175, v125, v136
	v_mul_f32_e32 v168, v122, v136
	v_mul_f32_e32 v169, v123, v136
	v_mul_f32_e32 v170, v120, v136
	v_mul_f32_e32 v171, v121, v136
	v_mul_f32_e32 v160, v118, v136
	v_mul_f32_e32 v161, v119, v136
	v_mul_f32_e32 v162, v116, v136
	v_mul_f32_e32 v163, v117, v136
	v_mul_f32_e32 v164, v114, v136
	v_mul_f32_e32 v165, v115, v136
	v_mul_f32_e32 v166, v112, v136
	v_mul_f32_e32 v167, v113, v136
	v_cvt_pk_bf16_f32 v188, v174, v175
	v_cvt_pk_bf16_f32 v189, v172, v173
	v_cvt_pk_bf16_f32 v190, v170, v171
	v_cvt_pk_bf16_f32 v191, v168, v169
	global_store_dwordx4 v[176:177], v[188:191], off sc1
	s_nop 1
	v_cvt_pk_bf16_f32 v188, v162, v163
	v_cvt_pk_bf16_f32 v189, v160, v161
	v_cvt_pk_bf16_f32 v190, v166, v167
	v_cvt_pk_bf16_f32 v191, v164, v165
	global_store_dwordx4 v[176:177], v[188:191], off offset:256 sc1
	s_cbranch_scc1 .LBB0_1664
	v_mul_f32_e32 v136, v175, v175
	v_mul_f32_e32 v173, v173, v173
	v_mul_f32_e32 v171, v171, v171
	v_mul_f32_e32 v169, v169, v169
	v_fmac_f32_e32 v136, v174, v174
	v_fmac_f32_e32 v173, v172, v172
	v_fmac_f32_e32 v171, v170, v170
	v_fmac_f32_e32 v169, v168, v168
	v_add_f32_e32 v136, v136, v173
	v_add_f32_e32 v168, v171, v169
	v_mul_f32_e32 v172, v163, v163
	v_mul_f32_e32 v173, v161, v161
	v_add_f32_e32 v168, v136, v168
	v_mul_f32_e32 v136, v167, v167
	v_mul_f32_e32 v169, v165, v165
	v_fmac_f32_e32 v172, v162, v162
	v_fmac_f32_e32 v173, v160, v160
	v_fmac_f32_e32 v136, v166, v166
	v_fmac_f32_e32 v169, v164, v164
	v_add_f32_e32 v172, v172, v173
	v_add_f32_e32 v136, v136, v169
	v_add_f32_e32 v169, v172, v136
	s_and_b64 vcc, exec, s[8:9]
	s_cbranch_vccz .LBB0_1660
	ds_bpermute_b32 v136, v179, v168
	s_waitcnt lgkmcnt(0)
	v_add_f32_e32 v136, v168, v136
	ds_bpermute_b32 v170, v180, v136
	s_and_saveexec_b64 s[76:77], s[0:1]
	s_cbranch_execz .LBB0_1655
	v_lshl_add_u64 v[172:173], v[154:155], 4, s[60:61]
	s_waitcnt lgkmcnt(0)
	v_add_f32_e32 v136, v136, v170
	global_store_dword v[172:173], v136, off

;     DI void operator()(const f32x4 (&acc)[2][2][4][2], const Unit& u, int wr, int wc, int fr, int fq) const {
;     ...
;                             const int i0 = 16 * wc + 4 * fq, pos = row & (SEQ - 1); const f32x4 c = *(const f32x4*)(cs + pos * 32 + i0), sv = *(const f32x4*)(sn + pos * 32 + i0);
;                             *(f32x4*)(KR + (size_t)row * 64 + i0) = v[1][0] * c - v[1][1] * sv; *(f32x4*)(KR + (size_t)row * 64 + 32 + i0) = v[1][1] * c + v[1][0] * sv; } } } }
.LBB0_1658:
	s_or_b64 exec, exec, s[76:77]
	v_lshlrev_b32_e32 v136, 7, v154
	v_and_b32_e32 v136, 0x7e780, v136
	s_waitcnt lgkmcnt(0)
	v_lshl_add_u64 v[170:171], v[142:143], 0, v[136:137]
	global_load_dwordx4 v[170:173], v[170:171], off
	v_lshl_add_u64 v[174:175], v[140:141], 0, v[136:137]
	global_load_dwordx4 v[174:177], v[174:175], off
	v_lshlrev_b64 v[188:189], 8, v[154:155]
	v_lshl_add_u64 v[188:189], v[144:145], 0, v[188:189]
	s_waitcnt vmcnt(1)
	v_mul_f32_e32 v190, v164, v172
	v_mul_f32_e32 v191, v165, v173
	v_mul_f32_e32 v192, v166, v170
	v_mul_f32_e32 v193, v167, v171
	v_mul_f32_e32 v194, v160, v172
	v_mul_f32_e32 v195, v161, v173
	v_mul_f32_e32 v196, v162, v170
	v_mul_f32_e32 v197, v163, v171
	s_waitcnt vmcnt(0)
	v_pk_fma_f32 v[172:173], v[160:161], v[176:177], v[190:191] neg_lo:[0,0,1] neg_hi:[0,0,1]
	v_pk_fma_f32 v[170:171], v[162:163], v[174:175], v[192:193] neg_lo:[0,0,1] neg_hi:[0,0,1]
	v_fma_f32 v162, v164, v176, v194
	v_fma_f32 v163, v165, v177, v195
	v_fma_f32 v160, v166, v174, v196
	v_fma_f32 v161, v167, v175, v197
	global_store_dwordx4 v[188:189], v[170:173], off sc1
	global_store_dwordx4 v[188:189], v[160:163], off offset:128 sc1

; __device__ __forceinline__ unsigned cvt_pk_bf16(float lo, float hi) { unsigned r; asm volatile("v_cvt_pk_bf16_f32 %0, %1, %2" : "=v"(r) : "v"(lo), "v"(hi)); return r; }
; DI float shx(float v, int mask, int lane) { return __int_as_float(__builtin_amdgcn_ds_bpermute((lane ^ mask) << 2, __float_as_int(v))); }
;     DI void operator()(const f32x4 (&acc)[2][2][4][2], const Unit& u, int wr, int wc, int fr, int fq) const {
;     ...
;             for (int m = 0; m < 4; ++m) { const int row = row0 + ai * 128 + m * 16; const float s = rs[row]; bf16_t* rowp = O + (size_t)row * 2048 + col0;
;                 f32x4 v[2][2];
; #pragma unroll
;                 for (int bj = 0; bj < 2; ++bj) { v[bj][0] = acc[ai][bj][m][0] * s; v[bj][1] = acc[ai][bj][m][1] * s; u32x4 w;
;                     w.x = cvt_pk_bf16(v[bj][0][0], v[bj][0][1]); w.y = cvt_pk_bf16(v[bj][0][2], v[bj][0][3]); w.z = cvt_pk_bf16(v[bj][1][0], v[bj][1][1]); w.w = cvt_pk_bf16(v[bj][1][2], v[bj][1][3]);
;                     *(u32x4*)(rowp + bj * 128) = w; }
;                 if (pn < 2) {
;                     float s0 = 0.f, s1 = 0.f;
; #pragma unroll
;                     for (int n = 0; n < 2; ++n) { s0 += (v[0][n][0] * v[0][n][0] + v[0][n][1] * v[0][n][1]) + (v[0][n][2] * v[0][n][2] + v[0][n][3] * v[0][n][3]);
;                                                   s1 += (v[1][n][0] * v[1][n][0] + v[1][n][1] * v[1][n][1]) + (v[1][n][2] * v[1][n][2] + v[1][n][3] * v[1][n][3]); }
;                     if (pn == 0) { float ss = s0 + s1; ss += shx(ss, 16, ln); ss += shx(ss, 32, ln); if (fq == 0) ssq4[(size_t)row * 4 + wc] = ss; }
;                     else { s0 += shx(s0, 16, ln); s0 += shx(s0, 32, ln); if (fq == 0) sskv4[(size_t)row * 4 + wc] = s0;
;                         if (wc < 2) { s1 += shx(s1, 16, ln); s1 += shx(s1, 32, ln); if (fq == 0) sskr2[(size_t)row * 2 + wc] = s1;
.LBB0_1664:
	s_waitcnt lgkmcnt(0)
	v_or_b32_e32 v160, 16, v154
	v_ashrrev_i32_e32 v161, 31, v160
	v_lshl_add_u64 v[162:163], v[160:161], 2, s[18:19]
	global_load_dword v136, v[162:163], off
	v_cndmask_b32_e64 v162, 0, 1, s[6:7]
	v_cndmask_b32_e64 v187, 0, 1, s[8:9]
	v_cmp_ne_u32_e64 s[8:9], 1, v162
	v_lshlrev_b64 v[162:163], 12, v[160:161]
	v_lshl_add_u64 v[162:163], s[14:15], 0, v[162:163]
	s_andn2_b64 vcc, exec, s[6:7]
	v_lshl_add_u64 v[192:193], v[156:157], 1, v[162:163]
	v_cmp_ne_u32_e64 s[6:7], 1, v187
	s_waitcnt vmcnt(0)
	v_mul_f32_e32 v174, v110, v136
	v_mul_f32_e32 v175, v111, v136
	v_mul_f32_e32 v176, v108, v136
	v_mul_f32_e32 v177, v109, v136
	v_mul_f32_e32 v170, v106, v136
	v_mul_f32_e32 v171, v107, v136
	v_mul_f32_e32 v172, v104, v136
	v_mul_f32_e32 v173, v105, v136
	v_mul_f32_e32 v162, v102, v136
	v_mul_f32_e32 v163, v103, v136
	v_mul_f32_e32 v168, v100, v136
	v_mul_f32_e32 v169, v101, v136
	v_mul_f32_e32 v164, v98, v136
	v_mul_f32_e32 v165, v99, v136
	v_mul_f32_e32 v166, v96, v136
	v_mul_f32_e32 v167, v97, v136
	v_cvt_pk_bf16_f32 v188, v176, v177
	v_cvt_pk_bf16_f32 v189, v174, v175
	v_cvt_pk_bf16_f32 v190, v172, v173
	v_cvt_pk_bf16_f32 v191, v170, v171
	global_store_dwordx4 v[192:193], v[188:191], off sc1
	s_nop 1
	v_cvt_pk_bf16_f32 v188, v168, v169
	v_cvt_pk_bf16_f32 v189, v162, v163
	v_cvt_pk_bf16_f32 v190, v166, v167
	v_cvt_pk_bf16_f32 v191, v164, v165
	global_store_dwordx4 v[192:193], v[188:191], off offset:256 sc1
	s_cbranch_vccnz .LBB0_1677
	v_mul_f32_e32 v136, v177, v177
	v_mul_f32_e32 v175, v175, v175
	v_mul_f32_e32 v173, v173, v173
	v_mul_f32_e32 v171, v171, v171
	v_fmac_f32_e32 v136, v176, v176
	v_fmac_f32_e32 v175, v174, v174
	v_fmac_f32_e32 v173, v172, v172
	v_fmac_f32_e32 v171, v170, v170
	v_add_f32_e32 v136, v136, v175
	v_add_f32_e32 v170, v173, v171
	v_mul_f32_e32 v174, v169, v169
	v_mul_f32_e32 v175, v163, v163
	v_add_f32_e32 v170, v136, v170
	v_mul_f32_e32 v136, v167, v167
	v_mul_f32_e32 v171, v165, v165
	v_fmac_f32_e32 v174, v168, v168
	v_fmac_f32_e32 v175, v162, v162
	v_fmac_f32_e32 v136, v166, v166
	v_fmac_f32_e32 v171, v164, v164
	v_add_f32_e32 v174, v174, v175
	v_add_f32_e32 v136, v136, v171
	s_and_b64 vcc, exec, s[6:7]
	v_add_f32_e32 v171, v174, v136
	s_cbranch_vccnz .LBB0_1673
	ds_bpermute_b32 v136, v179, v170
	s_waitcnt lgkmcnt(0)
	v_add_f32_e32 v136, v170, v136
	ds_bpermute_b32 v172, v180, v136
	s_and_saveexec_b64 s[76:77], s[0:1]
	s_cbranch_execz .LBB0_1668
	v_lshl_add_u64 v[174:175], v[160:161], 4, s[60:61]
	s_waitcnt lgkmcnt(0)
	v_add_f32_e32 v136, v136, v172
	global_store_dword v[174:175], v136, off

;     DI void operator()(const f32x4 (&acc)[2][2][4][2], const Unit& u, int wr, int wc, int fr, int fq) const {
;     ...
;                             const int i0 = 16 * wc + 4 * fq, pos = row & (SEQ - 1); const f32x4 c = *(const f32x4*)(cs + pos * 32 + i0), sv = *(const f32x4*)(sn + pos * 32 + i0);
;                             *(f32x4*)(KR + (size_t)row * 64 + i0) = v[1][0] * c - v[1][1] * sv; *(f32x4*)(KR + (size_t)row * 64 + 32 + i0) = v[1][1] * c + v[1][0] * sv; } } } }
.LBB0_1671:
	s_or_b64 exec, exec, s[76:77]
	v_lshlrev_b32_e32 v136, 7, v160
	v_and_b32_e32 v136, 0x7ef80, v136
	s_waitcnt lgkmcnt(0)
	v_lshl_add_u64 v[172:173], v[142:143], 0, v[136:137]
	global_load_dwordx4 v[172:175], v[172:173], off
	v_lshl_add_u64 v[176:177], v[140:141], 0, v[136:137]
	global_load_dwordx4 v[188:191], v[176:177], off
	v_lshlrev_b64 v[176:177], 8, v[160:161]
	v_lshl_add_u64 v[176:177], v[144:145], 0, v[176:177]
	s_waitcnt vmcnt(1)
	v_mul_f32_e32 v192, v164, v174
	v_mul_f32_e32 v193, v165, v175
	v_mul_f32_e32 v194, v166, v172
	v_mul_f32_e32 v195, v167, v173
	v_mul_f32_e32 v196, v162, v174
	v_mul_f32_e32 v197, v163, v175
	v_mul_f32_e32 v198, v168, v172
	v_mul_f32_e32 v199, v169, v173
	s_waitcnt vmcnt(0)
	v_pk_fma_f32 v[174:175], v[162:163], v[190:191], v[192:193] neg_lo:[0,0,1] neg_hi:[0,0,1]
	v_pk_fma_f32 v[172:173], v[168:169], v[188:189], v[194:195] neg_lo:[0,0,1] neg_hi:[0,0,1]
	v_fma_f32 v164, v164, v190, v196
	v_fma_f32 v165, v165, v191, v197
	v_fma_f32 v162, v166, v188, v198
	v_fma_f32 v163, v167, v189, v199
	global_store_dwordx4 v[176:177], v[172:175], off sc1
	global_store_dwordx4 v[176:177], v[162:165], off offset:128 sc1

; __device__ __forceinline__ unsigned cvt_pk_bf16(float lo, float hi) { unsigned r; asm volatile("v_cvt_pk_bf16_f32 %0, %1, %2" : "=v"(r) : "v"(lo), "v"(hi)); return r; }
; DI float shx(float v, int mask, int lane) { return __int_as_float(__builtin_amdgcn_ds_bpermute((lane ^ mask) << 2, __float_as_int(v))); }
;     DI void operator()(const f32x4 (&acc)[2][2][4][2], const Unit& u, int wr, int wc, int fr, int fq) const {
;     ...
;             for (int m = 0; m < 4; ++m) { const int row = row0 + ai * 128 + m * 16; const float s = rs[row]; bf16_t* rowp = O + (size_t)row * 2048 + col0;
;                 f32x4 v[2][2];
; #pragma unroll
;                 for (int bj = 0; bj < 2; ++bj) { v[bj][0] = acc[ai][bj][m][0] * s; v[bj][1] = acc[ai][bj][m][1] * s; u32x4 w;
;                     w.x = cvt_pk_bf16(v[bj][0][0], v[bj][0][1]); w.y = cvt_pk_bf16(v[bj][0][2], v[bj][0][3]); w.z = cvt_pk_bf16(v[bj][1][0], v[bj][1][1]); w.w = cvt_pk_bf16(v[bj][1][2], v[bj][1][3]);
;                     *(u32x4*)(rowp + bj * 128) = w; }
;                 if (pn < 2) {
;                     float s0 = 0.f, s1 = 0.f;
; #pragma unroll
;                     for (int n = 0; n < 2; ++n) { s0 += (v[0][n][0] * v[0][n][0] + v[0][n][1] * v[0][n][1]) + (v[0][n][2] * v[0][n][2] + v[0][n][3] * v[0][n][3]);
;                                                   s1 += (v[1][n][0] * v[1][n][0] + v[1][n][1] * v[1][n][1]) + (v[1][n][2] * v[1][n][2] + v[1][n][3] * v[1][n][3]); }
;                     if (pn == 0) { float ss = s0 + s1; ss += shx(ss, 16, ln); ss += shx(ss, 32, ln); if (fq == 0) ssq4[(size_t)row * 4 + wc] = ss; }
;                     else { s0 += shx(s0, 16, ln); s0 += shx(s0, 32, ln); if (fq == 0) sskv4[(size_t)row * 4 + wc] = s0;
;                         if (wc < 2) { s1 += shx(s1, 16, ln); s1 += shx(s1, 32, ln); if (fq == 0) sskr2[(size_t)row * 2 + wc] = s1;
.LBB0_1677:
	v_or_b32_e32 v160, 32, v154
	v_ashrrev_i32_e32 v161, 31, v160
	s_waitcnt lgkmcnt(0)
	v_lshl_add_u64 v[162:163], v[160:161], 2, s[18:19]
	global_load_dword v136, v[162:163], off
	v_lshlrev_b64 v[162:163], 12, v[160:161]
	v_lshl_add_u64 v[162:163], s[14:15], 0, v[162:163]
	v_lshl_add_u64 v[192:193], v[156:157], 1, v[162:163]
	s_and_b64 vcc, exec, s[8:9]
	s_waitcnt vmcnt(0)
	v_mul_f32_e32 v174, v94, v136
	v_mul_f32_e32 v175, v95, v136
	v_mul_f32_e32 v176, v92, v136
	v_mul_f32_e32 v177, v93, v136
	v_mul_f32_e32 v170, v90, v136
	v_mul_f32_e32 v171, v91, v136
	v_mul_f32_e32 v172, v88, v136
	v_mul_f32_e32 v173, v89, v136
	v_mul_f32_e32 v162, v86, v136
	v_mul_f32_e32 v163, v87, v136
	v_mul_f32_e32 v164, v84, v136
	v_mul_f32_e32 v165, v85, v136
	v_mul_f32_e32 v166, v82, v136
	v_mul_f32_e32 v167, v83, v136
	v_mul_f32_e32 v168, v80, v136
	v_mul_f32_e32 v169, v81, v136
	v_cvt_pk_bf16_f32 v188, v176, v177
	v_cvt_pk_bf16_f32 v189, v174, v175
	v_cvt_pk_bf16_f32 v190, v172, v173
	v_cvt_pk_bf16_f32 v191, v170, v171
	global_store_dwordx4 v[192:193], v[188:191], off sc1
	s_nop 1
	v_cvt_pk_bf16_f32 v188, v164, v165
	v_cvt_pk_bf16_f32 v189, v162, v163
	v_cvt_pk_bf16_f32 v190, v168, v169
	v_cvt_pk_bf16_f32 v191, v166, v167
	global_store_dwordx4 v[192:193], v[188:191], off offset:256 sc1
	s_cbranch_vccnz .LBB0_1690
	v_mul_f32_e32 v136, v177, v177
	v_mul_f32_e32 v175, v175, v175
	v_mul_f32_e32 v173, v173, v173
	v_mul_f32_e32 v171, v171, v171
	v_fmac_f32_e32 v136, v176, v176
	v_fmac_f32_e32 v175, v174, v174
	v_fmac_f32_e32 v173, v172, v172
	v_fmac_f32_e32 v171, v170, v170
	v_add_f32_e32 v136, v136, v175
	v_add_f32_e32 v170, v173, v171
	v_mul_f32_e32 v174, v165, v165
	v_mul_f32_e32 v175, v163, v163
	v_add_f32_e32 v170, v136, v170
	v_mul_f32_e32 v136, v169, v169
	v_mul_f32_e32 v171, v167, v167
	v_fmac_f32_e32 v174, v164, v164
	v_fmac_f32_e32 v175, v162, v162
	v_fmac_f32_e32 v136, v168, v168
	v_fmac_f32_e32 v171, v166, v166
	v_add_f32_e32 v174, v174, v175
	v_add_f32_e32 v136, v136, v171
	s_and_b64 vcc, exec, s[6:7]
	v_add_f32_e32 v171, v174, v136
	s_cbranch_vccnz .LBB0_1686
	ds_bpermute_b32 v136, v179, v170
	s_waitcnt lgkmcnt(0)
	v_add_f32_e32 v136, v170, v136
	ds_bpermute_b32 v172, v180, v136
	s_and_saveexec_b64 s[76:77], s[0:1]
	s_cbranch_execz .LBB0_1681
	v_lshl_add_u64 v[174:175], v[160:161], 4, s[60:61]
	s_waitcnt lgkmcnt(0)
	v_add_f32_e32 v136, v136, v172
	global_store_dword v[174:175], v136, off

;     DI void operator()(const f32x4 (&acc)[2][2][4][2], const Unit& u, int wr, int wc, int fr, int fq) const {
;     ...
;                             const int i0 = 16 * wc + 4 * fq, pos = row & (SEQ - 1); const f32x4 c = *(const f32x4*)(cs + pos * 32 + i0), sv = *(const f32x4*)(sn + pos * 32 + i0);
;                             *(f32x4*)(KR + (size_t)row * 64 + i0) = v[1][0] * c - v[1][1] * sv; *(f32x4*)(KR + (size_t)row * 64 + 32 + i0) = v[1][1] * c + v[1][0] * sv; } } } }
.LBB0_1684:
	s_or_b64 exec, exec, s[76:77]
	v_lshlrev_b32_e32 v136, 7, v160
	v_and_b32_e32 v136, 0x7f780, v136
	s_waitcnt lgkmcnt(0)
	v_lshl_add_u64 v[172:173], v[142:143], 0, v[136:137]
	global_load_dwordx4 v[172:175], v[172:173], off
	v_lshl_add_u64 v[176:177], v[140:141], 0, v[136:137]
	global_load_dwordx4 v[188:191], v[176:177], off
	v_lshlrev_b64 v[176:177], 8, v[160:161]
	v_lshl_add_u64 v[176:177], v[144:145], 0, v[176:177]
	s_waitcnt vmcnt(1)
	v_mul_f32_e32 v192, v166, v174
	v_mul_f32_e32 v193, v167, v175
	v_mul_f32_e32 v194, v168, v172
	v_mul_f32_e32 v195, v169, v173
	v_mul_f32_e32 v196, v162, v174
	v_mul_f32_e32 v197, v163, v175
	v_mul_f32_e32 v198, v164, v172
	v_mul_f32_e32 v199, v165, v173
	s_waitcnt vmcnt(0)
	v_pk_fma_f32 v[174:175], v[162:163], v[190:191], v[192:193] neg_lo:[0,0,1] neg_hi:[0,0,1]
	v_pk_fma_f32 v[172:173], v[164:165], v[188:189], v[194:195] neg_lo:[0,0,1] neg_hi:[0,0,1]
	v_fma_f32 v164, v166, v190, v196
	v_fma_f32 v165, v167, v191, v197
	v_fma_f32 v162, v168, v188, v198
	v_fma_f32 v163, v169, v189, v199
	global_store_dwordx4 v[176:177], v[172:175], off sc1
	global_store_dwordx4 v[176:177], v[162:165], off offset:128 sc1

; __device__ __forceinline__ unsigned cvt_pk_bf16(float lo, float hi) { unsigned r; asm volatile("v_cvt_pk_bf16_f32 %0, %1, %2" : "=v"(r) : "v"(lo), "v"(hi)); return r; }
; DI float shx(float v, int mask, int lane) { return __int_as_float(__builtin_amdgcn_ds_bpermute((lane ^ mask) << 2, __float_as_int(v))); }
;     DI void operator()(const f32x4 (&acc)[2][2][4][2], const Unit& u, int wr, int wc, int fr, int fq) const {
;     ...
;             for (int m = 0; m < 4; ++m) { const int row = row0 + ai * 128 + m * 16; const float s = rs[row]; bf16_t* rowp = O + (size_t)row * 2048 + col0;
;                 f32x4 v[2][2];
; #pragma unroll
;                 for (int bj = 0; bj < 2; ++bj) { v[bj][0] = acc[ai][bj][m][0] * s; v[bj][1] = acc[ai][bj][m][1] * s; u32x4 w;
;                     w.x = cvt_pk_bf16(v[bj][0][0], v[bj][0][1]); w.y = cvt_pk_bf16(v[bj][0][2], v[bj][0][3]); w.z = cvt_pk_bf16(v[bj][1][0], v[bj][1][1]); w.w = cvt_pk_bf16(v[bj][1][2], v[bj][1][3]);
;                     *(u32x4*)(rowp + bj * 128) = w; }
;                 if (pn < 2) {
;                     float s0 = 0.f, s1 = 0.f;
; #pragma unroll
;                     for (int n = 0; n < 2; ++n) { s0 += (v[0][n][0] * v[0][n][0] + v[0][n][1] * v[0][n][1]) + (v[0][n][2] * v[0][n][2] + v[0][n][3] * v[0][n][3]);
;                                                   s1 += (v[1][n][0] * v[1][n][0] + v[1][n][1] * v[1][n][1]) + (v[1][n][2] * v[1][n][2] + v[1][n][3] * v[1][n][3]); }
;                     if (pn == 0) { float ss = s0 + s1; ss += shx(ss, 16, ln); ss += shx(ss, 32, ln); if (fq == 0) ssq4[(size_t)row * 4 + wc] = ss; }
;                     else { s0 += shx(s0, 16, ln); s0 += shx(s0, 32, ln); if (fq == 0) sskv4[(size_t)row * 4 + wc] = s0;
;                         if (wc < 2) { s1 += shx(s1, 16, ln); s1 += shx(s1, 32, ln); if (fq == 0) sskr2[(size_t)row * 2 + wc] = s1;
.LBB0_1690:
	v_or_b32_e32 v160, 48, v154
	v_ashrrev_i32_e32 v161, 31, v160
	s_waitcnt lgkmcnt(0)
	v_lshl_add_u64 v[162:163], v[160:161], 2, s[18:19]
	global_load_dword v136, v[162:163], off
	v_lshlrev_b64 v[162:163], 12, v[160:161]
	v_lshl_add_u64 v[162:163], s[14:15], 0, v[162:163]
	v_lshl_add_u64 v[192:193], v[156:157], 1, v[162:163]
	s_and_b64 vcc, exec, s[8:9]
	s_waitcnt vmcnt(0)
	v_mul_f32_e32 v174, v78, v136
	v_mul_f32_e32 v175, v79, v136
	v_mul_f32_e32 v176, v76, v136
	v_mul_f32_e32 v177, v77, v136
	v_mul_f32_e32 v170, v74, v136
	v_mul_f32_e32 v171, v75, v136
	v_mul_f32_e32 v172, v72, v136
	v_mul_f32_e32 v173, v73, v136
	v_mul_f32_e32 v162, v70, v136
	v_mul_f32_e32 v163, v71, v136
	v_mul_f32_e32 v164, v68, v136
	v_mul_f32_e32 v165, v69, v136
	v_mul_f32_e32 v166, v66, v136
	v_mul_f32_e32 v167, v67, v136
	v_mul_f32_e32 v168, v64, v136
	v_mul_f32_e32 v169, v65, v136
	v_cvt_pk_bf16_f32 v188, v176, v177
	v_cvt_pk_bf16_f32 v189, v174, v175
	v_cvt_pk_bf16_f32 v190, v172, v173
	v_cvt_pk_bf16_f32 v191, v170, v171
	global_store_dwordx4 v[192:193], v[188:191], off sc1
	s_nop 1
	v_cvt_pk_bf16_f32 v188, v164, v165
	v_cvt_pk_bf16_f32 v189, v162, v163
	v_cvt_pk_bf16_f32 v190, v168, v169
	v_cvt_pk_bf16_f32 v191, v166, v167
	global_store_dwordx4 v[192:193], v[188:191], off offset:256 sc1
	s_cbranch_vccnz .LBB0_1703
	v_mul_f32_e32 v136, v177, v177
	v_mul_f32_e32 v175, v175, v175
	v_mul_f32_e32 v173, v173, v173
	v_mul_f32_e32 v171, v171, v171
	v_fmac_f32_e32 v136, v176, v176
	v_fmac_f32_e32 v175, v174, v174
	v_fmac_f32_e32 v173, v172, v172
	v_fmac_f32_e32 v171, v170, v170
	v_add_f32_e32 v136, v136, v175
	v_add_f32_e32 v170, v173, v171
	v_mul_f32_e32 v174, v165, v165
	v_mul_f32_e32 v175, v163, v163
	v_add_f32_e32 v170, v136, v170
	v_mul_f32_e32 v136, v169, v169
	v_mul_f32_e32 v171, v167, v167
	v_fmac_f32_e32 v174, v164, v164
	v_fmac_f32_e32 v175, v162, v162
	v_fmac_f32_e32 v136, v168, v168
	v_fmac_f32_e32 v171, v166, v166
	v_add_f32_e32 v174, v174, v175
	v_add_f32_e32 v136, v136, v171
	s_and_b64 vcc, exec, s[6:7]
	v_add_f32_e32 v171, v174, v136
	s_cbranch_vccnz .LBB0_1699
	ds_bpermute_b32 v136, v179, v170
	s_waitcnt lgkmcnt(0)
	v_add_f32_e32 v136, v170, v136
	ds_bpermute_b32 v172, v180, v136
	s_and_saveexec_b64 s[76:77], s[0:1]
	s_cbranch_execz .LBB0_1694
	v_lshl_add_u64 v[174:175], v[160:161], 4, s[60:61]
	s_waitcnt lgkmcnt(0)
	v_add_f32_e32 v136, v136, v172
	global_store_dword v[174:175], v136, off

;     DI void operator()(const f32x4 (&acc)[2][2][4][2], const Unit& u, int wr, int wc, int fr, int fq) const {
;     ...
;                             const int i0 = 16 * wc + 4 * fq, pos = row & (SEQ - 1); const f32x4 c = *(const f32x4*)(cs + pos * 32 + i0), sv = *(const f32x4*)(sn + pos * 32 + i0);
;                             *(f32x4*)(KR + (size_t)row * 64 + i0) = v[1][0] * c - v[1][1] * sv; *(f32x4*)(KR + (size_t)row * 64 + 32 + i0) = v[1][1] * c + v[1][0] * sv; } } } }
.LBB0_1697:
	s_or_b64 exec, exec, s[76:77]
	v_lshlrev_b32_e32 v136, 7, v160
	v_and_b32_e32 v136, 0x7ff80, v136
	s_waitcnt lgkmcnt(0)
	v_lshl_add_u64 v[172:173], v[142:143], 0, v[136:137]
	global_load_dwordx4 v[172:175], v[172:173], off
	v_lshl_add_u64 v[176:177], v[140:141], 0, v[136:137]
	global_load_dwordx4 v[188:191], v[176:177], off
	v_lshlrev_b64 v[176:177], 8, v[160:161]
	v_lshl_add_u64 v[176:177], v[144:145], 0, v[176:177]
	s_waitcnt vmcnt(1)
	v_mul_f32_e32 v192, v166, v174
	v_mul_f32_e32 v193, v167, v175
	v_mul_f32_e32 v194, v168, v172
	v_mul_f32_e32 v195, v169, v173
	v_mul_f32_e32 v196, v162, v174
	v_mul_f32_e32 v197, v163, v175
	v_mul_f32_e32 v198, v164, v172
	v_mul_f32_e32 v199, v165, v173
	s_waitcnt vmcnt(0)
	v_pk_fma_f32 v[174:175], v[162:163], v[190:191], v[192:193] neg_lo:[0,0,1] neg_hi:[0,0,1]
	v_pk_fma_f32 v[172:173], v[164:165], v[188:189], v[194:195] neg_lo:[0,0,1] neg_hi:[0,0,1]
	v_fma_f32 v164, v166, v190, v196
	v_fma_f32 v165, v167, v191, v197
	v_fma_f32 v162, v168, v188, v198
	v_fma_f32 v163, v169, v189, v199
	global_store_dwordx4 v[176:177], v[172:175], off sc1
	global_store_dwordx4 v[176:177], v[162:165], off offset:128 sc1

; __device__ __forceinline__ unsigned cvt_pk_bf16(float lo, float hi) { unsigned r; asm volatile("v_cvt_pk_bf16_f32 %0, %1, %2" : "=v"(r) : "v"(lo), "v"(hi)); return r; }
; DI float shx(float v, int mask, int lane) { return __int_as_float(__builtin_amdgcn_ds_bpermute((lane ^ mask) << 2, __float_as_int(v))); }
;     DI void operator()(const f32x4 (&acc)[2][2][4][2], const Unit& u, int wr, int wc, int fr, int fq) const {
;     ...
;             for (int m = 0; m < 4; ++m) { const int row = row0 + ai * 128 + m * 16; const float s = rs[row]; bf16_t* rowp = O + (size_t)row * 2048 + col0;
;                 f32x4 v[2][2];
; #pragma unroll
;                 for (int bj = 0; bj < 2; ++bj) { v[bj][0] = acc[ai][bj][m][0] * s; v[bj][1] = acc[ai][bj][m][1] * s; u32x4 w;
;                     w.x = cvt_pk_bf16(v[bj][0][0], v[bj][0][1]); w.y = cvt_pk_bf16(v[bj][0][2], v[bj][0][3]); w.z = cvt_pk_bf16(v[bj][1][0], v[bj][1][1]); w.w = cvt_pk_bf16(v[bj][1][2], v[bj][1][3]);
;                     *(u32x4*)(rowp + bj * 128) = w; }
;                 if (pn < 2) {
;                     float s0 = 0.f, s1 = 0.f;
; #pragma unroll
;                     for (int n = 0; n < 2; ++n) { s0 += (v[0][n][0] * v[0][n][0] + v[0][n][1] * v[0][n][1]) + (v[0][n][2] * v[0][n][2] + v[0][n][3] * v[0][n][3]);
;                                                   s1 += (v[1][n][0] * v[1][n][0] + v[1][n][1] * v[1][n][1]) + (v[1][n][2] * v[1][n][2] + v[1][n][3] * v[1][n][3]); }
;                     if (pn == 0) { float ss = s0 + s1; ss += shx(ss, 16, ln); ss += shx(ss, 32, ln); if (fq == 0) ssq4[(size_t)row * 4 + wc] = ss; }
;                     else { s0 += shx(s0, 16, ln); s0 += shx(s0, 32, ln); if (fq == 0) sskv4[(size_t)row * 4 + wc] = s0;
;                         if (wc < 2) { s1 += shx(s1, 16, ln); s1 += shx(s1, 32, ln); if (fq == 0) sskr2[(size_t)row * 2 + wc] = s1;
.LBB0_1703:
	global_load_dword v136, v[158:159], off offset:512
	v_add_u32_e32 v160, 0x80, v154
	v_ashrrev_i32_e32 v161, 31, v160
	s_waitcnt lgkmcnt(0)
	v_lshlrev_b64 v[162:163], 12, v[160:161]
	v_lshl_add_u64 v[162:163], s[14:15], 0, v[162:163]
	v_lshl_add_u64 v[192:193], v[156:157], 1, v[162:163]
	s_and_b64 vcc, exec, s[8:9]
	s_waitcnt vmcnt(0)
	v_mul_f32_e32 v174, v62, v136
	v_mul_f32_e32 v175, v63, v136
	v_mul_f32_e32 v176, v60, v136
	v_mul_f32_e32 v177, v61, v136
	v_mul_f32_e32 v170, v58, v136
	v_mul_f32_e32 v171, v59, v136
	v_mul_f32_e32 v172, v56, v136
	v_mul_f32_e32 v173, v57, v136
	v_mul_f32_e32 v162, v54, v136
	v_mul_f32_e32 v163, v55, v136
	v_mul_f32_e32 v164, v52, v136
	v_mul_f32_e32 v165, v53, v136
	v_mul_f32_e32 v166, v50, v136
	v_mul_f32_e32 v167, v51, v136
	v_mul_f32_e32 v168, v48, v136
	v_mul_f32_e32 v169, v49, v136
	v_cvt_pk_bf16_f32 v188, v176, v177
	v_cvt_pk_bf16_f32 v189, v174, v175
	v_cvt_pk_bf16_f32 v190, v172, v173
	v_cvt_pk_bf16_f32 v191, v170, v171
	global_store_dwordx4 v[192:193], v[188:191], off sc1
	s_nop 1
	v_cvt_pk_bf16_f32 v188, v164, v165
	v_cvt_pk_bf16_f32 v189, v162, v163
	v_cvt_pk_bf16_f32 v190, v168, v169
	v_cvt_pk_bf16_f32 v191, v166, v167
	global_store_dwordx4 v[192:193], v[188:191], off offset:256 sc1
	s_cbranch_vccnz .LBB0_1716
	v_mul_f32_e32 v136, v177, v177
	v_mul_f32_e32 v175, v175, v175
	v_mul_f32_e32 v173, v173, v173
	v_mul_f32_e32 v171, v171, v171
	v_fmac_f32_e32 v136, v176, v176
	v_fmac_f32_e32 v175, v174, v174
	v_fmac_f32_e32 v173, v172, v172
	v_fmac_f32_e32 v171, v170, v170
	v_add_f32_e32 v136, v136, v175
	v_add_f32_e32 v170, v173, v171
	v_mul_f32_e32 v174, v165, v165
	v_mul_f32_e32 v175, v163, v163
	v_add_f32_e32 v170, v136, v170
	v_mul_f32_e32 v136, v169, v169
	v_mul_f32_e32 v171, v167, v167
	v_fmac_f32_e32 v174, v164, v164
	v_fmac_f32_e32 v175, v162, v162
	v_fmac_f32_e32 v136, v168, v168
	v_fmac_f32_e32 v171, v166, v166
	v_add_f32_e32 v174, v174, v175
	v_add_f32_e32 v136, v136, v171
	s_and_b64 vcc, exec, s[6:7]
	v_add_f32_e32 v171, v174, v136
	s_cbranch_vccnz .LBB0_1712
	ds_bpermute_b32 v136, v179, v170
	s_waitcnt lgkmcnt(0)
	v_add_f32_e32 v136, v170, v136
	ds_bpermute_b32 v172, v180, v136
	s_and_saveexec_b64 s[76:77], s[0:1]
	s_cbranch_execz .LBB0_1707
	v_lshl_add_u64 v[174:175], v[160:161], 4, s[60:61]
	s_waitcnt lgkmcnt(0)
	v_add_f32_e32 v136, v136, v172
	global_store_dword v[174:175], v136, off

;     DI void operator()(const f32x4 (&acc)[2][2][4][2], const Unit& u, int wr, int wc, int fr, int fq) const {
;     ...
;                             const int i0 = 16 * wc + 4 * fq, pos = row & (SEQ - 1); const f32x4 c = *(const f32x4*)(cs + pos * 32 + i0), sv = *(const f32x4*)(sn + pos * 32 + i0);
;                             *(f32x4*)(KR + (size_t)row * 64 + i0) = v[1][0] * c - v[1][1] * sv; *(f32x4*)(KR + (size_t)row * 64 + 32 + i0) = v[1][1] * c + v[1][0] * sv; } } } }
.LBB0_1710:
	s_or_b64 exec, exec, s[76:77]
	v_lshlrev_b32_e32 v136, 7, v160
	v_and_b32_e32 v136, 0x7e780, v136
	s_waitcnt lgkmcnt(0)
	v_lshl_add_u64 v[172:173], v[142:143], 0, v[136:137]
	global_load_dwordx4 v[172:175], v[172:173], off
	v_lshl_add_u64 v[176:177], v[140:141], 0, v[136:137]
	global_load_dwordx4 v[188:191], v[176:177], off
	v_lshlrev_b64 v[176:177], 8, v[160:161]
	v_lshl_add_u64 v[176:177], v[144:145], 0, v[176:177]
	s_waitcnt vmcnt(1)
	v_mul_f32_e32 v192, v166, v174
	v_mul_f32_e32 v193, v167, v175
	v_mul_f32_e32 v194, v168, v172
	v_mul_f32_e32 v195, v169, v173
	v_mul_f32_e32 v196, v162, v174
	v_mul_f32_e32 v197, v163, v175
	v_mul_f32_e32 v198, v164, v172
	v_mul_f32_e32 v199, v165, v173
	s_waitcnt vmcnt(0)
	v_pk_fma_f32 v[174:175], v[162:163], v[190:191], v[192:193] neg_lo:[0,0,1] neg_hi:[0,0,1]
	v_pk_fma_f32 v[172:173], v[164:165], v[188:189], v[194:195] neg_lo:[0,0,1] neg_hi:[0,0,1]
	v_fma_f32 v164, v166, v190, v196
	v_fma_f32 v165, v167, v191, v197
	v_fma_f32 v162, v168, v188, v198
	v_fma_f32 v163, v169, v189, v199
	global_store_dwordx4 v[176:177], v[172:175], off sc1
	global_store_dwordx4 v[176:177], v[162:165], off offset:128 sc1

; __device__ __forceinline__ unsigned cvt_pk_bf16(float lo, float hi) { unsigned r; asm volatile("v_cvt_pk_bf16_f32 %0, %1, %2" : "=v"(r) : "v"(lo), "v"(hi)); return r; }
; DI float shx(float v, int mask, int lane) { return __int_as_float(__builtin_amdgcn_ds_bpermute((lane ^ mask) << 2, __float_as_int(v))); }
;     DI void operator()(const f32x4 (&acc)[2][2][4][2], const Unit& u, int wr, int wc, int fr, int fq) const {
;     ...
;             for (int m = 0; m < 4; ++m) { const int row = row0 + ai * 128 + m * 16; const float s = rs[row]; bf16_t* rowp = O + (size_t)row * 2048 + col0;
;                 f32x4 v[2][2];
; #pragma unroll
;                 for (int bj = 0; bj < 2; ++bj) { v[bj][0] = acc[ai][bj][m][0] * s; v[bj][1] = acc[ai][bj][m][1] * s; u32x4 w;
;                     w.x = cvt_pk_bf16(v[bj][0][0], v[bj][0][1]); w.y = cvt_pk_bf16(v[bj][0][2], v[bj][0][3]); w.z = cvt_pk_bf16(v[bj][1][0], v[bj][1][1]); w.w = cvt_pk_bf16(v[bj][1][2], v[bj][1][3]);
;                     *(u32x4*)(rowp + bj * 128) = w; }
;                 if (pn < 2) {
;                     float s0 = 0.f, s1 = 0.f;
; #pragma unroll
;                     for (int n = 0; n < 2; ++n) { s0 += (v[0][n][0] * v[0][n][0] + v[0][n][1] * v[0][n][1]) + (v[0][n][2] * v[0][n][2] + v[0][n][3] * v[0][n][3]);
;                                                   s1 += (v[1][n][0] * v[1][n][0] + v[1][n][1] * v[1][n][1]) + (v[1][n][2] * v[1][n][2] + v[1][n][3] * v[1][n][3]); }
;                     if (pn == 0) { float ss = s0 + s1; ss += shx(ss, 16, ln); ss += shx(ss, 32, ln); if (fq == 0) ssq4[(size_t)row * 4 + wc] = ss; }
;                     else { s0 += shx(s0, 16, ln); s0 += shx(s0, 32, ln); if (fq == 0) sskv4[(size_t)row * 4 + wc] = s0;
;                         if (wc < 2) { s1 += shx(s1, 16, ln); s1 += shx(s1, 32, ln); if (fq == 0) sskr2[(size_t)row * 2 + wc] = s1;
.LBB0_1716:
	global_load_dword v136, v[158:159], off offset:576
	v_add_u32_e32 v160, 0x90, v154
	v_ashrrev_i32_e32 v161, 31, v160
	s_waitcnt lgkmcnt(0)
	v_lshlrev_b64 v[162:163], 12, v[160:161]
	v_lshl_add_u64 v[162:163], s[14:15], 0, v[162:163]
	v_lshl_add_u64 v[192:193], v[156:157], 1, v[162:163]
	s_and_b64 vcc, exec, s[8:9]
	s_waitcnt vmcnt(0)
	v_mul_f32_e32 v174, v46, v136
	v_mul_f32_e32 v175, v47, v136
	v_mul_f32_e32 v176, v44, v136
	v_mul_f32_e32 v177, v45, v136
	v_mul_f32_e32 v170, v42, v136
	v_mul_f32_e32 v171, v43, v136
	v_mul_f32_e32 v172, v40, v136
	v_mul_f32_e32 v173, v41, v136
	v_mul_f32_e32 v162, v38, v136
	v_mul_f32_e32 v163, v39, v136
	v_mul_f32_e32 v164, v36, v136
	v_mul_f32_e32 v165, v37, v136
	v_mul_f32_e32 v166, v34, v136
	v_mul_f32_e32 v167, v35, v136
	v_mul_f32_e32 v168, v32, v136
	v_mul_f32_e32 v169, v33, v136
	v_cvt_pk_bf16_f32 v188, v176, v177
	v_cvt_pk_bf16_f32 v189, v174, v175
	v_cvt_pk_bf16_f32 v190, v172, v173
	v_cvt_pk_bf16_f32 v191, v170, v171
	global_store_dwordx4 v[192:193], v[188:191], off sc1
	s_nop 1
	v_cvt_pk_bf16_f32 v188, v164, v165
	v_cvt_pk_bf16_f32 v189, v162, v163
	v_cvt_pk_bf16_f32 v190, v168, v169
	v_cvt_pk_bf16_f32 v191, v166, v167
	global_store_dwordx4 v[192:193], v[188:191], off offset:256 sc1
	s_cbranch_vccnz .LBB0_1729
	v_mul_f32_e32 v136, v177, v177
	v_mul_f32_e32 v175, v175, v175
	v_mul_f32_e32 v173, v173, v173
	v_mul_f32_e32 v171, v171, v171
	v_fmac_f32_e32 v136, v176, v176
	v_fmac_f32_e32 v175, v174, v174
	v_fmac_f32_e32 v173, v172, v172
	v_fmac_f32_e32 v171, v170, v170
	v_add_f32_e32 v136, v136, v175
	v_add_f32_e32 v170, v173, v171
	v_mul_f32_e32 v174, v165, v165
	v_mul_f32_e32 v175, v163, v163
	v_add_f32_e32 v170, v136, v170
	v_mul_f32_e32 v136, v169, v169
	v_mul_f32_e32 v171, v167, v167
	v_fmac_f32_e32 v174, v164, v164
	v_fmac_f32_e32 v175, v162, v162
	v_fmac_f32_e32 v136, v168, v168
	v_fmac_f32_e32 v171, v166, v166
	v_add_f32_e32 v174, v174, v175
	v_add_f32_e32 v136, v136, v171
	s_and_b64 vcc, exec, s[6:7]
	v_add_f32_e32 v171, v174, v136
	s_cbranch_vccnz .LBB0_1725
	ds_bpermute_b32 v136, v179, v170
	s_waitcnt lgkmcnt(0)
	v_add_f32_e32 v136, v170, v136
	ds_bpermute_b32 v172, v180, v136
	s_and_saveexec_b64 s[76:77], s[0:1]
	s_cbranch_execz .LBB0_1720
	v_lshl_add_u64 v[174:175], v[160:161], 4, s[60:61]
	s_waitcnt lgkmcnt(0)
	v_add_f32_e32 v136, v136, v172
	global_store_dword v[174:175], v136, off

;     DI void operator()(const f32x4 (&acc)[2][2][4][2], const Unit& u, int wr, int wc, int fr, int fq) const {
;     ...
;                             const int i0 = 16 * wc + 4 * fq, pos = row & (SEQ - 1); const f32x4 c = *(const f32x4*)(cs + pos * 32 + i0), sv = *(const f32x4*)(sn + pos * 32 + i0);
;                             *(f32x4*)(KR + (size_t)row * 64 + i0) = v[1][0] * c - v[1][1] * sv; *(f32x4*)(KR + (size_t)row * 64 + 32 + i0) = v[1][1] * c + v[1][0] * sv; } } } }
.LBB0_1723:
	s_or_b64 exec, exec, s[76:77]
	v_lshlrev_b32_e32 v136, 7, v160
	v_and_b32_e32 v136, 0x7ef80, v136
	s_waitcnt lgkmcnt(0)
	v_lshl_add_u64 v[172:173], v[142:143], 0, v[136:137]
	global_load_dwordx4 v[172:175], v[172:173], off
	v_lshl_add_u64 v[176:177], v[140:141], 0, v[136:137]
	global_load_dwordx4 v[188:191], v[176:177], off
	v_lshlrev_b64 v[176:177], 8, v[160:161]
	v_lshl_add_u64 v[176:177], v[144:145], 0, v[176:177]
	s_waitcnt vmcnt(1)
	v_mul_f32_e32 v192, v166, v174
	v_mul_f32_e32 v193, v167, v175
	v_mul_f32_e32 v194, v168, v172
	v_mul_f32_e32 v195, v169, v173
	v_mul_f32_e32 v196, v162, v174
	v_mul_f32_e32 v197, v163, v175
	v_mul_f32_e32 v198, v164, v172
	v_mul_f32_e32 v199, v165, v173
	s_waitcnt vmcnt(0)
	v_pk_fma_f32 v[174:175], v[162:163], v[190:191], v[192:193] neg_lo:[0,0,1] neg_hi:[0,0,1]
	v_pk_fma_f32 v[172:173], v[164:165], v[188:189], v[194:195] neg_lo:[0,0,1] neg_hi:[0,0,1]
	v_fma_f32 v164, v166, v190, v196
	v_fma_f32 v165, v167, v191, v197
	v_fma_f32 v162, v168, v188, v198
	v_fma_f32 v163, v169, v189, v199
	global_store_dwordx4 v[176:177], v[172:175], off sc1
	global_store_dwordx4 v[176:177], v[162:165], off offset:128 sc1

; __device__ __forceinline__ unsigned cvt_pk_bf16(float lo, float hi) { unsigned r; asm volatile("v_cvt_pk_bf16_f32 %0, %1, %2" : "=v"(r) : "v"(lo), "v"(hi)); return r; }
; DI float shx(float v, int mask, int lane) { return __int_as_float(__builtin_amdgcn_ds_bpermute((lane ^ mask) << 2, __float_as_int(v))); }
;     DI void operator()(const f32x4 (&acc)[2][2][4][2], const Unit& u, int wr, int wc, int fr, int fq) const {
;     ...
;             for (int m = 0; m < 4; ++m) { const int row = row0 + ai * 128 + m * 16; const float s = rs[row]; bf16_t* rowp = O + (size_t)row * 2048 + col0;
;                 f32x4 v[2][2];
; #pragma unroll
;                 for (int bj = 0; bj < 2; ++bj) { v[bj][0] = acc[ai][bj][m][0] * s; v[bj][1] = acc[ai][bj][m][1] * s; u32x4 w;
;                     w.x = cvt_pk_bf16(v[bj][0][0], v[bj][0][1]); w.y = cvt_pk_bf16(v[bj][0][2], v[bj][0][3]); w.z = cvt_pk_bf16(v[bj][1][0], v[bj][1][1]); w.w = cvt_pk_bf16(v[bj][1][2], v[bj][1][3]);
;                     *(u32x4*)(rowp + bj * 128) = w; }
;                 if (pn < 2) {
;                     float s0 = 0.f, s1 = 0.f;
; #pragma unroll
;                     for (int n = 0; n < 2; ++n) { s0 += (v[0][n][0] * v[0][n][0] + v[0][n][1] * v[0][n][1]) + (v[0][n][2] * v[0][n][2] + v[0][n][3] * v[0][n][3]);
;                                                   s1 += (v[1][n][0] * v[1][n][0] + v[1][n][1] * v[1][n][1]) + (v[1][n][2] * v[1][n][2] + v[1][n][3] * v[1][n][3]); }
;                     if (pn == 0) { float ss = s0 + s1; ss += shx(ss, 16, ln); ss += shx(ss, 32, ln); if (fq == 0) ssq4[(size_t)row * 4 + wc] = ss; }
;                     else { s0 += shx(s0, 16, ln); s0 += shx(s0, 32, ln); if (fq == 0) sskv4[(size_t)row * 4 + wc] = s0;
;                         if (wc < 2) { s1 += shx(s1, 16, ln); s1 += shx(s1, 32, ln); if (fq == 0) sskr2[(size_t)row * 2 + wc] = s1;
.LBB0_1729:
	global_load_dword v136, v[158:159], off offset:640
	v_add_u32_e32 v160, 0xa0, v154
	v_ashrrev_i32_e32 v161, 31, v160
	s_waitcnt lgkmcnt(0)
	v_lshlrev_b64 v[162:163], 12, v[160:161]
	v_lshl_add_u64 v[162:163], s[14:15], 0, v[162:163]
	v_lshl_add_u64 v[192:193], v[156:157], 1, v[162:163]
	s_and_b64 vcc, exec, s[8:9]
	s_waitcnt vmcnt(0)
	v_mul_f32_e32 v174, v30, v136
	v_mul_f32_e32 v175, v31, v136
	v_mul_f32_e32 v176, v28, v136
	v_mul_f32_e32 v177, v29, v136
	v_mul_f32_e32 v170, v26, v136
	v_mul_f32_e32 v171, v27, v136
	v_mul_f32_e32 v172, v24, v136
	v_mul_f32_e32 v173, v25, v136
	v_mul_f32_e32 v162, v22, v136
	v_mul_f32_e32 v163, v23, v136
	v_mul_f32_e32 v164, v20, v136
	v_mul_f32_e32 v165, v21, v136
	v_mul_f32_e32 v166, v18, v136
	v_mul_f32_e32 v167, v19, v136
	v_mul_f32_e32 v168, v16, v136
	v_mul_f32_e32 v169, v17, v136
	v_cvt_pk_bf16_f32 v188, v176, v177
	v_cvt_pk_bf16_f32 v189, v174, v175
	v_cvt_pk_bf16_f32 v190, v172, v173
	v_cvt_pk_bf16_f32 v191, v170, v171
	global_store_dwordx4 v[192:193], v[188:191], off sc1
	s_nop 1
	v_cvt_pk_bf16_f32 v188, v164, v165
	v_cvt_pk_bf16_f32 v189, v162, v163
	v_cvt_pk_bf16_f32 v190, v168, v169
	v_cvt_pk_bf16_f32 v191, v166, v167
	global_store_dwordx4 v[192:193], v[188:191], off offset:256 sc1
	s_cbranch_vccnz .LBB0_1742
	v_mul_f32_e32 v136, v177, v177
	v_mul_f32_e32 v175, v175, v175
	v_mul_f32_e32 v173, v173, v173
	v_mul_f32_e32 v171, v171, v171
	v_fmac_f32_e32 v136, v176, v176
	v_fmac_f32_e32 v175, v174, v174
	v_fmac_f32_e32 v173, v172, v172
	v_fmac_f32_e32 v171, v170, v170
	v_add_f32_e32 v136, v136, v175
	v_add_f32_e32 v170, v173, v171
	v_mul_f32_e32 v174, v165, v165
	v_mul_f32_e32 v175, v163, v163
	v_add_f32_e32 v170, v136, v170
	v_mul_f32_e32 v136, v169, v169
	v_mul_f32_e32 v171, v167, v167
	v_fmac_f32_e32 v174, v164, v164
	v_fmac_f32_e32 v175, v162, v162
	v_fmac_f32_e32 v136, v168, v168
	v_fmac_f32_e32 v171, v166, v166
	v_add_f32_e32 v174, v174, v175
	v_add_f32_e32 v136, v136, v171
	s_and_b64 vcc, exec, s[6:7]
	v_add_f32_e32 v171, v174, v136
	s_cbranch_vccnz .LBB0_1738
	ds_bpermute_b32 v136, v179, v170
	s_waitcnt lgkmcnt(0)
	v_add_f32_e32 v136, v170, v136
	ds_bpermute_b32 v172, v180, v136
	s_and_saveexec_b64 s[76:77], s[0:1]
	s_cbranch_execz .LBB0_1733
	v_lshl_add_u64 v[174:175], v[160:161], 4, s[60:61]
	s_waitcnt lgkmcnt(0)
	v_add_f32_e32 v136, v136, v172
	global_store_dword v[174:175], v136, off

; __device__ __forceinline__ unsigned cvt_pk_bf16(float lo, float hi) { unsigned r; asm volatile("v_cvt_pk_bf16_f32 %0, %1, %2" : "=v"(r) : "v"(lo), "v"(hi)); return r; }
; DI float shx(float v, int mask, int lane) { return __int_as_float(__builtin_amdgcn_ds_bpermute((lane ^ mask) << 2, __float_as_int(v))); }
;     DI void operator()(const f32x4 (&acc)[2][2][4][2], const Unit& u, int wr, int wc, int fr, int fq) const {
;     ...
;             for (int m = 0; m < 4; ++m) { const int row = row0 + ai * 128 + m * 16; const float s = rs[row]; bf16_t* rowp = O + (size_t)row * 2048 + col0;
;                 f32x4 v[2][2];
; #pragma unroll
;                 for (int bj = 0; bj < 2; ++bj) { v[bj][0] = acc[ai][bj][m][0] * s; v[bj][1] = acc[ai][bj][m][1] * s; u32x4 w;
;                     w.x = cvt_pk_bf16(v[bj][0][0], v[bj][0][1]); w.y = cvt_pk_bf16(v[bj][0][2], v[bj][0][3]); w.z = cvt_pk_bf16(v[bj][1][0], v[bj][1][1]); w.w = cvt_pk_bf16(v[bj][1][2], v[bj][1][3]);
;                     *(u32x4*)(rowp + bj * 128) = w; }
;                 if (pn < 2) {
;                     float s0 = 0.f, s1 = 0.f;
; #pragma unroll
;                     for (int n = 0; n < 2; ++n) { s0 += (v[0][n][0] * v[0][n][0] + v[0][n][1] * v[0][n][1]) + (v[0][n][2] * v[0][n][2] + v[0][n][3] * v[0][n][3]);
;                                                   s1 += (v[1][n][0] * v[1][n][0] + v[1][n][1] * v[1][n][1]) + (v[1][n][2] * v[1][n][2] + v[1][n][3] * v[1][n][3]); }
;                     if (pn == 0) { float ss = s0 + s1; ss += shx(ss, 16, ln); ss += shx(ss, 32, ln); if (fq == 0) ssq4[(size_t)row * 4 + wc] = ss; }
;                     else { s0 += shx(s0, 16, ln); s0 += shx(s0, 32, ln); if (fq == 0) sskv4[(size_t)row * 4 + wc] = s0;
;                         if (wc < 2) { s1 += shx(s1, 16, ln); s1 += shx(s1, 32, ln); if (fq == 0) sskr2[(size_t)row * 2 + wc] = s1;
.LBB0_1742:
	global_load_dword v136, v[158:159], off offset:704
	v_add_u32_e32 v158, 0xb0, v154
	v_ashrrev_i32_e32 v159, 31, v158
	v_lshlrev_b64 v[160:161], 12, v[158:159]
	v_lshl_add_u64 v[160:161], s[14:15], 0, v[160:161]
	v_lshl_add_u64 v[188:189], v[156:157], 1, v[160:161]
	s_and_b64 vcc, exec, s[8:9]
	s_waitcnt vmcnt(0)
	v_mul_f32_e32 v170, v14, v136
	v_mul_f32_e32 v171, v15, v136
	s_waitcnt lgkmcnt(0)
	v_mul_f32_e32 v172, v12, v136
	v_mul_f32_e32 v173, v13, v136
	v_mul_f32_e32 v166, v10, v136
	v_mul_f32_e32 v167, v11, v136
	v_mul_f32_e32 v168, v8, v136
	v_mul_f32_e32 v169, v9, v136
	v_mul_f32_e32 v156, v6, v136
	v_mul_f32_e32 v157, v7, v136
	v_mul_f32_e32 v160, v4, v136
	v_mul_f32_e32 v161, v5, v136
	v_mul_f32_e32 v162, v2, v136
	v_mul_f32_e32 v163, v3, v136
	v_mul_f32_e32 v164, v0, v136
	v_mul_f32_e32 v165, v1, v136
	v_cvt_pk_bf16_f32 v174, v172, v173
	v_cvt_pk_bf16_f32 v175, v170, v171
	v_cvt_pk_bf16_f32 v176, v168, v169
	v_cvt_pk_bf16_f32 v177, v166, v167
	global_store_dwordx4 v[188:189], v[174:177], off sc1
	s_nop 1
	v_cvt_pk_bf16_f32 v174, v160, v161
	v_cvt_pk_bf16_f32 v175, v156, v157
	v_cvt_pk_bf16_f32 v176, v164, v165
	v_cvt_pk_bf16_f32 v177, v162, v163
	global_store_dwordx4 v[188:189], v[174:177], off offset:256 sc1
	s_cbranch_vccnz .LBB0_1751
	v_mul_f32_e32 v136, v173, v173
	v_mul_f32_e32 v171, v171, v171
	v_mul_f32_e32 v169, v169, v169
	v_mul_f32_e32 v167, v167, v167
	v_fmac_f32_e32 v136, v172, v172
	v_fmac_f32_e32 v171, v170, v170
	v_fmac_f32_e32 v169, v168, v168
	v_fmac_f32_e32 v167, v166, v166
	v_add_f32_e32 v136, v136, v171
	v_add_f32_e32 v166, v169, v167
	v_mul_f32_e32 v170, v161, v161
	v_mul_f32_e32 v171, v157, v157
	v_add_f32_e32 v166, v136, v166
	v_mul_f32_e32 v136, v165, v165
	v_mul_f32_e32 v167, v163, v163
	v_fmac_f32_e32 v170, v160, v160
	v_fmac_f32_e32 v171, v156, v156
	v_fmac_f32_e32 v136, v164, v164
	v_fmac_f32_e32 v167, v162, v162
	v_add_f32_e32 v170, v170, v171
	v_add_f32_e32 v136, v136, v167
	s_and_b64 vcc, exec, s[6:7]
	v_add_f32_e32 v167, v170, v136
	s_cbranch_vccnz .LBB0_1755
	ds_bpermute_b32 v136, v179, v166
	s_waitcnt lgkmcnt(0)
	v_add_f32_e32 v136, v166, v136
	ds_bpermute_b32 v168, v180, v136
	s_and_saveexec_b64 s[6:7], s[0:1]
	s_cbranch_execz .LBB0_1746
	v_lshl_add_u64 v[170:171], v[158:159], 4, s[60:61]
	s_waitcnt lgkmcnt(0)
	v_add_f32_e32 v136, v136, v168
	global_store_dword v[170:171], v136, off

;     DI void operator()(const f32x4 (&acc)[2][2][4][2], const Unit& u, int wr, int wc, int fr, int fq) const {
;     ...
;                             const int i0 = 16 * wc + 4 * fq, pos = row & (SEQ - 1); const f32x4 c = *(const f32x4*)(cs + pos * 32 + i0), sv = *(const f32x4*)(sn + pos * 32 + i0);
;                             *(f32x4*)(KR + (size_t)row * 64 + i0) = v[1][0] * c - v[1][1] * sv; *(f32x4*)(KR + (size_t)row * 64 + 32 + i0) = v[1][1] * c + v[1][0] * sv; } } } }
.LBB0_1749:
	s_or_b64 exec, exec, s[6:7]
	v_lshlrev_b32_e32 v136, 7, v158
	v_and_b32_e32 v136, 0x7ff80, v136
	s_waitcnt lgkmcnt(0)
	v_lshl_add_u64 v[168:169], v[142:143], 0, v[136:137]
	global_load_dwordx4 v[168:171], v[168:169], off
	v_lshl_add_u64 v[172:173], v[140:141], 0, v[136:137]
	global_load_dwordx4 v[172:175], v[172:173], off
	v_lshlrev_b64 v[176:177], 8, v[158:159]
	v_lshl_add_u64 v[176:177], v[144:145], 0, v[176:177]
	s_waitcnt vmcnt(1)
	v_mul_f32_e32 v188, v162, v170
	v_mul_f32_e32 v189, v163, v171
	v_mul_f32_e32 v190, v164, v168
	v_mul_f32_e32 v191, v165, v169
	v_mul_f32_e32 v192, v156, v170
	v_mul_f32_e32 v193, v157, v171
	v_mul_f32_e32 v194, v160, v168
	v_mul_f32_e32 v195, v161, v169
	s_waitcnt vmcnt(0)
	v_pk_fma_f32 v[170:171], v[156:157], v[174:175], v[188:189] neg_lo:[0,0,1] neg_hi:[0,0,1]
	v_pk_fma_f32 v[168:169], v[160:161], v[172:173], v[190:191] neg_lo:[0,0,1] neg_hi:[0,0,1]
	v_fma_f32 v162, v162, v174, v192
	v_fma_f32 v163, v163, v175, v193
	v_fma_f32 v160, v164, v172, v194
	v_fma_f32 v161, v165, v173, v195
	global_store_dwordx4 v[176:177], v[168:171], off sc1
	global_store_dwordx4 v[176:177], v[160:163], off offset:128 sc1

; __device__ __forceinline__ unsigned cvt_pk_bf16(float lo, float hi) { unsigned r; asm volatile("v_cvt_pk_bf16_f32 %0, %1, %2" : "=v"(r) : "v"(lo), "v"(hi)); return r; }
; DI float shx(float v, int mask, int lane) { return __int_as_float(__builtin_amdgcn_ds_bpermute((lane ^ mask) << 2, __float_as_int(v))); }
;     DI void operator()(const f32x4 (&acc)[2][2][4][2], const Unit& u, int wr, int wc, int fr, int fq) const {
;     ...
;         if (pn >= 2 && pn < 6) {
;             const float* gp = pn < 4 ? gdq : gdk; const float gsc = pn < 4 ? 0.125f * LOG2E : 1.f;
;             f32x4 g[2][2];
; #pragma unroll
;             for (int bj = 0; bj < 2; ++bj)
; #pragma unroll
;                 for (int n = 0; n < 2; ++n) g[bj][n] = *(const f32x4*)(gp + 32 * bj + 8 * fq + 4 * n) * gsc;
; #pragma unroll
;             for (int ai = 0; ai < 2; ++ai)
; #pragma unroll
;                 for (int m = 0; m < 4; ++m) { const int row = row0 + ai * 128 + m * 16; const float s = rs[row]; float ss = 0.f;
; #pragma unroll
;                     for (int bj = 0; bj < 2; ++bj)
; #pragma unroll
;                         for (int n = 0; n < 2; ++n) { const f32x4 v = acc[ai][bj][m][n]; ss += (v[0] * v[0] + v[1] * v[1]) + (v[2] * v[2] + v[3] * v[3]); }
;                     ss += shx(ss, 16, ln); ss += shx(ss, 32, ln);
;                     const float r = s * rsqrtf(ss * s * s * (1.f / 64.f) + EPS);
;                     bf16_t* rowp = O + (size_t)row * 2048 + pn * 256 + 64 * wc + 8 * fq;
; #pragma unroll
;                     for (int bj = 0; bj < 2; ++bj) { const f32x4 v0 = acc[ai][bj][m][0] * r * g[bj][0], v1 = acc[ai][bj][m][1] * r * g[bj][1]; u32x4 w;
;                         w.x = cvt_pk_bf16(v0[0], v0[1]); w.y = cvt_pk_bf16(v0[2], v0[3]); w.z = cvt_pk_bf16(v1[0], v1[1]); w.w = cvt_pk_bf16(v1[2], v1[3]);
;                         *(u32x4*)(rowp + 32 * bj) = w; } }
.LBB0_1752:
	s_waitcnt lgkmcnt(0)
	v_lshl_add_u64 v[156:157], v[154:155], 2, s[18:19]
	s_cmp_lt_u32 s48, 4
	global_load_dword v187, v[156:157], off
	s_cselect_b64 vcc, -1, 0
	s_and_b64 s[2:3], vcc, exec
	s_cselect_b32 s3, s39, s41
	s_cselect_b32 s2, s38, s40
	v_lshlrev_b32_e32 v136, 2, v138
	global_load_dwordx4 v[160:163], v136, s[2:3]
	global_load_dwordx4 v[164:167], v136, s[2:3] offset:16
	global_load_dwordx4 v[168:171], v136, s[2:3] offset:128
	global_load_dwordx4 v[188:191], v136, s[2:3] offset:144
	v_mul_f32_e32 v158, v126, v126
	v_mul_f32_e32 v159, v127, v127
	v_mul_f32_e32 v174, v124, v124
	v_mul_f32_e32 v175, v125, v125
	v_mul_f32_e32 v176, v122, v122
	v_mul_f32_e32 v177, v123, v123
	v_mul_f32_e32 v192, v120, v120
	v_mul_f32_e32 v193, v121, v121
	v_pk_mov_b32 v[198:199], v[174:175], v[158:159] op_sel:[1,0]
	v_mov_b32_e32 v175, v159
	v_pk_mov_b32 v[158:159], v[192:193], v[176:177] op_sel:[1,0]
	v_mov_b32_e32 v193, v177
	v_mul_f32_e32 v136, v117, v117
	v_mul_f32_e32 v194, v119, v119
	v_add_f32_e32 v174, v198, v174
	v_add_f32_e32 v175, v199, v175
	v_add_f32_e32 v158, v158, v192
	v_add_f32_e32 v159, v159, v193
	v_mul_f32_e32 v173, v112, v112
	v_mul_f32_e32 v200, v113, v113
	v_mul_f32_e32 v201, v114, v114
	v_mul_f32_e32 v202, v115, v115
	v_pk_fma_f32 v[176:177], v[116:117], v[116:117], v[136:137] op_sel_hi:[1,1,0]
	v_pk_fma_f32 v[194:195], v[118:119], v[118:119], v[194:195] op_sel_hi:[1,1,0]
	v_pk_add_f32 v[174:175], v[174:175], v[174:175] op_sel:[0,1] op_sel_hi:[1,0]
	v_pk_add_f32 v[158:159], v[158:159], v[158:159] op_sel:[0,1] op_sel_hi:[1,0]
	v_mov_b32_e32 v177, v201
	v_mov_b32_e32 v195, v202
	v_mov_b32_e32 v175, v173
	v_mov_b32_e32 v159, v200
	v_add_f32_e32 v176, v176, v194
	v_add_f32_e32 v177, v177, v195
	v_add_f32_e32 v158, v174, v158
	v_add_f32_e32 v159, v175, v159
	v_lshlrev_b64 v[196:197], 12, v[154:155]
	v_add_f32_e32 v158, v158, v176
	v_add_f32_e32 v159, v159, v177
	s_lshl_b32 s48, s48, 9
	v_add_f32_e32 v155, v158, v159
	ds_bpermute_b32 v173, v179, v155
	v_lshl_add_u64 v[158:159], s[14:15], 0, v[196:197]
	s_mov_b32 s67, s49
	v_lshl_add_u64 v[158:159], v[158:159], 0, s[48:49]
	v_cndmask_b32_e32 v172, 1.0, v186, vcc
	s_waitcnt lgkmcnt(0)
	v_add_f32_e32 v155, v155, v173
	ds_bpermute_b32 v173, v180, v155
	v_lshlrev_b32_e32 v136, 1, v138
	v_lshl_add_u64 v[158:159], v[158:159], 0, s[66:67]
	v_lshl_add_u64 v[174:175], v[158:159], 0, v[136:137]
	v_or_b32_e32 v176, 16, v154
	s_waitcnt lgkmcnt(0)
	v_add_f32_e32 v155, v155, v173
	s_mov_b32 s6, 0x80000
	s_mov_b64 s[2:3], 0x80000
	s_waitcnt vmcnt(0)
	v_mul_f32_e32 v155, v187, v155
	v_mul_f32_e32 v155, v187, v155
	v_fmamk_f32 v155, v155, 0x3c800000, v185
	v_mul_f32_e32 v158, v172, v162
	v_mul_f32_e32 v159, v172, v163
	v_mul_f32_e32 v162, v172, v166
	v_mul_f32_e32 v163, v172, v167
	v_mul_f32_e32 v166, v172, v170
	v_mul_f32_e32 v167, v172, v171
	v_mul_f32_e32 v170, 0x4b800000, v155
	v_cmp_gt_f32_e32 vcc, s93, v155
	v_mul_f32_e32 v160, v172, v160
	v_mul_f32_e32 v161, v172, v161
	v_mul_f32_e32 v164, v172, v164
	v_mul_f32_e32 v165, v172, v165
	v_cndmask_b32_e32 v155, v155, v170, vcc
	v_rsq_f32_e32 v155, v155
	v_mul_f32_e32 v168, v172, v168
	v_mul_f32_e32 v169, v172, v169
	v_mul_f32_e32 v170, v172, v190
	v_mul_f32_e32 v171, v172, v191
	v_mul_f32_e32 v173, v172, v189
	v_mul_f32_e32 v172, v172, v188
	v_mul_f32_e32 v177, 0x45800000, v155
	v_cndmask_b32_e32 v155, v155, v177, vcc
	v_mul_f32_e32 v188, v187, v155
	v_mul_f32_e32 v124, v124, v188
	v_mul_f32_e32 v125, v125, v188
	v_mul_f32_e32 v126, v126, v188
	v_mul_f32_e32 v127, v127, v188
	v_mul_f32_e32 v112, v112, v188
	v_mul_f32_e32 v113, v113, v188
	v_mul_f32_e32 v120, v120, v188
	v_mul_f32_e32 v121, v121, v188
	v_mul_f32_e32 v122, v122, v188
	v_mul_f32_e32 v123, v123, v188
	v_mul_f32_e32 v116, v116, v188
	v_mul_f32_e32 v117, v117, v188
	v_mul_f32_e32 v118, v118, v188
	v_mul_f32_e32 v119, v119, v188
	v_mul_f32_e32 v114, v114, v188
	v_mul_f32_e32 v115, v115, v188
	v_mul_f32_e32 v126, v158, v126
	v_mul_f32_e32 v127, v159, v127
	v_mul_f32_e32 v124, v160, v124
	v_mul_f32_e32 v125, v161, v125
	v_mul_f32_e32 v190, v172, v112
	v_mul_f32_e32 v191, v173, v113
	v_cvt_pk_bf16_f32 v112, v124, v125
	v_cvt_pk_bf16_f32 v113, v126, v127
	v_mul_f32_e32 v122, v162, v122
	v_mul_f32_e32 v123, v163, v123
	v_mul_f32_e32 v120, v164, v120
	v_mul_f32_e32 v121, v165, v121
	v_mul_f32_e32 v118, v166, v118
	v_mul_f32_e32 v119, v167, v119
	v_mul_f32_e32 v116, v168, v116
	v_mul_f32_e32 v117, v169, v117
	v_mul_f32_e32 v188, v170, v114
	v_mul_f32_e32 v189, v171, v115
	v_cvt_pk_bf16_f32 v114, v120, v121
	v_cvt_pk_bf16_f32 v115, v122, v123
	global_store_dwordx4 v[174:175], v[112:115], off sc1
	v_ashrrev_i32_e32 v177, 31, v176
	v_mul_f32_e32 v120, v101, v101
	v_cvt_pk_bf16_f32 v112, v116, v117
	v_cvt_pk_bf16_f32 v113, v118, v119
	v_cvt_pk_bf16_f32 v114, v190, v191
	v_cvt_pk_bf16_f32 v115, v188, v189
	global_store_dwordx4 v[174:175], v[112:115], off offset:64 sc1
	v_mul_f32_e32 v116, v106, v106
	v_mul_f32_e32 v117, v107, v107
	v_mul_f32_e32 v118, v104, v104
	v_mul_f32_e32 v119, v105, v105
	v_lshl_add_u64 v[112:113], v[176:177], 2, s[18:19]
	global_load_dword v123, v[112:113], off
	v_mul_f32_e32 v112, v110, v110
	v_mul_f32_e32 v113, v111, v111
	v_mul_f32_e32 v114, v108, v108
	v_mul_f32_e32 v115, v109, v109
	v_mul_f32_e32 v122, v103, v103
	v_pk_mov_b32 v[124:125], v[114:115], v[112:113] op_sel:[1,0]
	v_mov_b32_e32 v115, v113
	v_pk_mov_b32 v[112:113], v[118:119], v[116:117] op_sel:[1,0]
	v_mov_b32_e32 v119, v117
	v_add_f32_e32 v114, v124, v114
	v_add_f32_e32 v115, v125, v115
	v_add_f32_e32 v112, v112, v118
	v_add_f32_e32 v113, v113, v119
	v_mul_f32_e32 v126, v96, v96
	v_mul_f32_e32 v127, v97, v97
	v_mul_f32_e32 v155, v98, v98
	v_mul_f32_e32 v187, v99, v99
	v_pk_fma_f32 v[116:117], v[100:101], v[100:101], v[120:121] op_sel_hi:[1,1,0]
	v_pk_add_f32 v[114:115], v[114:115], v[114:115] op_sel:[0,1] op_sel_hi:[1,0]
	v_pk_add_f32 v[112:113], v[112:113], v[112:113] op_sel:[0,1] op_sel_hi:[1,0]
	v_mov_b32_e32 v117, v155
	v_mov_b32_e32 v115, v126
	v_mov_b32_e32 v113, v127
	v_add_f32_e32 v112, v114, v112
	v_add_f32_e32 v113, v115, v113
	s_waitcnt vmcnt(0)
; __device__ __forceinline__ unsigned cvt_pk_bf16(float lo, float hi) { unsigned r; asm volatile("v_cvt_pk_bf16_f32 %0, %1, %2" : "=v"(r) : "v"(lo), "v"(hi)); return r; }
; DI float shx(float v, int mask, int lane) { return __int_as_float(__builtin_amdgcn_ds_bpermute((lane ^ mask) << 2, __float_as_int(v))); }
;     DI void operator()(const f32x4 (&acc)[2][2][4][2], const Unit& u, int wr, int wc, int fr, int fq) const {
;     ...
;                 for (int m = 0; m < 4; ++m) { const int row = row0 + ai * 128 + m * 16; const float s = rs[row]; float ss = 0.f;
; #pragma unroll
;                     for (int bj = 0; bj < 2; ++bj)
; #pragma unroll
;                         for (int n = 0; n < 2; ++n) { const f32x4 v = acc[ai][bj][m][n]; ss += (v[0] * v[0] + v[1] * v[1]) + (v[2] * v[2] + v[3] * v[3]); }
;                     ss += shx(ss, 16, ln); ss += shx(ss, 32, ln);
;                     const float r = s * rsqrtf(ss * s * s * (1.f / 64.f) + EPS);
;                     bf16_t* rowp = O + (size_t)row * 2048 + pn * 256 + 64 * wc + 8 * fq;
; #pragma unroll
;                     for (int bj = 0; bj < 2; ++bj) { const f32x4 v0 = acc[ai][bj][m][0] * r * g[bj][0], v1 = acc[ai][bj][m][1] * r * g[bj][1]; u32x4 w;
;                         w.x = cvt_pk_bf16(v0[0], v0[1]); w.y = cvt_pk_bf16(v0[2], v0[3]); w.z = cvt_pk_bf16(v1[0], v1[1]); w.w = cvt_pk_bf16(v1[2], v1[3]);
;                         *(u32x4*)(rowp + 32 * bj) = w; } }
	v_pk_fma_f32 v[120:121], v[102:103], v[102:103], v[122:123] op_sel_hi:[1,1,0]
	s_nop 0
	v_mov_b32_e32 v121, v187
	v_add_f32_e32 v116, v116, v120
	v_add_f32_e32 v117, v117, v121
	s_nop 0
	v_add_f32_e32 v112, v112, v116
	v_add_f32_e32 v113, v113, v117
	s_nop 0
	v_add_f32_e32 v113, v112, v113
	ds_bpermute_b32 v114, v179, v113
	v_or_b32_e32 v112, 32, v154
	s_waitcnt lgkmcnt(0)
	v_add_f32_e32 v118, v113, v114
	ds_bpermute_b32 v119, v180, v118
	v_lshlrev_b64 v[114:115], 12, v[176:177]
	v_lshl_add_u64 v[114:115], s[14:15], 0, v[114:115]
	v_lshl_add_u64 v[114:115], v[114:115], 0, s[48:49]
	v_lshl_add_u64 v[114:115], v[114:115], 0, s[66:67]
	s_waitcnt lgkmcnt(0)
	v_add_f32_e32 v118, v118, v119
	v_mul_f32_e32 v118, v123, v118
	v_mul_f32_e32 v118, v123, v118
	v_fmamk_f32 v118, v118, 0x3c800000, v185
	v_mul_f32_e32 v119, 0x4b800000, v118
	v_cmp_gt_f32_e32 vcc, s93, v118
	v_ashrrev_i32_e32 v113, 31, v112
	v_lshl_add_u64 v[114:115], v[114:115], 0, v[136:137]
	v_cndmask_b32_e32 v118, v118, v119, vcc
	v_rsq_f32_e32 v118, v118
	v_lshl_add_u64 v[116:117], v[112:113], 2, s[18:19]
	v_mul_f32_e32 v119, 0x45800000, v118
	v_cndmask_b32_e32 v118, v118, v119, vcc
	v_mul_f32_e32 v118, v123, v118
	v_mul_f32_e32 v108, v108, v118
	v_mul_f32_e32 v109, v109, v118
	v_mul_f32_e32 v110, v110, v118
	v_mul_f32_e32 v111, v111, v118
	v_mul_f32_e32 v104, v104, v118
	v_mul_f32_e32 v105, v105, v118
	v_mul_f32_e32 v106, v106, v118
	v_mul_f32_e32 v107, v107, v118
	v_mul_f32_e32 v96, v96, v118
	v_mul_f32_e32 v97, v97, v118
	v_mul_f32_e32 v98, v98, v118
	v_mul_f32_e32 v99, v99, v118
	v_mul_f32_e32 v100, v100, v118
	v_mul_f32_e32 v101, v101, v118
	v_mul_f32_e32 v102, v102, v118
	v_mul_f32_e32 v103, v103, v118
	v_mul_f32_e32 v110, v158, v110
	v_mul_f32_e32 v111, v159, v111
	v_mul_f32_e32 v108, v160, v108
	v_mul_f32_e32 v109, v161, v109
	v_mul_f32_e32 v106, v162, v106
	v_mul_f32_e32 v107, v163, v107
	v_mul_f32_e32 v104, v164, v104
	v_mul_f32_e32 v105, v165, v105
	v_mul_f32_e32 v118, v170, v98
	v_mul_f32_e32 v119, v171, v99
	v_mul_f32_e32 v120, v172, v96
	v_mul_f32_e32 v121, v173, v97
	v_cvt_pk_bf16_f32 v96, v108, v109
	v_cvt_pk_bf16_f32 v97, v110, v111
	v_cvt_pk_bf16_f32 v98, v104, v105
	v_cvt_pk_bf16_f32 v99, v106, v107
	v_mul_f32_e32 v102, v166, v102
	v_mul_f32_e32 v103, v167, v103
	v_mul_f32_e32 v100, v168, v100
	v_mul_f32_e32 v101, v169, v101
	global_store_dwordx4 v[114:115], v[96:99], off sc1
	v_mul_f32_e32 v104, v85, v85
	v_mul_f32_e32 v106, v87, v87
	v_cvt_pk_bf16_f32 v96, v100, v101
	v_cvt_pk_bf16_f32 v97, v102, v103
	v_cvt_pk_bf16_f32 v98, v120, v121
	v_cvt_pk_bf16_f32 v99, v118, v119
	global_store_dwordx4 v[114:115], v[96:99], off offset:64 sc1
	global_load_dword v107, v[116:117], off
	v_mul_f32_e32 v100, v90, v90
	v_mul_f32_e32 v101, v91, v91
	v_mul_f32_e32 v96, v94, v94
	v_mul_f32_e32 v97, v95, v95
	v_mul_f32_e32 v98, v92, v92
	v_mul_f32_e32 v99, v93, v93
	v_mul_f32_e32 v102, v88, v88
	v_mul_f32_e32 v103, v89, v89
	v_pk_mov_b32 v[108:109], v[98:99], v[96:97] op_sel:[1,0]
	v_mov_b32_e32 v99, v97
	v_pk_mov_b32 v[96:97], v[102:103], v[100:101] op_sel:[1,0]
	v_mov_b32_e32 v103, v101
	v_add_f32_e32 v98, v108, v98
	v_add_f32_e32 v99, v109, v99
	v_add_f32_e32 v96, v96, v102
	v_add_f32_e32 v97, v97, v103
	v_mul_f32_e32 v110, v80, v80
	v_mul_f32_e32 v111, v81, v81
	v_mul_f32_e32 v114, v82, v82
	v_mul_f32_e32 v115, v83, v83
	v_pk_fma_f32 v[100:101], v[84:85], v[84:85], v[104:105] op_sel_hi:[1,1,0]
	v_pk_add_f32 v[98:99], v[98:99], v[98:99] op_sel:[0,1] op_sel_hi:[1,0]
	v_pk_add_f32 v[96:97], v[96:97], v[96:97] op_sel:[0,1] op_sel_hi:[1,0]
	v_mov_b32_e32 v101, v114
	v_mov_b32_e32 v99, v110
	v_mov_b32_e32 v97, v111
	v_add_f32_e32 v96, v98, v96
	v_add_f32_e32 v97, v99, v97
	s_waitcnt vmcnt(0)
	v_pk_fma_f32 v[104:105], v[86:87], v[86:87], v[106:107] op_sel_hi:[1,1,0]
	s_nop 0
	v_mov_b32_e32 v105, v115
	v_add_f32_e32 v100, v100, v104
	v_add_f32_e32 v101, v101, v105
	s_nop 0
	v_add_f32_e32 v96, v96, v100
	v_add_f32_e32 v97, v97, v101
	s_nop 0
	v_add_f32_e32 v97, v96, v97
	ds_bpermute_b32 v98, v179, v97
	v_or_b32_e32 v96, 48, v154
	s_waitcnt lgkmcnt(0)
	v_add_f32_e32 v102, v97, v98
	ds_bpermute_b32 v103, v180, v102
	v_lshlrev_b64 v[98:99], 12, v[112:113]
	v_lshl_add_u64 v[98:99], s[14:15], 0, v[98:99]
	v_lshl_add_u64 v[98:99], v[98:99], 0, s[48:49]
	v_lshl_add_u64 v[98:99], v[98:99], 0, s[66:67]
	s_waitcnt lgkmcnt(0)
; __device__ __forceinline__ unsigned cvt_pk_bf16(float lo, float hi) { unsigned r; asm volatile("v_cvt_pk_bf16_f32 %0, %1, %2" : "=v"(r) : "v"(lo), "v"(hi)); return r; }
; DI float shx(float v, int mask, int lane) { return __int_as_float(__builtin_amdgcn_ds_bpermute((lane ^ mask) << 2, __float_as_int(v))); }
;     DI void operator()(const f32x4 (&acc)[2][2][4][2], const Unit& u, int wr, int wc, int fr, int fq) const {
;     ...
;                 for (int m = 0; m < 4; ++m) { const int row = row0 + ai * 128 + m * 16; const float s = rs[row]; float ss = 0.f;
; #pragma unroll
;                     for (int bj = 0; bj < 2; ++bj)
; #pragma unroll
;                         for (int n = 0; n < 2; ++n) { const f32x4 v = acc[ai][bj][m][n]; ss += (v[0] * v[0] + v[1] * v[1]) + (v[2] * v[2] + v[3] * v[3]); }
;                     ss += shx(ss, 16, ln); ss += shx(ss, 32, ln);
;                     const float r = s * rsqrtf(ss * s * s * (1.f / 64.f) + EPS);
;                     bf16_t* rowp = O + (size_t)row * 2048 + pn * 256 + 64 * wc + 8 * fq;
; #pragma unroll
;                     for (int bj = 0; bj < 2; ++bj) { const f32x4 v0 = acc[ai][bj][m][0] * r * g[bj][0], v1 = acc[ai][bj][m][1] * r * g[bj][1]; u32x4 w;
;                         w.x = cvt_pk_bf16(v0[0], v0[1]); w.y = cvt_pk_bf16(v0[2], v0[3]); w.z = cvt_pk_bf16(v1[0], v1[1]); w.w = cvt_pk_bf16(v1[2], v1[3]);
;                         *(u32x4*)(rowp + 32 * bj) = w; } }
	v_add_f32_e32 v102, v102, v103
	v_mul_f32_e32 v102, v107, v102
	v_mul_f32_e32 v102, v107, v102
	v_fmamk_f32 v102, v102, 0x3c800000, v185
	v_mul_f32_e32 v103, 0x4b800000, v102
	v_cmp_gt_f32_e32 vcc, s93, v102
	v_ashrrev_i32_e32 v97, 31, v96
	v_lshl_add_u64 v[98:99], v[98:99], 0, v[136:137]
	v_cndmask_b32_e32 v102, v102, v103, vcc
	v_rsq_f32_e32 v102, v102
	v_lshl_add_u64 v[100:101], v[96:97], 2, s[18:19]
	v_mul_f32_e32 v103, 0x45800000, v102
	v_cndmask_b32_e32 v102, v102, v103, vcc
	v_mul_f32_e32 v102, v107, v102
	v_mul_f32_e32 v92, v92, v102
	v_mul_f32_e32 v93, v93, v102
	v_mul_f32_e32 v94, v94, v102
	v_mul_f32_e32 v95, v95, v102
	v_mul_f32_e32 v88, v88, v102
	v_mul_f32_e32 v89, v89, v102
	v_mul_f32_e32 v90, v90, v102
	v_mul_f32_e32 v91, v91, v102
	v_mul_f32_e32 v80, v80, v102
	v_mul_f32_e32 v81, v81, v102
	v_mul_f32_e32 v82, v82, v102
	v_mul_f32_e32 v83, v83, v102
	v_mul_f32_e32 v84, v84, v102
	v_mul_f32_e32 v85, v85, v102
	v_mul_f32_e32 v86, v86, v102
	v_mul_f32_e32 v87, v87, v102
	v_mul_f32_e32 v94, v158, v94
	v_mul_f32_e32 v95, v159, v95
	v_mul_f32_e32 v92, v160, v92
	v_mul_f32_e32 v93, v161, v93
	v_mul_f32_e32 v90, v162, v90
	v_mul_f32_e32 v91, v163, v91
	v_mul_f32_e32 v88, v164, v88
	v_mul_f32_e32 v89, v165, v89
	v_mul_f32_e32 v102, v170, v82
	v_mul_f32_e32 v103, v171, v83
	v_mul_f32_e32 v104, v172, v80
	v_mul_f32_e32 v105, v173, v81
	v_cvt_pk_bf16_f32 v80, v92, v93
	v_cvt_pk_bf16_f32 v81, v94, v95
	v_cvt_pk_bf16_f32 v82, v88, v89
	v_cvt_pk_bf16_f32 v83, v90, v91
	v_mul_f32_e32 v86, v166, v86
	v_mul_f32_e32 v87, v167, v87
	v_mul_f32_e32 v84, v168, v84
	v_mul_f32_e32 v85, v169, v85
	global_store_dwordx4 v[98:99], v[80:83], off sc1
	v_mul_f32_e32 v88, v69, v69
	v_mul_f32_e32 v90, v71, v71
	v_cvt_pk_bf16_f32 v80, v84, v85
	v_cvt_pk_bf16_f32 v81, v86, v87
	v_cvt_pk_bf16_f32 v82, v104, v105
	v_cvt_pk_bf16_f32 v83, v102, v103
	global_store_dwordx4 v[98:99], v[80:83], off offset:64 sc1
	global_load_dword v91, v[100:101], off
	v_mul_f32_e32 v84, v74, v74
	v_mul_f32_e32 v85, v75, v75
	v_mul_f32_e32 v80, v78, v78
	v_mul_f32_e32 v81, v79, v79
	v_mul_f32_e32 v82, v76, v76
	v_mul_f32_e32 v83, v77, v77
	v_mul_f32_e32 v86, v72, v72
	v_mul_f32_e32 v87, v73, v73
	v_pk_mov_b32 v[92:93], v[82:83], v[80:81] op_sel:[1,0]
	v_mov_b32_e32 v83, v81
	v_pk_mov_b32 v[80:81], v[86:87], v[84:85] op_sel:[1,0]
	v_mov_b32_e32 v87, v85
	v_add_f32_e32 v82, v92, v82
	v_add_f32_e32 v83, v93, v83
	v_add_f32_e32 v80, v80, v86
	v_add_f32_e32 v81, v81, v87
	v_mul_f32_e32 v94, v64, v64
	v_mul_f32_e32 v95, v65, v65
	v_mul_f32_e32 v98, v66, v66
	v_mul_f32_e32 v99, v67, v67
	v_pk_fma_f32 v[84:85], v[68:69], v[68:69], v[88:89] op_sel_hi:[1,1,0]
	v_pk_add_f32 v[82:83], v[82:83], v[82:83] op_sel:[0,1] op_sel_hi:[1,0]
	v_pk_add_f32 v[80:81], v[80:81], v[80:81] op_sel:[0,1] op_sel_hi:[1,0]
	v_mov_b32_e32 v85, v98
	v_mov_b32_e32 v83, v94
	v_mov_b32_e32 v81, v95
	v_add_f32_e32 v80, v82, v80
	v_add_f32_e32 v81, v83, v81
	s_waitcnt vmcnt(0)
	v_pk_fma_f32 v[88:89], v[70:71], v[70:71], v[90:91] op_sel_hi:[1,1,0]
	s_nop 0
	v_mov_b32_e32 v89, v99
	v_add_f32_e32 v84, v84, v88
	v_add_f32_e32 v85, v85, v89
	s_nop 0
	v_add_f32_e32 v80, v80, v84
	v_add_f32_e32 v81, v81, v85
	s_nop 0
	v_add_f32_e32 v80, v80, v81
	ds_bpermute_b32 v81, v179, v80
	s_waitcnt lgkmcnt(0)
	v_add_f32_e32 v82, v80, v81
	ds_bpermute_b32 v83, v180, v82
	v_lshlrev_b64 v[80:81], 12, v[96:97]
	v_lshl_add_u64 v[80:81], s[14:15], 0, v[80:81]
	v_lshl_add_u64 v[80:81], v[80:81], 0, s[48:49]
	v_lshl_add_u64 v[80:81], v[80:81], 0, s[66:67]
	s_waitcnt lgkmcnt(0)
	v_add_f32_e32 v82, v82, v83
	v_mul_f32_e32 v82, v91, v82
	v_mul_f32_e32 v82, v91, v82
	v_fmamk_f32 v82, v82, 0x3c800000, v185
	v_mul_f32_e32 v83, 0x4b800000, v82
	v_cmp_gt_f32_e32 vcc, s93, v82
	v_lshl_add_u64 v[80:81], v[80:81], 0, v[136:137]
	s_nop 0
	v_cndmask_b32_e32 v82, v82, v83, vcc
	v_rsq_f32_e32 v82, v82
	s_nop 0
	v_mul_f32_e32 v83, 0x45800000, v82
	v_cndmask_b32_e32 v82, v82, v83, vcc
	v_mul_f32_e32 v82, v91, v82
	v_mul_f32_e32 v76, v76, v82
	v_mul_f32_e32 v77, v77, v82
	v_mul_f32_e32 v78, v78, v82
	v_mul_f32_e32 v79, v79, v82
	v_mul_f32_e32 v72, v72, v82
	v_mul_f32_e32 v73, v73, v82
	v_mul_f32_e32 v74, v74, v82
	v_mul_f32_e32 v75, v75, v82
	v_mul_f32_e32 v64, v64, v82
	v_mul_f32_e32 v65, v65, v82
	v_mul_f32_e32 v66, v66, v82
	v_mul_f32_e32 v67, v67, v82
	v_mul_f32_e32 v68, v68, v82
	v_mul_f32_e32 v69, v69, v82
	v_mul_f32_e32 v70, v70, v82
	v_mul_f32_e32 v71, v71, v82
	v_mul_f32_e32 v78, v158, v78
	v_mul_f32_e32 v79, v159, v79
	v_mul_f32_e32 v76, v160, v76
	v_mul_f32_e32 v77, v161, v77
	v_mul_f32_e32 v74, v162, v74
	v_mul_f32_e32 v75, v163, v75
	v_mul_f32_e32 v72, v164, v72
	v_mul_f32_e32 v73, v165, v73
	v_mul_f32_e32 v82, v170, v66
	v_mul_f32_e32 v83, v171, v67
	v_mul_f32_e32 v84, v172, v64
	v_mul_f32_e32 v85, v173, v65
	v_cvt_pk_bf16_f32 v64, v76, v77
	v_cvt_pk_bf16_f32 v65, v78, v79
	v_cvt_pk_bf16_f32 v66, v72, v73
	v_cvt_pk_bf16_f32 v67, v74, v75
	v_mul_f32_e32 v70, v166, v70
	v_mul_f32_e32 v71, v167, v71
	v_mul_f32_e32 v68, v168, v68
	v_mul_f32_e32 v69, v169, v69
	global_store_dwordx4 v[80:81], v[64:67], off sc1
	v_mul_f32_e32 v72, v53, v53
	v_mul_f32_e32 v74, v55, v55
	v_cvt_pk_bf16_f32 v64, v68, v69
	v_cvt_pk_bf16_f32 v65, v70, v71
	v_cvt_pk_bf16_f32 v66, v84, v85
	v_cvt_pk_bf16_f32 v67, v82, v83
	global_store_dwordx4 v[80:81], v[64:67], off offset:64 sc1
	global_load_dword v75, v[156:157], off offset:512
	v_mul_f32_e32 v68, v58, v58
	v_mul_f32_e32 v69, v59, v59
	v_mul_f32_e32 v64, v62, v62
	v_mul_f32_e32 v65, v63, v63
	v_mul_f32_e32 v66, v60, v60
	v_mul_f32_e32 v67, v61, v61
	v_mul_f32_e32 v70, v56, v56
	v_mul_f32_e32 v71, v57, v57
	v_pk_mov_b32 v[76:77], v[66:67], v[64:65] op_sel:[1,0]
	v_mov_b32_e32 v67, v65
	v_pk_mov_b32 v[64:65], v[70:71], v[68:69] op_sel:[1,0]
	v_mov_b32_e32 v71, v69
	v_add_f32_e32 v66, v76, v66
	v_add_f32_e32 v67, v77, v67
	v_add_f32_e32 v64, v64, v70
	v_add_f32_e32 v65, v65, v71
	v_mul_f32_e32 v78, v48, v48
	v_mul_f32_e32 v79, v49, v49
	v_mul_f32_e32 v80, v50, v50
	v_mul_f32_e32 v81, v51, v51
	v_pk_fma_f32 v[68:69], v[52:53], v[52:53], v[72:73] op_sel_hi:[1,1,0]
	v_pk_add_f32 v[66:67], v[66:67], v[66:67] op_sel:[0,1] op_sel_hi:[1,0]
	v_pk_add_f32 v[64:65], v[64:65], v[64:65] op_sel:[0,1] op_sel_hi:[1,0]
	v_mov_b32_e32 v69, v80
	v_mov_b32_e32 v67, v78
	v_mov_b32_e32 v65, v79
	v_add_f32_e32 v64, v66, v64
	v_add_f32_e32 v65, v67, v65
	s_waitcnt vmcnt(0)
; __device__ __forceinline__ unsigned cvt_pk_bf16(float lo, float hi) { unsigned r; asm volatile("v_cvt_pk_bf16_f32 %0, %1, %2" : "=v"(r) : "v"(lo), "v"(hi)); return r; }
; DI float shx(float v, int mask, int lane) { return __int_as_float(__builtin_amdgcn_ds_bpermute((lane ^ mask) << 2, __float_as_int(v))); }
;     DI void operator()(const f32x4 (&acc)[2][2][4][2], const Unit& u, int wr, int wc, int fr, int fq) const {
;     ...
;                 for (int m = 0; m < 4; ++m) { const int row = row0 + ai * 128 + m * 16; const float s = rs[row]; float ss = 0.f;
; #pragma unroll
;                     for (int bj = 0; bj < 2; ++bj)
; #pragma unroll
;                         for (int n = 0; n < 2; ++n) { const f32x4 v = acc[ai][bj][m][n]; ss += (v[0] * v[0] + v[1] * v[1]) + (v[2] * v[2] + v[3] * v[3]); }
;                     ss += shx(ss, 16, ln); ss += shx(ss, 32, ln);
;                     const float r = s * rsqrtf(ss * s * s * (1.f / 64.f) + EPS);
;                     bf16_t* rowp = O + (size_t)row * 2048 + pn * 256 + 64 * wc + 8 * fq;
; #pragma unroll
;                     for (int bj = 0; bj < 2; ++bj) { const f32x4 v0 = acc[ai][bj][m][0] * r * g[bj][0], v1 = acc[ai][bj][m][1] * r * g[bj][1]; u32x4 w;
;                         w.x = cvt_pk_bf16(v0[0], v0[1]); w.y = cvt_pk_bf16(v0[2], v0[3]); w.z = cvt_pk_bf16(v1[0], v1[1]); w.w = cvt_pk_bf16(v1[2], v1[3]);
;                         *(u32x4*)(rowp + 32 * bj) = w; } }
	v_pk_fma_f32 v[72:73], v[54:55], v[54:55], v[74:75] op_sel_hi:[1,1,0]
	s_nop 0
	v_mov_b32_e32 v73, v81
	v_add_f32_e32 v68, v68, v72
	v_add_f32_e32 v69, v69, v73
	s_nop 0
	v_add_f32_e32 v64, v64, v68
	v_add_f32_e32 v65, v65, v69
	s_nop 0
	v_add_f32_e32 v64, v64, v65
	ds_bpermute_b32 v65, v179, v64
	s_waitcnt lgkmcnt(0)
	v_add_f32_e32 v66, v64, v65
	ds_bpermute_b32 v67, v180, v66
	v_lshl_add_u64 v[64:65], v[174:175], 0, s[2:3]
	s_mov_b64 s[2:3], 0x90000
	s_waitcnt lgkmcnt(0)
	v_add_f32_e32 v66, v66, v67
	v_mul_f32_e32 v66, v75, v66
	v_mul_f32_e32 v66, v75, v66
	v_fmamk_f32 v66, v66, 0x3c800000, v185
	v_mul_f32_e32 v67, 0x4b800000, v66
	v_cmp_gt_f32_e32 vcc, s93, v66
	s_nop 1
	v_cndmask_b32_e32 v66, v66, v67, vcc
	v_rsq_f32_e32 v68, v66
	v_add_co_u32_e64 v66, s[6:7], s6, v174
	v_mul_f32_e32 v69, 0x45800000, v68
	v_cndmask_b32_e32 v68, v68, v69, vcc
	v_mul_f32_e32 v68, v75, v68
	v_mul_f32_e32 v60, v60, v68
	v_mul_f32_e32 v61, v61, v68
	v_mul_f32_e32 v62, v62, v68
	v_mul_f32_e32 v63, v63, v68
	v_mul_f32_e32 v56, v56, v68
	v_mul_f32_e32 v57, v57, v68
	v_mul_f32_e32 v58, v58, v68
	v_mul_f32_e32 v59, v59, v68
	v_mul_f32_e32 v48, v48, v68
	v_mul_f32_e32 v49, v49, v68
	v_mul_f32_e32 v50, v50, v68
	v_mul_f32_e32 v51, v51, v68
	v_addc_co_u32_e64 v67, s[6:7], 0, v175, s[6:7]
	v_mul_f32_e32 v52, v52, v68
	v_mul_f32_e32 v53, v53, v68
	v_mul_f32_e32 v54, v54, v68
	v_mul_f32_e32 v55, v55, v68
	v_mul_f32_e32 v62, v158, v62
	v_mul_f32_e32 v63, v159, v63
	v_mul_f32_e32 v60, v160, v60
	v_mul_f32_e32 v61, v161, v61
	v_mul_f32_e32 v58, v162, v58
	v_mul_f32_e32 v59, v163, v59
	v_mul_f32_e32 v56, v164, v56
	v_mul_f32_e32 v57, v165, v57
	v_mul_f32_e32 v68, v170, v50
	v_mul_f32_e32 v69, v171, v51
	v_mul_f32_e32 v70, v172, v48
	v_mul_f32_e32 v71, v173, v49
	v_cvt_pk_bf16_f32 v48, v60, v61
	v_cvt_pk_bf16_f32 v49, v62, v63
	v_cvt_pk_bf16_f32 v50, v56, v57
	v_cvt_pk_bf16_f32 v51, v58, v59
	v_mul_f32_e32 v54, v166, v54
	v_mul_f32_e32 v55, v167, v55
	v_mul_f32_e32 v52, v168, v52
	v_mul_f32_e32 v53, v169, v53
	global_store_dwordx4 v[66:67], v[48:51], off sc1
	v_mul_f32_e32 v56, v37, v37
	v_mul_f32_e32 v58, v39, v39
	v_cvt_pk_bf16_f32 v48, v52, v53
	v_cvt_pk_bf16_f32 v49, v54, v55
	v_cvt_pk_bf16_f32 v50, v70, v71
	v_cvt_pk_bf16_f32 v51, v68, v69
	global_store_dwordx4 v[64:65], v[48:51], off offset:64 sc1
	global_load_dword v59, v[156:157], off offset:576
	v_mul_f32_e32 v52, v42, v42
	v_mul_f32_e32 v53, v43, v43
	v_mul_f32_e32 v48, v46, v46
	v_mul_f32_e32 v49, v47, v47
	v_mul_f32_e32 v50, v44, v44
	v_mul_f32_e32 v51, v45, v45
	v_mul_f32_e32 v54, v40, v40
	v_mul_f32_e32 v55, v41, v41
	v_pk_mov_b32 v[60:61], v[50:51], v[48:49] op_sel:[1,0]
	v_mov_b32_e32 v51, v49
	v_pk_mov_b32 v[48:49], v[54:55], v[52:53] op_sel:[1,0]
	v_mov_b32_e32 v55, v53
	v_add_f32_e32 v50, v60, v50
	v_add_f32_e32 v51, v61, v51
	v_add_f32_e32 v48, v48, v54
	v_add_f32_e32 v49, v49, v55
	v_mul_f32_e32 v62, v32, v32
	v_mul_f32_e32 v63, v33, v33
	v_mul_f32_e32 v64, v34, v34
	v_mul_f32_e32 v65, v35, v35
	v_pk_fma_f32 v[52:53], v[36:37], v[36:37], v[56:57] op_sel_hi:[1,1,0]
	v_pk_add_f32 v[50:51], v[50:51], v[50:51] op_sel:[0,1] op_sel_hi:[1,0]
	v_pk_add_f32 v[48:49], v[48:49], v[48:49] op_sel:[0,1] op_sel_hi:[1,0]
	v_mov_b32_e32 v53, v64
	v_mov_b32_e32 v51, v62
	v_mov_b32_e32 v49, v63
	v_add_f32_e32 v48, v50, v48
	v_add_f32_e32 v49, v51, v49
	s_mov_b32 s6, 0x90000
	s_waitcnt vmcnt(0)
	v_pk_fma_f32 v[56:57], v[38:39], v[38:39], v[58:59] op_sel_hi:[1,1,0]
	s_nop 0
	v_mov_b32_e32 v57, v65
	v_add_f32_e32 v52, v52, v56
	v_add_f32_e32 v53, v53, v57
	s_nop 0
	v_add_f32_e32 v48, v48, v52
	v_add_f32_e32 v49, v49, v53
	s_nop 0
	v_add_f32_e32 v48, v48, v49
	ds_bpermute_b32 v49, v179, v48
	s_waitcnt lgkmcnt(0)
	v_add_f32_e32 v50, v48, v49
	ds_bpermute_b32 v51, v180, v50
	v_lshl_add_u64 v[48:49], v[174:175], 0, s[2:3]
	s_mov_b64 s[2:3], 0xa0000
	s_waitcnt lgkmcnt(0)
	v_add_f32_e32 v50, v50, v51
	v_mul_f32_e32 v50, v59, v50
	v_mul_f32_e32 v50, v59, v50
	v_fmamk_f32 v50, v50, 0x3c800000, v185
	v_mul_f32_e32 v51, 0x4b800000, v50
	v_cmp_gt_f32_e32 vcc, s93, v50
	s_nop 1
	v_cndmask_b32_e32 v50, v50, v51, vcc
	v_rsq_f32_e32 v52, v50
	v_add_co_u32_e64 v50, s[6:7], s6, v174
	v_mul_f32_e32 v53, 0x45800000, v52
	v_cndmask_b32_e32 v52, v52, v53, vcc
	v_mul_f32_e32 v52, v59, v52
	v_mul_f32_e32 v44, v44, v52
	v_mul_f32_e32 v45, v45, v52
	v_mul_f32_e32 v46, v46, v52
	v_mul_f32_e32 v47, v47, v52
	v_mul_f32_e32 v40, v40, v52
	v_mul_f32_e32 v41, v41, v52
	v_mul_f32_e32 v42, v42, v52
	v_mul_f32_e32 v43, v43, v52
	v_mul_f32_e32 v32, v32, v52
	v_mul_f32_e32 v33, v33, v52
	v_mul_f32_e32 v34, v34, v52
	v_mul_f32_e32 v35, v35, v52
	v_addc_co_u32_e64 v51, s[6:7], 0, v175, s[6:7]
	v_mul_f32_e32 v36, v36, v52
	v_mul_f32_e32 v37, v37, v52
	v_mul_f32_e32 v38, v38, v52
	v_mul_f32_e32 v39, v39, v52
	v_mul_f32_e32 v46, v158, v46
	v_mul_f32_e32 v47, v159, v47
	v_mul_f32_e32 v44, v160, v44
	v_mul_f32_e32 v45, v161, v45
	v_mul_f32_e32 v42, v162, v42
	v_mul_f32_e32 v43, v163, v43
	v_mul_f32_e32 v40, v164, v40
	v_mul_f32_e32 v41, v165, v41
	v_mul_f32_e32 v52, v170, v34
	v_mul_f32_e32 v53, v171, v35
	v_mul_f32_e32 v54, v172, v32
	v_mul_f32_e32 v55, v173, v33
	v_cvt_pk_bf16_f32 v32, v44, v45
	v_cvt_pk_bf16_f32 v33, v46, v47
	v_cvt_pk_bf16_f32 v34, v40, v41
	v_cvt_pk_bf16_f32 v35, v42, v43
	v_mul_f32_e32 v38, v166, v38
	v_mul_f32_e32 v39, v167, v39
	v_mul_f32_e32 v36, v168, v36
	v_mul_f32_e32 v37, v169, v37
	global_store_dwordx4 v[50:51], v[32:35], off sc1
	v_mul_f32_e32 v40, v21, v21
	v_mul_f32_e32 v42, v23, v23
	v_cvt_pk_bf16_f32 v32, v36, v37
	v_cvt_pk_bf16_f32 v33, v38, v39
	v_cvt_pk_bf16_f32 v34, v54, v55
	v_cvt_pk_bf16_f32 v35, v52, v53
	global_store_dwordx4 v[48:49], v[32:35], off offset:64 sc1
	global_load_dword v43, v[156:157], off offset:640
	v_mul_f32_e32 v36, v26, v26
	v_mul_f32_e32 v37, v27, v27
	v_mul_f32_e32 v32, v30, v30
	v_mul_f32_e32 v33, v31, v31
	v_mul_f32_e32 v34, v28, v28
	v_mul_f32_e32 v35, v29, v29
	v_mul_f32_e32 v38, v24, v24
	v_mul_f32_e32 v39, v25, v25
	v_pk_mov_b32 v[44:45], v[34:35], v[32:33] op_sel:[1,0]
	v_mov_b32_e32 v35, v33
	v_pk_mov_b32 v[32:33], v[38:39], v[36:37] op_sel:[1,0]
	v_mov_b32_e32 v39, v37
	v_add_f32_e32 v34, v44, v34
	v_add_f32_e32 v35, v45, v35
	v_add_f32_e32 v32, v32, v38
	v_add_f32_e32 v33, v33, v39
	v_mul_f32_e32 v46, v16, v16
	v_mul_f32_e32 v47, v17, v17
	v_mul_f32_e32 v48, v18, v18
	v_mul_f32_e32 v49, v19, v19
	v_pk_fma_f32 v[36:37], v[20:21], v[20:21], v[40:41] op_sel_hi:[1,1,0]
	v_pk_add_f32 v[34:35], v[34:35], v[34:35] op_sel:[0,1] op_sel_hi:[1,0]
	v_pk_add_f32 v[32:33], v[32:33], v[32:33] op_sel:[0,1] op_sel_hi:[1,0]
	v_mov_b32_e32 v37, v48
	v_mov_b32_e32 v35, v46
	v_mov_b32_e32 v33, v47
	v_add_f32_e32 v32, v34, v32
	v_add_f32_e32 v33, v35, v33
	s_mov_b32 s6, 0xa0000
	s_waitcnt vmcnt(0)
; __device__ __forceinline__ unsigned cvt_pk_bf16(float lo, float hi) { unsigned r; asm volatile("v_cvt_pk_bf16_f32 %0, %1, %2" : "=v"(r) : "v"(lo), "v"(hi)); return r; }
; DI float shx(float v, int mask, int lane) { return __int_as_float(__builtin_amdgcn_ds_bpermute((lane ^ mask) << 2, __float_as_int(v))); }
;     DI void operator()(const f32x4 (&acc)[2][2][4][2], const Unit& u, int wr, int wc, int fr, int fq) const {
;     ...
;                 for (int m = 0; m < 4; ++m) { const int row = row0 + ai * 128 + m * 16; const float s = rs[row]; float ss = 0.f;
; #pragma unroll
;                     for (int bj = 0; bj < 2; ++bj)
; #pragma unroll
;                         for (int n = 0; n < 2; ++n) { const f32x4 v = acc[ai][bj][m][n]; ss += (v[0] * v[0] + v[1] * v[1]) + (v[2] * v[2] + v[3] * v[3]); }
;                     ss += shx(ss, 16, ln); ss += shx(ss, 32, ln);
;                     const float r = s * rsqrtf(ss * s * s * (1.f / 64.f) + EPS);
;                     bf16_t* rowp = O + (size_t)row * 2048 + pn * 256 + 64 * wc + 8 * fq;
; #pragma unroll
;                     for (int bj = 0; bj < 2; ++bj) { const f32x4 v0 = acc[ai][bj][m][0] * r * g[bj][0], v1 = acc[ai][bj][m][1] * r * g[bj][1]; u32x4 w;
;                         w.x = cvt_pk_bf16(v0[0], v0[1]); w.y = cvt_pk_bf16(v0[2], v0[3]); w.z = cvt_pk_bf16(v1[0], v1[1]); w.w = cvt_pk_bf16(v1[2], v1[3]);
;                         *(u32x4*)(rowp + 32 * bj) = w; } }
;             return;
	v_pk_fma_f32 v[40:41], v[22:23], v[22:23], v[42:43] op_sel_hi:[1,1,0]
	s_nop 0
	v_mov_b32_e32 v41, v49
	v_add_f32_e32 v36, v36, v40
	v_add_f32_e32 v37, v37, v41
	s_nop 0
	v_add_f32_e32 v32, v32, v36
	v_add_f32_e32 v33, v33, v37
	s_nop 0
	v_add_f32_e32 v32, v32, v33
	ds_bpermute_b32 v33, v179, v32
	s_waitcnt lgkmcnt(0)
	v_add_f32_e32 v34, v32, v33
	ds_bpermute_b32 v35, v180, v34
	v_lshl_add_u64 v[32:33], v[174:175], 0, s[2:3]
	s_mov_b64 s[2:3], 0xb0000
	s_waitcnt lgkmcnt(0)
	v_add_f32_e32 v34, v34, v35
	v_mul_f32_e32 v34, v43, v34
	v_mul_f32_e32 v34, v43, v34
	v_fmamk_f32 v34, v34, 0x3c800000, v185
	v_mul_f32_e32 v35, 0x4b800000, v34
	v_cmp_gt_f32_e32 vcc, s93, v34
	s_nop 1
	v_cndmask_b32_e32 v34, v34, v35, vcc
	v_rsq_f32_e32 v36, v34
	v_add_co_u32_e64 v34, s[6:7], s6, v174
	v_mul_f32_e32 v37, 0x45800000, v36
	v_cndmask_b32_e32 v36, v36, v37, vcc
	v_mul_f32_e32 v36, v43, v36
	v_mul_f32_e32 v28, v28, v36
	v_mul_f32_e32 v29, v29, v36
	v_mul_f32_e32 v30, v30, v36
	v_mul_f32_e32 v31, v31, v36
	v_mul_f32_e32 v24, v24, v36
	v_mul_f32_e32 v25, v25, v36
	v_mul_f32_e32 v26, v26, v36
	v_mul_f32_e32 v27, v27, v36
	v_mul_f32_e32 v16, v16, v36
	v_mul_f32_e32 v17, v17, v36
	v_mul_f32_e32 v18, v18, v36
	v_mul_f32_e32 v19, v19, v36
	v_addc_co_u32_e64 v35, s[6:7], 0, v175, s[6:7]
	v_mul_f32_e32 v20, v20, v36
	v_mul_f32_e32 v21, v21, v36
	v_mul_f32_e32 v22, v22, v36
	v_mul_f32_e32 v23, v23, v36
	v_mul_f32_e32 v30, v158, v30
	v_mul_f32_e32 v31, v159, v31
	v_mul_f32_e32 v28, v160, v28
	v_mul_f32_e32 v29, v161, v29
	v_mul_f32_e32 v26, v162, v26
	v_mul_f32_e32 v27, v163, v27
	v_mul_f32_e32 v24, v164, v24
	v_mul_f32_e32 v25, v165, v25
	v_mul_f32_e32 v36, v170, v18
	v_mul_f32_e32 v37, v171, v19
	v_mul_f32_e32 v38, v172, v16
	v_mul_f32_e32 v39, v173, v17
	v_cvt_pk_bf16_f32 v16, v28, v29
	v_cvt_pk_bf16_f32 v17, v30, v31
	v_cvt_pk_bf16_f32 v18, v24, v25
	v_cvt_pk_bf16_f32 v19, v26, v27
	v_mul_f32_e32 v22, v166, v22
	v_mul_f32_e32 v23, v167, v23
	v_mul_f32_e32 v20, v168, v20
	v_mul_f32_e32 v21, v169, v21
	global_store_dwordx4 v[34:35], v[16:19], off sc1
	v_mul_f32_e32 v24, v5, v5
	v_mul_f32_e32 v26, v7, v7
	v_cvt_pk_bf16_f32 v16, v20, v21
	v_cvt_pk_bf16_f32 v17, v22, v23
	v_cvt_pk_bf16_f32 v18, v38, v39
	v_cvt_pk_bf16_f32 v19, v36, v37
	global_store_dwordx4 v[32:33], v[16:19], off offset:64 sc1
	global_load_dword v27, v[156:157], off offset:704
	v_mul_f32_e32 v20, v10, v10
	v_mul_f32_e32 v21, v11, v11
	v_mul_f32_e32 v16, v14, v14
	v_mul_f32_e32 v17, v15, v15
	v_mul_f32_e32 v18, v12, v12
	v_mul_f32_e32 v19, v13, v13
	v_mul_f32_e32 v22, v8, v8
	v_mul_f32_e32 v23, v9, v9
	v_pk_mov_b32 v[28:29], v[18:19], v[16:17] op_sel:[1,0]
	v_mov_b32_e32 v19, v17
	v_pk_mov_b32 v[16:17], v[22:23], v[20:21] op_sel:[1,0]
	v_mov_b32_e32 v23, v21
	v_add_f32_e32 v18, v28, v18
	v_add_f32_e32 v19, v29, v19
	v_add_f32_e32 v16, v16, v22
	v_add_f32_e32 v17, v17, v23
	v_mul_f32_e32 v30, v0, v0
	v_mul_f32_e32 v31, v1, v1
	v_mul_f32_e32 v32, v2, v2
	v_mul_f32_e32 v33, v3, v3
	v_pk_fma_f32 v[20:21], v[4:5], v[4:5], v[24:25] op_sel_hi:[1,1,0]
	v_pk_add_f32 v[18:19], v[18:19], v[18:19] op_sel:[0,1] op_sel_hi:[1,0]
	v_pk_add_f32 v[16:17], v[16:17], v[16:17] op_sel:[0,1] op_sel_hi:[1,0]
	v_mov_b32_e32 v21, v32
	v_mov_b32_e32 v19, v30
	v_mov_b32_e32 v17, v31
	v_add_f32_e32 v16, v18, v16
	v_add_f32_e32 v17, v19, v17
	s_waitcnt vmcnt(0)
	v_pk_fma_f32 v[24:25], v[6:7], v[6:7], v[26:27] op_sel_hi:[1,1,0]
	s_nop 0
	v_mov_b32_e32 v25, v33
	v_add_f32_e32 v20, v20, v24
	v_add_f32_e32 v21, v21, v25
	s_nop 0
	v_add_f32_e32 v16, v16, v20
	v_add_f32_e32 v17, v17, v21
	s_nop 0
	v_add_f32_e32 v16, v16, v17
	ds_bpermute_b32 v17, v179, v16
	s_waitcnt lgkmcnt(0)
	v_add_f32_e32 v18, v16, v17
	ds_bpermute_b32 v19, v180, v18
	v_lshl_add_u64 v[16:17], v[174:175], 0, s[2:3]
	s_waitcnt lgkmcnt(0)
	v_add_f32_e32 v18, v18, v19
	v_mul_f32_e32 v18, v27, v18
	v_mul_f32_e32 v18, v27, v18
	v_fmamk_f32 v18, v18, 0x3c800000, v185
	v_mul_f32_e32 v19, 0x4b800000, v18
	v_cmp_gt_f32_e32 vcc, s93, v18
	s_nop 1
	v_cndmask_b32_e32 v18, v18, v19, vcc
	v_rsq_f32_e32 v20, v18
	v_add_co_u32_e64 v18, s[6:7], s94, v174
	v_mul_f32_e32 v21, 0x45800000, v20
	v_cndmask_b32_e32 v20, v20, v21, vcc
	v_mul_f32_e32 v20, v27, v20
	v_mul_f32_e32 v12, v12, v20
	v_mul_f32_e32 v13, v13, v20
	v_mul_f32_e32 v14, v14, v20
	v_mul_f32_e32 v15, v15, v20
	v_mul_f32_e32 v8, v8, v20
	v_mul_f32_e32 v9, v9, v20
	v_mul_f32_e32 v10, v10, v20
	v_mul_f32_e32 v11, v11, v20
	v_mul_f32_e32 v0, v0, v20
	v_mul_f32_e32 v1, v1, v20
	v_mul_f32_e32 v2, v2, v20
	v_mul_f32_e32 v3, v3, v20
	v_addc_co_u32_e64 v19, s[6:7], 0, v175, s[6:7]
	v_mul_f32_e32 v4, v4, v20
	v_mul_f32_e32 v5, v5, v20
	v_mul_f32_e32 v6, v6, v20
	v_mul_f32_e32 v7, v7, v20
	v_mul_f32_e32 v14, v158, v14
	v_mul_f32_e32 v15, v159, v15
	v_mul_f32_e32 v12, v160, v12
	v_mul_f32_e32 v13, v161, v13
	v_mul_f32_e32 v10, v162, v10
	v_mul_f32_e32 v11, v163, v11
	v_mul_f32_e32 v8, v164, v8
	v_mul_f32_e32 v9, v165, v9
	v_mul_f32_e32 v20, v170, v2
	v_mul_f32_e32 v21, v171, v3
	v_mul_f32_e32 v22, v172, v0
	v_mul_f32_e32 v23, v173, v1
	v_cvt_pk_bf16_f32 v0, v12, v13
	v_cvt_pk_bf16_f32 v1, v14, v15
	v_cvt_pk_bf16_f32 v2, v8, v9
	v_cvt_pk_bf16_f32 v3, v10, v11
	v_mul_f32_e32 v6, v166, v6
	v_mul_f32_e32 v7, v167, v7
	v_mul_f32_e32 v4, v168, v4
	v_mul_f32_e32 v5, v169, v5
	global_store_dwordx4 v[18:19], v[0:3], off sc1
	s_nop 1
	v_cvt_pk_bf16_f32 v0, v4, v5
	v_cvt_pk_bf16_f32 v1, v6, v7
	v_cvt_pk_bf16_f32 v2, v22, v23
	v_cvt_pk_bf16_f32 v3, v20, v21
	global_store_dwordx4 v[16:17], v[0:3], off offset:64 sc1
	s_andn2_b64 vcc, exec, s[4:5]
	s_mov_b64 s[4:5], -1
	s_cbranch_vccnz .LBB0_1637

; __device__ __forceinline__ unsigned cvt_pk_bf16(float lo, float hi) { unsigned r; asm volatile("v_cvt_pk_bf16_f32 %0, %1, %2" : "=v"(r) : "v"(lo), "v"(hi)); return r; }
;     DI void operator()(const f32x4 (&acc)[2][2][4][2], const Unit& u, int wr, int wc, int fr, int fq) const {
;     ...
;             for (int m = 0; m < 4; ++m) { const int row = row0 + ai * 128 + m * 16; const f32x4 q4 = *(const f32x4*)(ssq4 + (size_t)row * 4);
;                 const float s = rsqrtf(((q4[0] + q4[1]) + (q4[2] + q4[3])) * (1.f / 256.f) + EPS); bf16_t* rowp = Q + (size_t)row * 768;
; #pragma unroll
;                 for (int bj = 0; bj < 2; ++bj) { const int c0 = u.pn * 256 + bj * 128 + wc * 32, h = c0 / 192, d0 = c0 - h * 192;
;                     if (d0 < 128) { const f32x4 v0 = acc[ai][bj][m][0] * s, v1 = acc[ai][bj][m][1] * s; u32x4 w;
;                         w.x = cvt_pk_bf16(v0[0], v0[1]); w.y = cvt_pk_bf16(v0[2], v0[3]); w.z = cvt_pk_bf16(v1[0], v1[1]); w.w = cvt_pk_bf16(v1[2], v1[3]);
;                         *(u32x4*)(rowp + c0 + 8 * fq) = w; }
.LBB0_1792:
	v_lshlrev_b32_e32 v136, 1, v138
	s_andn2_b64 vcc, exec, s[8:9]
	v_lshl_add_u64 v[120:121], v[158:159], 0, v[136:137]
	s_cbranch_vccnz .LBB0_1794
	v_mov_b32_e32 v168, v156
	v_mov_b32_e32 v169, v156
	v_mul_f32_e32 v126, v126, v168
	v_mul_f32_e32 v127, v127, v169
	s_ashr_i32 s63, s62, 31
	v_mul_f32_e32 v168, v122, v168
	v_mul_f32_e32 v169, v123, v169
	v_cvt_pk_bf16_f32 v122, v162, v163
	v_cvt_pk_bf16_f32 v123, v126, v127
	v_lshl_add_u64 v[126:127], s[62:63], 1, v[120:121]
	v_cvt_pk_bf16_f32 v124, v124, v125
	v_cvt_pk_bf16_f32 v125, v168, v169
	global_store_dwordx4 v[126:127], v[122:125], off sc1

; __device__ __forceinline__ unsigned cvt_pk_bf16(float lo, float hi) { unsigned r; asm volatile("v_cvt_pk_bf16_f32 %0, %1, %2" : "=v"(r) : "v"(lo), "v"(hi)); return r; }
;     DI void operator()(const f32x4 (&acc)[2][2][4][2], const Unit& u, int wr, int wc, int fr, int fq) const {
;     ...
;             for (int m = 0; m < 4; ++m) { const int row = row0 + ai * 128 + m * 16; const f32x4 q4 = *(const f32x4*)(ssq4 + (size_t)row * 4);
;                 const float s = rsqrtf(((q4[0] + q4[1]) + (q4[2] + q4[3])) * (1.f / 256.f) + EPS); bf16_t* rowp = Q + (size_t)row * 768;
; #pragma unroll
;                 for (int bj = 0; bj < 2; ++bj) { const int c0 = u.pn * 256 + bj * 128 + wc * 32, h = c0 / 192, d0 = c0 - h * 192;
;                     if (d0 < 128) { const f32x4 v0 = acc[ai][bj][m][0] * s, v1 = acc[ai][bj][m][1] * s; u32x4 w;
;                         w.x = cvt_pk_bf16(v0[0], v0[1]); w.y = cvt_pk_bf16(v0[2], v0[3]); w.z = cvt_pk_bf16(v1[0], v1[1]); w.w = cvt_pk_bf16(v1[2], v1[3]);
;                         *(u32x4*)(rowp + c0 + 8 * fq) = w; }
.LBB0_1796:
	s_andn2_b64 vcc, exec, s[6:7]
	s_cbranch_vccnz .LBB0_1798
	v_mov_b32_e32 v157, v156
	s_ashr_i32 s63, s62, 31
	v_mul_f32_e32 v118, v118, v156
	v_mul_f32_e32 v119, v119, v157
	v_mul_f32_e32 v122, v114, v156
	v_mul_f32_e32 v123, v115, v157
	v_cvt_pk_bf16_f32 v114, v116, v117
	v_cvt_pk_bf16_f32 v115, v118, v119
	v_cvt_pk_bf16_f32 v116, v112, v113
	v_lshl_add_u64 v[112:113], s[62:63], 1, v[120:121]
	v_cvt_pk_bf16_f32 v117, v122, v123
	global_store_dwordx4 v[112:113], v[114:117], off offset:256 sc1

; __device__ __forceinline__ unsigned cvt_pk_bf16(float lo, float hi) { unsigned r; asm volatile("v_cvt_pk_bf16_f32 %0, %1, %2" : "=v"(r) : "v"(lo), "v"(hi)); return r; }
;     DI void operator()(const f32x4 (&acc)[2][2][4][2], const Unit& u, int wr, int wc, int fr, int fq) const {
;     ...
;             for (int m = 0; m < 4; ++m) { const int row = row0 + ai * 128 + m * 16; const f32x4 q4 = *(const f32x4*)(ssq4 + (size_t)row * 4);
;                 const float s = rsqrtf(((q4[0] + q4[1]) + (q4[2] + q4[3])) * (1.f / 256.f) + EPS); bf16_t* rowp = Q + (size_t)row * 768;
; #pragma unroll
;                 for (int bj = 0; bj < 2; ++bj) { const int c0 = u.pn * 256 + bj * 128 + wc * 32, h = c0 / 192, d0 = c0 - h * 192;
;                     if (d0 < 128) { const f32x4 v0 = acc[ai][bj][m][0] * s, v1 = acc[ai][bj][m][1] * s; u32x4 w;
;                         w.x = cvt_pk_bf16(v0[0], v0[1]); w.y = cvt_pk_bf16(v0[2], v0[3]); w.z = cvt_pk_bf16(v1[0], v1[1]); w.w = cvt_pk_bf16(v1[2], v1[3]);
;                         *(u32x4*)(rowp + c0 + 8 * fq) = w; }
.LBB0_1800:
	s_andn2_b64 vcc, exec, s[66:67]
	v_lshl_add_u64 v[104:105], v[114:115], 0, v[136:137]
	s_cbranch_vccnz .LBB0_1802
	v_mov_b32_e32 v120, v112
	v_mov_b32_e32 v121, v112
	v_mul_f32_e32 v110, v110, v120
	v_mul_f32_e32 v111, v111, v121
	s_ashr_i32 s63, s62, 31
	v_mul_f32_e32 v120, v106, v120
	v_mul_f32_e32 v121, v107, v121
	v_cvt_pk_bf16_f32 v106, v118, v119
	v_cvt_pk_bf16_f32 v107, v110, v111
	v_lshl_add_u64 v[110:111], s[62:63], 1, v[104:105]
	v_cvt_pk_bf16_f32 v108, v108, v109
	v_cvt_pk_bf16_f32 v109, v120, v121
	global_store_dwordx4 v[110:111], v[106:109], off sc1

; __device__ __forceinline__ unsigned cvt_pk_bf16(float lo, float hi) { unsigned r; asm volatile("v_cvt_pk_bf16_f32 %0, %1, %2" : "=v"(r) : "v"(lo), "v"(hi)); return r; }
;     DI void operator()(const f32x4 (&acc)[2][2][4][2], const Unit& u, int wr, int wc, int fr, int fq) const {
;     ...
;             for (int m = 0; m < 4; ++m) { const int row = row0 + ai * 128 + m * 16; const f32x4 q4 = *(const f32x4*)(ssq4 + (size_t)row * 4);
;                 const float s = rsqrtf(((q4[0] + q4[1]) + (q4[2] + q4[3])) * (1.f / 256.f) + EPS); bf16_t* rowp = Q + (size_t)row * 768;
; #pragma unroll
;                 for (int bj = 0; bj < 2; ++bj) { const int c0 = u.pn * 256 + bj * 128 + wc * 32, h = c0 / 192, d0 = c0 - h * 192;
;                     if (d0 < 128) { const f32x4 v0 = acc[ai][bj][m][0] * s, v1 = acc[ai][bj][m][1] * s; u32x4 w;
;                         w.x = cvt_pk_bf16(v0[0], v0[1]); w.y = cvt_pk_bf16(v0[2], v0[3]); w.z = cvt_pk_bf16(v1[0], v1[1]); w.w = cvt_pk_bf16(v1[2], v1[3]);
;                         *(u32x4*)(rowp + c0 + 8 * fq) = w; }
.LBB0_1804:
	s_andn2_b64 vcc, exec, s[12:13]
	s_cbranch_vccnz .LBB0_1806
	v_mov_b32_e32 v113, v112
	s_ashr_i32 s63, s62, 31
	v_mul_f32_e32 v102, v102, v112
	v_mul_f32_e32 v103, v103, v113
	v_mul_f32_e32 v106, v98, v112
	v_mul_f32_e32 v107, v99, v113
	v_cvt_pk_bf16_f32 v98, v100, v101
	v_cvt_pk_bf16_f32 v99, v102, v103
	v_cvt_pk_bf16_f32 v100, v96, v97
	v_lshl_add_u64 v[96:97], s[62:63], 1, v[104:105]
	v_cvt_pk_bf16_f32 v101, v106, v107
	global_store_dwordx4 v[96:97], v[98:101], off offset:256 sc1

; __device__ __forceinline__ unsigned cvt_pk_bf16(float lo, float hi) { unsigned r; asm volatile("v_cvt_pk_bf16_f32 %0, %1, %2" : "=v"(r) : "v"(lo), "v"(hi)); return r; }
;     DI void operator()(const f32x4 (&acc)[2][2][4][2], const Unit& u, int wr, int wc, int fr, int fq) const {
;     ...
;             for (int m = 0; m < 4; ++m) { const int row = row0 + ai * 128 + m * 16; const f32x4 q4 = *(const f32x4*)(ssq4 + (size_t)row * 4);
;                 const float s = rsqrtf(((q4[0] + q4[1]) + (q4[2] + q4[3])) * (1.f / 256.f) + EPS); bf16_t* rowp = Q + (size_t)row * 768;
; #pragma unroll
;                 for (int bj = 0; bj < 2; ++bj) { const int c0 = u.pn * 256 + bj * 128 + wc * 32, h = c0 / 192, d0 = c0 - h * 192;
;                     if (d0 < 128) { const f32x4 v0 = acc[ai][bj][m][0] * s, v1 = acc[ai][bj][m][1] * s; u32x4 w;
;                         w.x = cvt_pk_bf16(v0[0], v0[1]); w.y = cvt_pk_bf16(v0[2], v0[3]); w.z = cvt_pk_bf16(v1[0], v1[1]); w.w = cvt_pk_bf16(v1[2], v1[3]);
;                         *(u32x4*)(rowp + c0 + 8 * fq) = w; }
.LBB0_1808:
	s_andn2_b64 vcc, exec, s[64:65]
	v_lshl_add_u64 v[88:89], v[98:99], 0, v[136:137]
	s_cbranch_vccnz .LBB0_1810
	v_mov_b32_e32 v104, v96
	v_mov_b32_e32 v105, v96
	v_mul_f32_e32 v94, v94, v104
	v_mul_f32_e32 v95, v95, v105
	s_ashr_i32 s63, s62, 31
	v_mul_f32_e32 v104, v90, v104
	v_mul_f32_e32 v105, v91, v105
	v_cvt_pk_bf16_f32 v90, v102, v103
	v_cvt_pk_bf16_f32 v91, v94, v95
	v_lshl_add_u64 v[94:95], s[62:63], 1, v[88:89]
	v_cvt_pk_bf16_f32 v92, v92, v93
	v_cvt_pk_bf16_f32 v93, v104, v105
	global_store_dwordx4 v[94:95], v[90:93], off sc1

; __device__ __forceinline__ unsigned cvt_pk_bf16(float lo, float hi) { unsigned r; asm volatile("v_cvt_pk_bf16_f32 %0, %1, %2" : "=v"(r) : "v"(lo), "v"(hi)); return r; }
;     DI void operator()(const f32x4 (&acc)[2][2][4][2], const Unit& u, int wr, int wc, int fr, int fq) const {
;     ...
;             for (int m = 0; m < 4; ++m) { const int row = row0 + ai * 128 + m * 16; const f32x4 q4 = *(const f32x4*)(ssq4 + (size_t)row * 4);
;                 const float s = rsqrtf(((q4[0] + q4[1]) + (q4[2] + q4[3])) * (1.f / 256.f) + EPS); bf16_t* rowp = Q + (size_t)row * 768;
; #pragma unroll
;                 for (int bj = 0; bj < 2; ++bj) { const int c0 = u.pn * 256 + bj * 128 + wc * 32, h = c0 / 192, d0 = c0 - h * 192;
;                     if (d0 < 128) { const f32x4 v0 = acc[ai][bj][m][0] * s, v1 = acc[ai][bj][m][1] * s; u32x4 w;
;                         w.x = cvt_pk_bf16(v0[0], v0[1]); w.y = cvt_pk_bf16(v0[2], v0[3]); w.z = cvt_pk_bf16(v1[0], v1[1]); w.w = cvt_pk_bf16(v1[2], v1[3]);
;                         *(u32x4*)(rowp + c0 + 8 * fq) = w; }
.LBB0_1812:
	s_andn2_b64 vcc, exec, s[12:13]
	s_cbranch_vccnz .LBB0_1814
	v_mov_b32_e32 v97, v96
	s_ashr_i32 s63, s62, 31
	v_mul_f32_e32 v86, v86, v96
	v_mul_f32_e32 v87, v87, v97
	v_mul_f32_e32 v90, v82, v96
	v_mul_f32_e32 v91, v83, v97
	v_cvt_pk_bf16_f32 v82, v84, v85
	v_cvt_pk_bf16_f32 v83, v86, v87
	v_cvt_pk_bf16_f32 v84, v80, v81
	v_lshl_add_u64 v[80:81], s[62:63], 1, v[88:89]
	v_cvt_pk_bf16_f32 v85, v90, v91
	global_store_dwordx4 v[80:81], v[82:85], off offset:256 sc1

; __device__ __forceinline__ unsigned cvt_pk_bf16(float lo, float hi) { unsigned r; asm volatile("v_cvt_pk_bf16_f32 %0, %1, %2" : "=v"(r) : "v"(lo), "v"(hi)); return r; }
;     DI void operator()(const f32x4 (&acc)[2][2][4][2], const Unit& u, int wr, int wc, int fr, int fq) const {
;     ...
;             for (int m = 0; m < 4; ++m) { const int row = row0 + ai * 128 + m * 16; const f32x4 q4 = *(const f32x4*)(ssq4 + (size_t)row * 4);
;                 const float s = rsqrtf(((q4[0] + q4[1]) + (q4[2] + q4[3])) * (1.f / 256.f) + EPS); bf16_t* rowp = Q + (size_t)row * 768;
; #pragma unroll
;                 for (int bj = 0; bj < 2; ++bj) { const int c0 = u.pn * 256 + bj * 128 + wc * 32, h = c0 / 192, d0 = c0 - h * 192;
;                     if (d0 < 128) { const f32x4 v0 = acc[ai][bj][m][0] * s, v1 = acc[ai][bj][m][1] * s; u32x4 w;
;                         w.x = cvt_pk_bf16(v0[0], v0[1]); w.y = cvt_pk_bf16(v0[2], v0[3]); w.z = cvt_pk_bf16(v1[0], v1[1]); w.w = cvt_pk_bf16(v1[2], v1[3]);
;                         *(u32x4*)(rowp + c0 + 8 * fq) = w; }
.LBB0_1816:
	s_andn2_b64 vcc, exec, s[64:65]
	v_lshl_add_u64 v[72:73], v[82:83], 0, v[136:137]
	s_cbranch_vccnz .LBB0_1818
	v_mov_b32_e32 v88, v80
	v_mov_b32_e32 v89, v80
	v_mul_f32_e32 v78, v78, v88
	v_mul_f32_e32 v79, v79, v89
	s_ashr_i32 s63, s62, 31
	v_mul_f32_e32 v88, v74, v88
	v_mul_f32_e32 v89, v75, v89
	v_cvt_pk_bf16_f32 v74, v86, v87
	v_cvt_pk_bf16_f32 v75, v78, v79
	v_lshl_add_u64 v[78:79], s[62:63], 1, v[72:73]
	v_cvt_pk_bf16_f32 v76, v76, v77
	v_cvt_pk_bf16_f32 v77, v88, v89
	global_store_dwordx4 v[78:79], v[74:77], off sc1

; __device__ __forceinline__ unsigned cvt_pk_bf16(float lo, float hi) { unsigned r; asm volatile("v_cvt_pk_bf16_f32 %0, %1, %2" : "=v"(r) : "v"(lo), "v"(hi)); return r; }
;     DI void operator()(const f32x4 (&acc)[2][2][4][2], const Unit& u, int wr, int wc, int fr, int fq) const {
;     ...
;             for (int m = 0; m < 4; ++m) { const int row = row0 + ai * 128 + m * 16; const f32x4 q4 = *(const f32x4*)(ssq4 + (size_t)row * 4);
;                 const float s = rsqrtf(((q4[0] + q4[1]) + (q4[2] + q4[3])) * (1.f / 256.f) + EPS); bf16_t* rowp = Q + (size_t)row * 768;
; #pragma unroll
;                 for (int bj = 0; bj < 2; ++bj) { const int c0 = u.pn * 256 + bj * 128 + wc * 32, h = c0 / 192, d0 = c0 - h * 192;
;                     if (d0 < 128) { const f32x4 v0 = acc[ai][bj][m][0] * s, v1 = acc[ai][bj][m][1] * s; u32x4 w;
;                         w.x = cvt_pk_bf16(v0[0], v0[1]); w.y = cvt_pk_bf16(v0[2], v0[3]); w.z = cvt_pk_bf16(v1[0], v1[1]); w.w = cvt_pk_bf16(v1[2], v1[3]);
;                         *(u32x4*)(rowp + c0 + 8 * fq) = w; }
.LBB0_1820:
	s_andn2_b64 vcc, exec, s[12:13]
	s_cbranch_vccnz .LBB0_1822
	v_mov_b32_e32 v81, v80
	s_ashr_i32 s63, s62, 31
	v_mul_f32_e32 v70, v70, v80
	v_mul_f32_e32 v71, v71, v81
	v_mul_f32_e32 v74, v66, v80
	v_mul_f32_e32 v75, v67, v81
	v_cvt_pk_bf16_f32 v66, v68, v69
	v_cvt_pk_bf16_f32 v67, v70, v71
	v_cvt_pk_bf16_f32 v68, v64, v65
	v_lshl_add_u64 v[64:65], s[62:63], 1, v[72:73]
	v_cvt_pk_bf16_f32 v69, v74, v75
	global_store_dwordx4 v[64:65], v[66:69], off offset:256 sc1

; __device__ __forceinline__ unsigned cvt_pk_bf16(float lo, float hi) { unsigned r; asm volatile("v_cvt_pk_bf16_f32 %0, %1, %2" : "=v"(r) : "v"(lo), "v"(hi)); return r; }
;     DI void operator()(const f32x4 (&acc)[2][2][4][2], const Unit& u, int wr, int wc, int fr, int fq) const {
;     ...
;             for (int m = 0; m < 4; ++m) { const int row = row0 + ai * 128 + m * 16; const f32x4 q4 = *(const f32x4*)(ssq4 + (size_t)row * 4);
;                 const float s = rsqrtf(((q4[0] + q4[1]) + (q4[2] + q4[3])) * (1.f / 256.f) + EPS); bf16_t* rowp = Q + (size_t)row * 768;
; #pragma unroll
;                 for (int bj = 0; bj < 2; ++bj) { const int c0 = u.pn * 256 + bj * 128 + wc * 32, h = c0 / 192, d0 = c0 - h * 192;
;                     if (d0 < 128) { const f32x4 v0 = acc[ai][bj][m][0] * s, v1 = acc[ai][bj][m][1] * s; u32x4 w;
;                         w.x = cvt_pk_bf16(v0[0], v0[1]); w.y = cvt_pk_bf16(v0[2], v0[3]); w.z = cvt_pk_bf16(v1[0], v1[1]); w.w = cvt_pk_bf16(v1[2], v1[3]);
;                         *(u32x4*)(rowp + c0 + 8 * fq) = w; }
.LBB0_1824:
	s_andn2_b64 vcc, exec, s[64:65]
	v_lshl_add_u64 v[56:57], v[66:67], 0, v[136:137]
	s_cbranch_vccnz .LBB0_1826
	v_mov_b32_e32 v72, v64
	v_mov_b32_e32 v73, v64
	v_mul_f32_e32 v62, v62, v72
	v_mul_f32_e32 v63, v63, v73
	s_ashr_i32 s63, s62, 31
	v_mul_f32_e32 v72, v58, v72
	v_mul_f32_e32 v73, v59, v73
	v_cvt_pk_bf16_f32 v58, v70, v71
	v_cvt_pk_bf16_f32 v59, v62, v63
	v_lshl_add_u64 v[62:63], s[62:63], 1, v[56:57]
	v_cvt_pk_bf16_f32 v60, v60, v61
	v_cvt_pk_bf16_f32 v61, v72, v73
	global_store_dwordx4 v[62:63], v[58:61], off sc1

; __device__ __forceinline__ unsigned cvt_pk_bf16(float lo, float hi) { unsigned r; asm volatile("v_cvt_pk_bf16_f32 %0, %1, %2" : "=v"(r) : "v"(lo), "v"(hi)); return r; }
;     DI void operator()(const f32x4 (&acc)[2][2][4][2], const Unit& u, int wr, int wc, int fr, int fq) const {
;     ...
;             for (int m = 0; m < 4; ++m) { const int row = row0 + ai * 128 + m * 16; const f32x4 q4 = *(const f32x4*)(ssq4 + (size_t)row * 4);
;                 const float s = rsqrtf(((q4[0] + q4[1]) + (q4[2] + q4[3])) * (1.f / 256.f) + EPS); bf16_t* rowp = Q + (size_t)row * 768;
; #pragma unroll
;                 for (int bj = 0; bj < 2; ++bj) { const int c0 = u.pn * 256 + bj * 128 + wc * 32, h = c0 / 192, d0 = c0 - h * 192;
;                     if (d0 < 128) { const f32x4 v0 = acc[ai][bj][m][0] * s, v1 = acc[ai][bj][m][1] * s; u32x4 w;
;                         w.x = cvt_pk_bf16(v0[0], v0[1]); w.y = cvt_pk_bf16(v0[2], v0[3]); w.z = cvt_pk_bf16(v1[0], v1[1]); w.w = cvt_pk_bf16(v1[2], v1[3]);
;                         *(u32x4*)(rowp + c0 + 8 * fq) = w; }
.LBB0_1828:
	s_andn2_b64 vcc, exec, s[12:13]
	s_cbranch_vccnz .LBB0_1830
	v_mov_b32_e32 v65, v64
	s_ashr_i32 s63, s62, 31
	v_mul_f32_e32 v54, v54, v64
	v_mul_f32_e32 v55, v55, v65
	v_mul_f32_e32 v58, v50, v64
	v_mul_f32_e32 v59, v51, v65
	v_cvt_pk_bf16_f32 v50, v52, v53
	v_cvt_pk_bf16_f32 v51, v54, v55
	v_cvt_pk_bf16_f32 v52, v48, v49
	v_lshl_add_u64 v[48:49], s[62:63], 1, v[56:57]
	v_cvt_pk_bf16_f32 v53, v58, v59
	global_store_dwordx4 v[48:49], v[50:53], off offset:256 sc1

; __device__ __forceinline__ unsigned cvt_pk_bf16(float lo, float hi) { unsigned r; asm volatile("v_cvt_pk_bf16_f32 %0, %1, %2" : "=v"(r) : "v"(lo), "v"(hi)); return r; }
;     DI void operator()(const f32x4 (&acc)[2][2][4][2], const Unit& u, int wr, int wc, int fr, int fq) const {
;     ...
;             for (int m = 0; m < 4; ++m) { const int row = row0 + ai * 128 + m * 16; const f32x4 q4 = *(const f32x4*)(ssq4 + (size_t)row * 4);
;                 const float s = rsqrtf(((q4[0] + q4[1]) + (q4[2] + q4[3])) * (1.f / 256.f) + EPS); bf16_t* rowp = Q + (size_t)row * 768;
; #pragma unroll
;                 for (int bj = 0; bj < 2; ++bj) { const int c0 = u.pn * 256 + bj * 128 + wc * 32, h = c0 / 192, d0 = c0 - h * 192;
;                     if (d0 < 128) { const f32x4 v0 = acc[ai][bj][m][0] * s, v1 = acc[ai][bj][m][1] * s; u32x4 w;
;                         w.x = cvt_pk_bf16(v0[0], v0[1]); w.y = cvt_pk_bf16(v0[2], v0[3]); w.z = cvt_pk_bf16(v1[0], v1[1]); w.w = cvt_pk_bf16(v1[2], v1[3]);
;                         *(u32x4*)(rowp + c0 + 8 * fq) = w; }
.LBB0_1832:
	s_andn2_b64 vcc, exec, s[64:65]
	v_lshl_add_u64 v[40:41], v[50:51], 0, v[136:137]
	s_cbranch_vccnz .LBB0_1834
	v_mov_b32_e32 v56, v48
	v_mov_b32_e32 v57, v48
	v_mul_f32_e32 v46, v46, v56
	v_mul_f32_e32 v47, v47, v57
	s_ashr_i32 s63, s62, 31
	v_mul_f32_e32 v56, v42, v56
	v_mul_f32_e32 v57, v43, v57
	v_cvt_pk_bf16_f32 v42, v54, v55
	v_cvt_pk_bf16_f32 v43, v46, v47
	v_lshl_add_u64 v[46:47], s[62:63], 1, v[40:41]
	v_cvt_pk_bf16_f32 v44, v44, v45
	v_cvt_pk_bf16_f32 v45, v56, v57
	global_store_dwordx4 v[46:47], v[42:45], off sc1

; __device__ __forceinline__ unsigned cvt_pk_bf16(float lo, float hi) { unsigned r; asm volatile("v_cvt_pk_bf16_f32 %0, %1, %2" : "=v"(r) : "v"(lo), "v"(hi)); return r; }
;     DI void operator()(const f32x4 (&acc)[2][2][4][2], const Unit& u, int wr, int wc, int fr, int fq) const {
;     ...
;             for (int m = 0; m < 4; ++m) { const int row = row0 + ai * 128 + m * 16; const f32x4 q4 = *(const f32x4*)(ssq4 + (size_t)row * 4);
;                 const float s = rsqrtf(((q4[0] + q4[1]) + (q4[2] + q4[3])) * (1.f / 256.f) + EPS); bf16_t* rowp = Q + (size_t)row * 768;
; #pragma unroll
;                 for (int bj = 0; bj < 2; ++bj) { const int c0 = u.pn * 256 + bj * 128 + wc * 32, h = c0 / 192, d0 = c0 - h * 192;
;                     if (d0 < 128) { const f32x4 v0 = acc[ai][bj][m][0] * s, v1 = acc[ai][bj][m][1] * s; u32x4 w;
;                         w.x = cvt_pk_bf16(v0[0], v0[1]); w.y = cvt_pk_bf16(v0[2], v0[3]); w.z = cvt_pk_bf16(v1[0], v1[1]); w.w = cvt_pk_bf16(v1[2], v1[3]);
;                         *(u32x4*)(rowp + c0 + 8 * fq) = w; }
.LBB0_1836:
	s_andn2_b64 vcc, exec, s[12:13]
	s_cbranch_vccnz .LBB0_1838
	v_mov_b32_e32 v49, v48
	s_ashr_i32 s63, s62, 31
	v_mul_f32_e32 v38, v38, v48
	v_mul_f32_e32 v39, v39, v49
	v_mul_f32_e32 v42, v34, v48
	v_mul_f32_e32 v43, v35, v49
	v_cvt_pk_bf16_f32 v34, v36, v37
	v_cvt_pk_bf16_f32 v35, v38, v39
	v_cvt_pk_bf16_f32 v36, v32, v33
	v_lshl_add_u64 v[32:33], s[62:63], 1, v[40:41]
	v_cvt_pk_bf16_f32 v37, v42, v43
	global_store_dwordx4 v[32:33], v[34:37], off offset:256 sc1

; __device__ __forceinline__ unsigned cvt_pk_bf16(float lo, float hi) { unsigned r; asm volatile("v_cvt_pk_bf16_f32 %0, %1, %2" : "=v"(r) : "v"(lo), "v"(hi)); return r; }
;     DI void operator()(const f32x4 (&acc)[2][2][4][2], const Unit& u, int wr, int wc, int fr, int fq) const {
;     ...
;             for (int m = 0; m < 4; ++m) { const int row = row0 + ai * 128 + m * 16; const f32x4 q4 = *(const f32x4*)(ssq4 + (size_t)row * 4);
;                 const float s = rsqrtf(((q4[0] + q4[1]) + (q4[2] + q4[3])) * (1.f / 256.f) + EPS); bf16_t* rowp = Q + (size_t)row * 768;
; #pragma unroll
;                 for (int bj = 0; bj < 2; ++bj) { const int c0 = u.pn * 256 + bj * 128 + wc * 32, h = c0 / 192, d0 = c0 - h * 192;
;                     if (d0 < 128) { const f32x4 v0 = acc[ai][bj][m][0] * s, v1 = acc[ai][bj][m][1] * s; u32x4 w;
;                         w.x = cvt_pk_bf16(v0[0], v0[1]); w.y = cvt_pk_bf16(v0[2], v0[3]); w.z = cvt_pk_bf16(v1[0], v1[1]); w.w = cvt_pk_bf16(v1[2], v1[3]);
;                         *(u32x4*)(rowp + c0 + 8 * fq) = w; }
.LBB0_1840:
	s_andn2_b64 vcc, exec, s[64:65]
	v_lshl_add_u64 v[24:25], v[34:35], 0, v[136:137]
	s_cbranch_vccnz .LBB0_1842
	v_mov_b32_e32 v40, v32
	v_mov_b32_e32 v41, v32
	v_mul_f32_e32 v30, v30, v40
	v_mul_f32_e32 v31, v31, v41
	s_ashr_i32 s63, s62, 31
	v_mul_f32_e32 v40, v26, v40
	v_mul_f32_e32 v41, v27, v41
	v_cvt_pk_bf16_f32 v26, v38, v39
	v_cvt_pk_bf16_f32 v27, v30, v31
	v_lshl_add_u64 v[30:31], s[62:63], 1, v[24:25]
	v_cvt_pk_bf16_f32 v28, v28, v29
	v_cvt_pk_bf16_f32 v29, v40, v41
	global_store_dwordx4 v[30:31], v[26:29], off sc1

; __device__ __forceinline__ unsigned cvt_pk_bf16(float lo, float hi) { unsigned r; asm volatile("v_cvt_pk_bf16_f32 %0, %1, %2" : "=v"(r) : "v"(lo), "v"(hi)); return r; }
;     DI void operator()(const f32x4 (&acc)[2][2][4][2], const Unit& u, int wr, int wc, int fr, int fq) const {
;     ...
;             for (int m = 0; m < 4; ++m) { const int row = row0 + ai * 128 + m * 16; const f32x4 q4 = *(const f32x4*)(ssq4 + (size_t)row * 4);
;                 const float s = rsqrtf(((q4[0] + q4[1]) + (q4[2] + q4[3])) * (1.f / 256.f) + EPS); bf16_t* rowp = Q + (size_t)row * 768;
; #pragma unroll
;                 for (int bj = 0; bj < 2; ++bj) { const int c0 = u.pn * 256 + bj * 128 + wc * 32, h = c0 / 192, d0 = c0 - h * 192;
;                     if (d0 < 128) { const f32x4 v0 = acc[ai][bj][m][0] * s, v1 = acc[ai][bj][m][1] * s; u32x4 w;
;                         w.x = cvt_pk_bf16(v0[0], v0[1]); w.y = cvt_pk_bf16(v0[2], v0[3]); w.z = cvt_pk_bf16(v1[0], v1[1]); w.w = cvt_pk_bf16(v1[2], v1[3]);
;                         *(u32x4*)(rowp + c0 + 8 * fq) = w; }
.LBB0_1844:
	s_andn2_b64 vcc, exec, s[12:13]
	s_cbranch_vccnz .LBB0_1846
	v_mov_b32_e32 v33, v32
	s_ashr_i32 s63, s62, 31
	v_mul_f32_e32 v22, v22, v32
	v_mul_f32_e32 v23, v23, v33
	v_mul_f32_e32 v26, v18, v32
	v_mul_f32_e32 v27, v19, v33
	v_cvt_pk_bf16_f32 v18, v20, v21
	v_cvt_pk_bf16_f32 v19, v22, v23
	v_cvt_pk_bf16_f32 v20, v16, v17
	v_lshl_add_u64 v[16:17], s[62:63], 1, v[24:25]
	v_cvt_pk_bf16_f32 v21, v26, v27
	global_store_dwordx4 v[16:17], v[18:21], off offset:256 sc1

; __device__ __forceinline__ unsigned cvt_pk_bf16(float lo, float hi) { unsigned r; asm volatile("v_cvt_pk_bf16_f32 %0, %1, %2" : "=v"(r) : "v"(lo), "v"(hi)); return r; }
;     DI void operator()(const f32x4 (&acc)[2][2][4][2], const Unit& u, int wr, int wc, int fr, int fq) const {
;     ...
;             for (int m = 0; m < 4; ++m) { const int row = row0 + ai * 128 + m * 16; const f32x4 q4 = *(const f32x4*)(ssq4 + (size_t)row * 4);
;                 const float s = rsqrtf(((q4[0] + q4[1]) + (q4[2] + q4[3])) * (1.f / 256.f) + EPS); bf16_t* rowp = Q + (size_t)row * 768;
; #pragma unroll
;                 for (int bj = 0; bj < 2; ++bj) { const int c0 = u.pn * 256 + bj * 128 + wc * 32, h = c0 / 192, d0 = c0 - h * 192;
;                     if (d0 < 128) { const f32x4 v0 = acc[ai][bj][m][0] * s, v1 = acc[ai][bj][m][1] * s; u32x4 w;
;                         w.x = cvt_pk_bf16(v0[0], v0[1]); w.y = cvt_pk_bf16(v0[2], v0[3]); w.z = cvt_pk_bf16(v1[0], v1[1]); w.w = cvt_pk_bf16(v1[2], v1[3]);
;                         *(u32x4*)(rowp + c0 + 8 * fq) = w; }
.LBB0_1848:
	s_andn2_b64 vcc, exec, s[12:13]
	v_lshl_add_u64 v[8:9], v[18:19], 0, v[136:137]
	s_cbranch_vccnz .LBB0_1850
	v_mov_b32_e32 v24, v16
	v_mov_b32_e32 v25, v16
	v_mul_f32_e32 v14, v14, v24
	v_mul_f32_e32 v15, v15, v25
	s_ashr_i32 s63, s62, 31
	v_mul_f32_e32 v24, v10, v24
	v_mul_f32_e32 v25, v11, v25
	v_cvt_pk_bf16_f32 v10, v22, v23
	v_cvt_pk_bf16_f32 v11, v14, v15
	v_lshl_add_u64 v[14:15], s[62:63], 1, v[8:9]
	v_cvt_pk_bf16_f32 v12, v12, v13
	v_cvt_pk_bf16_f32 v13, v24, v25
	global_store_dwordx4 v[14:15], v[10:13], off sc1

; __device__ __forceinline__ unsigned cvt_pk_bf16(float lo, float hi) { unsigned r; asm volatile("v_cvt_pk_bf16_f32 %0, %1, %2" : "=v"(r) : "v"(lo), "v"(hi)); return r; }
;     DI void operator()(const f32x4 (&acc)[2][2][4][2], const Unit& u, int wr, int wc, int fr, int fq) const {
;     ...
;             for (int m = 0; m < 4; ++m) { const int row = row0 + ai * 128 + m * 16; const f32x4 q4 = *(const f32x4*)(ssq4 + (size_t)row * 4);
;                 const float s = rsqrtf(((q4[0] + q4[1]) + (q4[2] + q4[3])) * (1.f / 256.f) + EPS); bf16_t* rowp = Q + (size_t)row * 768;
; #pragma unroll
;                 for (int bj = 0; bj < 2; ++bj) { const int c0 = u.pn * 256 + bj * 128 + wc * 32, h = c0 / 192, d0 = c0 - h * 192;
;                     if (d0 < 128) { const f32x4 v0 = acc[ai][bj][m][0] * s, v1 = acc[ai][bj][m][1] * s; u32x4 w;
;                         w.x = cvt_pk_bf16(v0[0], v0[1]); w.y = cvt_pk_bf16(v0[2], v0[3]); w.z = cvt_pk_bf16(v1[0], v1[1]); w.w = cvt_pk_bf16(v1[2], v1[3]);
;                         *(u32x4*)(rowp + c0 + 8 * fq) = w; }
.LBB0_1854:
	v_mov_b32_e32 v17, v16
	s_ashr_i32 s63, s62, 31
	v_mul_f32_e32 v6, v6, v16
	v_mul_f32_e32 v7, v7, v17
	v_mul_f32_e32 v10, v2, v16
	v_mul_f32_e32 v11, v3, v17
	v_cvt_pk_bf16_f32 v2, v4, v5
	v_cvt_pk_bf16_f32 v3, v6, v7
	v_cvt_pk_bf16_f32 v4, v0, v1
	v_lshl_add_u64 v[0:1], s[62:63], 1, v[8:9]
	v_cvt_pk_bf16_f32 v5, v10, v11
	global_store_dwordx4 v[0:1], v[2:5], off offset:256 sc1
	s_and_b64 vcc, exec, s[4:5]
	s_mov_b64 s[4:5], -1
	s_cbranch_vccnz .LBB0_1778

; __device__ __forceinline__ unsigned cvt_pk_bf16(float lo, float hi) { unsigned r; asm volatile("v_cvt_pk_bf16_f32 %0, %1, %2" : "=v"(r) : "v"(lo), "v"(hi)); return r; }
; DI float shx(float v, int mask, int lane) { return __int_as_float(__builtin_amdgcn_ds_bpermute((lane ^ mask) << 2, __float_as_int(v))); }
;     DI void operator()(const f32x4 (&acc)[2][2][4][2], const Unit& u, int wr, int wc, int fr, int fq) const {
;     ...
; #pragma unroll
;         for (int ai = 0; ai < 2; ++ai)
; #pragma unroll
;             for (int m = 0; m < 4; ++m) { const f32x4 q4 = *(const f32x4*)(sskv4 + (size_t)(row0 + ai * 128 + m * 16) * 4); rs[ai][m] = rsqrtf(((q4[0] + q4[1]) + (q4[2] + q4[3])) * (1.f / 128.f) + EPS); }
; #pragma unroll
;         for (int ai = 0; ai < 2; ++ai)
; #pragma unroll
;             for (int m = 0; m < 4; ++m) { const int row = row0 + ai * 128 + m * 16; const float s = rs[ai][m];
;                 const f32x4 w0 = acc[ai][1][m][0] * s, w1 = acc[ai][1][m][1] * s; u32x4 w;
;                 w.x = cvt_pk_bf16(w0[0], w0[1]); w.y = cvt_pk_bf16(w0[2], w0[3]); w.z = cvt_pk_bf16(w1[0], w1[1]); w.w = cvt_pk_bf16(w1[2], w1[3]);
;                 *(u32x4*)(V + (size_t)row * 512 + h * 128 + cw) = w;
;                 const f32x4 v0 = acc[ai][0][m][0] * s, v1 = acc[ai][0][m][1] * s;
;                 float ss = ((v0[0] * v0[0] + v0[1] * v0[1]) + (v0[2] * v0[2] + v0[3] * v0[3])) + ((v1[0] * v1[0] + v1[1] * v1[1]) + (v1[2] * v1[2] + v1[3] * v1[3]));
;                 ss += shx(ss, 16, ln); ss += shx(ss, 32, ln);
;                 if (fq == 0) part[(ai * 128 + wr * 64 + m * 16 + fr) * 4 + wc] = ss; }
.LBB0_1877:
	v_lshl_add_u32 v192, s93, 8, v175
	v_ashrrev_i32_e32 v193, 31, v192
	v_or_b32_e32 v190, 16, v192
	v_lshl_add_u64 v[128:129], v[192:193], 4, s[22:23]
	v_ashrrev_i32_e32 v191, 31, v190
	global_load_dwordx4 v[206:209], v[128:129], off
	v_lshl_add_u64 v[128:129], v[190:191], 4, s[22:23]
	global_load_dwordx4 v[210:213], v[128:129], off
	v_or_b32_e32 v188, 32, v192
	v_or_b32_e32 v186, 48, v192
	v_add_u32_e32 v184, 0x80, v192
	v_add_u32_e32 v182, 0x90, v192
	v_add_u32_e32 v180, 0xa0, v192
	v_add_u32_e32 v178, 0xb0, v192
	v_ashrrev_i32_e32 v189, 31, v188
	v_ashrrev_i32_e32 v187, 31, v186
	v_ashrrev_i32_e32 v185, 31, v184
	v_ashrrev_i32_e32 v183, 31, v182
	v_ashrrev_i32_e32 v181, 31, v180
	v_ashrrev_i32_e32 v179, 31, v178
	v_lshl_add_u64 v[128:129], v[188:189], 4, s[22:23]
	v_lshl_add_u64 v[130:131], v[186:187], 4, s[22:23]
	v_lshl_add_u64 v[132:133], v[184:185], 4, s[22:23]
	v_lshl_add_u64 v[134:135], v[182:183], 4, s[22:23]
	v_lshl_add_u64 v[196:197], v[180:181], 4, s[22:23]
	v_lshl_add_u64 v[214:215], v[178:179], 4, s[22:23]
	global_load_dwordx4 v[148:151], v[128:129], off
	global_load_dwordx4 v[144:147], v[130:131], off
	global_load_dwordx4 v[140:143], v[132:133], off
	global_load_dwordx4 v[136:139], v[134:135], off
	s_nop 0
	global_load_dwordx4 v[132:135], v[196:197], off
	global_load_dwordx4 v[128:131], v[214:215], off
	s_lshl_b32 s62, s92, 7
	s_ashr_i32 s63, s62, 31
	s_waitcnt vmcnt(0)
	v_mov_b32_e32 v196, v207
	v_mov_b32_e32 v197, v208
	v_mov_b32_e32 v207, v209
	v_add_f32_e32 v196, v196, v206
	v_add_f32_e32 v197, v197, v207
	v_mov_b32_e32 v206, v211
	v_mov_b32_e32 v207, v212
	v_mov_b32_e32 v211, v213
	v_add_f32_e32 v206, v206, v210
	v_add_f32_e32 v207, v207, v211
	v_mov_b32_e32 v209, v196
	v_mov_b32_e32 v208, v206
	v_mov_b32_e32 v196, v207
	v_add_f32_e32 v196, v208, v196
	v_add_f32_e32 v197, v209, v197
	s_nop 0
	v_pk_fma_f32 v[196:197], v[196:197], s[36:37], v[174:175] op_sel_hi:[1,0,0]
	s_nop 0
	v_mul_f32_e32 v177, 0x4b800000, v197
	v_cmp_gt_f32_e64 s[8:9], s87, v197
	v_cmp_gt_f32_e32 vcc, s87, v196
	s_nop 0
	v_cndmask_b32_e64 v177, v197, v177, s[8:9]
	v_rsq_f32_e32 v177, v177
	s_nop 0
	v_mul_f32_e32 v194, 0x45800000, v177
	v_cndmask_b32_e64 v194, v177, v194, s[8:9]
	v_mul_f32_e32 v124, v124, v194
	v_mul_f32_e32 v125, v125, v194
	v_mul_f32_e32 v208, v58, v194
	v_mul_f32_e32 v209, v59, v194
	v_mul_f32_e32 v210, v56, v194
	v_mul_f32_e32 v211, v57, v194
	v_mul_f32_e32 v212, v62, v194
	v_mul_f32_e32 v213, v63, v194
	v_mul_f32_e32 v214, v60, v194
	v_mul_f32_e32 v215, v61, v194
	v_mul_f32_e32 v206, v122, v194
	v_mul_f32_e32 v207, v123, v194
	v_cvt_pk_bf16_f32 v122, v124, v125
	v_mul_f32_e32 v123, v211, v211
	v_mul_f32_e32 v124, v209, v209
	v_mul_f32_e32 v125, v215, v215
	v_mul_f32_e32 v177, v213, v213
	v_fmac_f32_e32 v123, v210, v210
	v_fmac_f32_e32 v124, v208, v208
	v_fmac_f32_e32 v125, v214, v214
	v_fmac_f32_e32 v177, v212, v212
	v_add_f32_e32 v123, v123, v124
	v_add_f32_e32 v124, v125, v177
	v_add_f32_e32 v177, v123, v124
	ds_bpermute_b32 v197, v198, v177
	v_mul_f32_e32 v120, v120, v194
	v_mul_f32_e32 v121, v121, v194
	v_mul_f32_e32 v126, v126, v194
	v_mul_f32_e32 v127, v127, v194
	s_nop 0
	v_cvt_pk_bf16_f32 v123, v126, v127
	v_cvt_pk_bf16_f32 v124, v120, v121
	s_waitcnt lgkmcnt(0)
	v_add_f32_e32 v120, v177, v197
	ds_bpermute_b32 v121, v199, v120
	v_lshlrev_b64 v[126:127], 10, v[192:193]
	v_lshl_add_u64 v[126:127], s[12:13], 0, v[126:127]
	v_lshl_add_u64 v[126:127], s[62:63], 1, v[126:127]
	v_lshl_add_u64 v[126:127], v[126:127], 0, v[160:161]
	v_cvt_pk_bf16_f32 v125, v206, v207
	global_store_dwordx4 v[126:127], v[122:125], off sc1
	s_and_saveexec_b64 s[8:9], s[4:5]
	s_cbranch_execz .LBB0_1879
	s_waitcnt lgkmcnt(0)
	v_add_f32_e32 v120, v120, v121
	ds_write_b32 v201, v120
.LBB0_1879:
	s_or_b64 exec, exec, s[8:9]
	v_mul_f32_e32 v120, 0x4b800000, v196
	v_cndmask_b32_e32 v120, v196, v120, vcc
	v_rsq_f32_e32 v120, v120
	s_waitcnt lgkmcnt(0)
	v_mul_f32_e32 v121, 0x45800000, v120
	v_cndmask_b32_e32 v120, v120, v121, vcc
	v_mul_f32_e32 v116, v116, v120
	v_mul_f32_e32 v117, v117, v120
	v_mul_f32_e32 v122, v114, v120
	v_mul_f32_e32 v123, v115, v120
	v_cvt_pk_bf16_f32 v114, v116, v117
	v_mul_f32_e32 v116, v54, v120
	v_mul_f32_e32 v117, v55, v120
	v_mul_f32_e32 v124, v52, v120
	v_mul_f32_e32 v125, v53, v120
	v_mul_f32_e32 v117, v117, v117
	v_mul_f32_e32 v115, v125, v125
	v_mul_f32_e32 v126, v50, v120
	v_mul_f32_e32 v127, v51, v120
	v_mul_f32_e32 v196, v48, v120
	v_mul_f32_e32 v197, v49, v120
	v_fmac_f32_e32 v115, v124, v124
	v_fmac_f32_e32 v117, v116, v116
	v_add_f32_e32 v115, v115, v117
	v_mul_f32_e32 v116, v197, v197
	v_mul_f32_e32 v117, v127, v127
	v_fmac_f32_e32 v116, v196, v196
	v_fmac_f32_e32 v117, v126, v126
	v_add_f32_e32 v116, v116, v117
	v_mul_f32_e32 v118, v118, v120
	v_mul_f32_e32 v119, v119, v120
	v_mul_f32_e32 v112, v112, v120
	v_mul_f32_e32 v113, v113, v120
	v_add_f32_e32 v121, v115, v116
	ds_bpermute_b32 v124, v198, v121
	v_cvt_pk_bf16_f32 v115, v118, v119
	v_cvt_pk_bf16_f32 v116, v112, v113
	v_lshlrev_b64 v[118:119], 10, v[190:191]
	v_lshl_add_u64 v[118:119], s[12:13], 0, v[118:119]
	s_waitcnt lgkmcnt(0)
	v_add_f32_e32 v112, v121, v124
	ds_bpermute_b32 v113, v199, v112
	v_lshl_add_u64 v[118:119], s[62:63], 1, v[118:119]
	v_lshl_add_u64 v[118:119], v[118:119], 0, v[160:161]
	v_cvt_pk_bf16_f32 v117, v122, v123
	global_store_dwordx4 v[118:119], v[114:117], off sc1
	s_and_saveexec_b64 s[8:9], s[4:5]
	s_cbranch_execz .LBB0_1881
	s_waitcnt lgkmcnt(0)
	v_add_f32_e32 v112, v112, v113
	ds_write_b32 v201, v112 offset:256
; __device__ __forceinline__ unsigned cvt_pk_bf16(float lo, float hi) { unsigned r; asm volatile("v_cvt_pk_bf16_f32 %0, %1, %2" : "=v"(r) : "v"(lo), "v"(hi)); return r; }
; DI float shx(float v, int mask, int lane) { return __int_as_float(__builtin_amdgcn_ds_bpermute((lane ^ mask) << 2, __float_as_int(v))); }
;     DI void operator()(const f32x4 (&acc)[2][2][4][2], const Unit& u, int wr, int wc, int fr, int fq) const {
;     ...
; #pragma unroll
;         for (int ai = 0; ai < 2; ++ai)
; #pragma unroll
;             for (int m = 0; m < 4; ++m) { const int row = row0 + ai * 128 + m * 16; const float s = rs[ai][m];
;                 const f32x4 w0 = acc[ai][1][m][0] * s, w1 = acc[ai][1][m][1] * s; u32x4 w;
;                 w.x = cvt_pk_bf16(w0[0], w0[1]); w.y = cvt_pk_bf16(w0[2], w0[3]); w.z = cvt_pk_bf16(w1[0], w1[1]); w.w = cvt_pk_bf16(w1[2], w1[3]);
;                 *(u32x4*)(V + (size_t)row * 512 + h * 128 + cw) = w;
;                 const f32x4 v0 = acc[ai][0][m][0] * s, v1 = acc[ai][0][m][1] * s;
;                 float ss = ((v0[0] * v0[0] + v0[1] * v0[1]) + (v0[2] * v0[2] + v0[3] * v0[3])) + ((v1[0] * v1[0] + v1[1] * v1[1]) + (v1[2] * v1[2] + v1[3] * v1[3]));
;                 ss += shx(ss, 16, ln); ss += shx(ss, 32, ln);
;                 if (fq == 0) part[(ai * 128 + wr * 64 + m * 16 + fr) * 4 + wc] = ss; }
.LBB0_1881:
	s_or_b64 exec, exec, s[8:9]
	v_mov_b32_e32 v112, v149
	s_waitcnt lgkmcnt(0)
	v_mov_b32_e32 v113, v150
	v_mov_b32_e32 v149, v151
	v_mov_b32_e32 v114, v145
	v_mov_b32_e32 v115, v146
	v_mov_b32_e32 v145, v147
	v_add_f32_e32 v112, v112, v148
	v_add_f32_e32 v113, v113, v149
	v_add_f32_e32 v114, v114, v144
	v_add_f32_e32 v115, v115, v145
	v_mov_b32_e32 v117, v112
	v_mov_b32_e32 v116, v114
	v_mov_b32_e32 v112, v115
	v_add_f32_e32 v112, v116, v112
	v_add_f32_e32 v113, v117, v113
	s_nop 0
	v_pk_fma_f32 v[114:115], v[112:113], s[36:37], v[174:175] op_sel_hi:[1,0,0]
	s_nop 0
	v_mul_f32_e32 v112, 0x4b800000, v115
	v_cmp_gt_f32_e64 s[8:9], s87, v115
	v_cmp_gt_f32_e32 vcc, s87, v114
	s_nop 0
	v_cndmask_b32_e64 v112, v115, v112, s[8:9]
	v_rsq_f32_e32 v112, v112
	s_nop 0
	v_mul_f32_e32 v113, 0x45800000, v112
	v_cndmask_b32_e64 v112, v112, v113, s[8:9]
	v_mul_f32_e32 v108, v108, v112
	v_mul_f32_e32 v109, v109, v112
	v_mul_f32_e32 v116, v106, v112
	v_mul_f32_e32 v117, v107, v112
	v_cvt_pk_bf16_f32 v106, v108, v109
	v_mul_f32_e32 v108, v46, v112
	v_mul_f32_e32 v109, v47, v112
	v_mul_f32_e32 v118, v44, v112
	v_mul_f32_e32 v119, v45, v112
	v_mul_f32_e32 v109, v109, v109
	v_mul_f32_e32 v107, v119, v119
	v_mul_f32_e32 v122, v42, v112
	v_mul_f32_e32 v123, v43, v112
	v_mul_f32_e32 v124, v40, v112
	v_mul_f32_e32 v125, v41, v112
	v_fmac_f32_e32 v107, v118, v118
	v_fmac_f32_e32 v109, v108, v108
	v_add_f32_e32 v107, v107, v109
	v_mul_f32_e32 v108, v125, v125
	v_mul_f32_e32 v109, v123, v123
	v_fmac_f32_e32 v108, v124, v124
	v_fmac_f32_e32 v109, v122, v122
	v_add_f32_e32 v108, v108, v109
	v_mul_f32_e32 v110, v110, v112
	v_mul_f32_e32 v111, v111, v112
	v_mul_f32_e32 v104, v104, v112
	v_mul_f32_e32 v105, v105, v112
	v_add_f32_e32 v113, v107, v108
	ds_bpermute_b32 v115, v198, v113
	v_cvt_pk_bf16_f32 v107, v110, v111
	v_cvt_pk_bf16_f32 v108, v104, v105
	v_lshlrev_b64 v[110:111], 10, v[188:189]
	v_lshl_add_u64 v[110:111], s[12:13], 0, v[110:111]
	s_waitcnt lgkmcnt(0)
	v_add_f32_e32 v104, v113, v115
	ds_bpermute_b32 v105, v199, v104
	v_lshl_add_u64 v[110:111], s[62:63], 1, v[110:111]
	v_lshl_add_u64 v[110:111], v[110:111], 0, v[160:161]
	v_cvt_pk_bf16_f32 v109, v116, v117
	global_store_dwordx4 v[110:111], v[106:109], off sc1
	s_and_saveexec_b64 s[8:9], s[4:5]
	s_cbranch_execz .LBB0_1883
	s_waitcnt lgkmcnt(0)
	v_add_f32_e32 v104, v104, v105
	ds_write_b32 v201, v104 offset:512
.LBB0_1883:
	s_or_b64 exec, exec, s[8:9]
	v_mul_f32_e32 v104, 0x4b800000, v114
	v_cndmask_b32_e32 v104, v114, v104, vcc
	v_rsq_f32_e32 v104, v104
	s_waitcnt lgkmcnt(0)
	v_mul_f32_e32 v105, 0x45800000, v104
	v_cndmask_b32_e32 v104, v104, v105, vcc
	v_mul_f32_e32 v100, v100, v104
	v_mul_f32_e32 v101, v101, v104
	v_mul_f32_e32 v106, v98, v104
	v_mul_f32_e32 v107, v99, v104
	v_cvt_pk_bf16_f32 v98, v100, v101
	v_mul_f32_e32 v100, v38, v104
	v_mul_f32_e32 v101, v39, v104
	v_mul_f32_e32 v108, v36, v104
	v_mul_f32_e32 v109, v37, v104
	v_mul_f32_e32 v101, v101, v101
	v_mul_f32_e32 v99, v109, v109
	v_mul_f32_e32 v110, v34, v104
	v_mul_f32_e32 v111, v35, v104
	v_mul_f32_e32 v114, v32, v104
	v_mul_f32_e32 v115, v33, v104
	v_fmac_f32_e32 v99, v108, v108
	v_fmac_f32_e32 v101, v100, v100
	v_add_f32_e32 v99, v99, v101
	v_mul_f32_e32 v100, v115, v115
	v_mul_f32_e32 v101, v111, v111
	v_fmac_f32_e32 v100, v114, v114
	v_fmac_f32_e32 v101, v110, v110
	v_add_f32_e32 v100, v100, v101
	v_mul_f32_e32 v102, v102, v104
	v_mul_f32_e32 v103, v103, v104
	v_mul_f32_e32 v96, v96, v104
	v_mul_f32_e32 v97, v97, v104
	v_add_f32_e32 v105, v99, v100
	ds_bpermute_b32 v108, v198, v105
	v_cvt_pk_bf16_f32 v99, v102, v103
	v_cvt_pk_bf16_f32 v100, v96, v97
	v_lshlrev_b64 v[102:103], 10, v[186:187]
	v_lshl_add_u64 v[102:103], s[12:13], 0, v[102:103]
	s_waitcnt lgkmcnt(0)
	v_add_f32_e32 v96, v105, v108
	ds_bpermute_b32 v97, v199, v96
	v_lshl_add_u64 v[102:103], s[62:63], 1, v[102:103]
	v_lshl_add_u64 v[102:103], v[102:103], 0, v[160:161]
	v_cvt_pk_bf16_f32 v101, v106, v107
	global_store_dwordx4 v[102:103], v[98:101], off sc1
	s_and_saveexec_b64 s[8:9], s[4:5]
	s_cbranch_execz .LBB0_1885
	s_waitcnt lgkmcnt(0)
	v_add_f32_e32 v96, v96, v97
	ds_write_b32 v201, v96 offset:768
.LBB0_1885:
	s_or_b64 exec, exec, s[8:9]
	v_mov_b32_e32 v96, v141
	s_waitcnt lgkmcnt(0)
	v_mov_b32_e32 v97, v142
	v_mov_b32_e32 v141, v143
	v_mov_b32_e32 v98, v137
	v_mov_b32_e32 v99, v138
	v_mov_b32_e32 v137, v139
	v_add_f32_e32 v96, v96, v140
	v_add_f32_e32 v97, v97, v141
	v_add_f32_e32 v98, v98, v136
	v_add_f32_e32 v99, v99, v137
	v_mov_b32_e32 v101, v96
	v_mov_b32_e32 v100, v98
	v_mov_b32_e32 v96, v99
	v_add_f32_e32 v96, v100, v96
	v_add_f32_e32 v97, v101, v97
	s_nop 0
	v_pk_fma_f32 v[98:99], v[96:97], s[36:37], v[174:175] op_sel_hi:[1,0,0]
	s_nop 0
	v_mul_f32_e32 v96, 0x4b800000, v99
	v_cmp_gt_f32_e64 s[8:9], s87, v99
	v_cmp_gt_f32_e32 vcc, s87, v98
	s_nop 0
	v_cndmask_b32_e64 v96, v99, v96, s[8:9]
	v_rsq_f32_e32 v96, v96
	s_nop 0
	v_mul_f32_e32 v97, 0x45800000, v96
	v_cndmask_b32_e64 v96, v96, v97, s[8:9]
	v_mul_f32_e32 v92, v92, v96
	v_mul_f32_e32 v93, v93, v96
	v_mul_f32_e32 v100, v90, v96
	v_mul_f32_e32 v101, v91, v96
	v_cvt_pk_bf16_f32 v90, v92, v93
	v_mul_f32_e32 v92, v30, v96
	v_mul_f32_e32 v93, v31, v96
	v_mul_f32_e32 v102, v28, v96
	v_mul_f32_e32 v103, v29, v96
	v_mul_f32_e32 v93, v93, v93
	v_mul_f32_e32 v91, v103, v103
	v_mul_f32_e32 v106, v26, v96
	v_mul_f32_e32 v107, v27, v96
	v_mul_f32_e32 v108, v24, v96
	v_mul_f32_e32 v109, v25, v96
	v_fmac_f32_e32 v91, v102, v102
	v_fmac_f32_e32 v93, v92, v92
	v_add_f32_e32 v91, v91, v93
	v_mul_f32_e32 v92, v109, v109
	v_mul_f32_e32 v93, v107, v107
	v_fmac_f32_e32 v92, v108, v108
	v_fmac_f32_e32 v93, v106, v106
	v_add_f32_e32 v92, v92, v93
	v_mul_f32_e32 v94, v94, v96
	v_mul_f32_e32 v95, v95, v96
	v_mul_f32_e32 v88, v88, v96
	v_mul_f32_e32 v89, v89, v96
	v_add_f32_e32 v97, v91, v92
	ds_bpermute_b32 v99, v198, v97
	v_cvt_pk_bf16_f32 v91, v94, v95
	v_cvt_pk_bf16_f32 v92, v88, v89
	v_lshlrev_b64 v[94:95], 10, v[184:185]
	v_lshl_add_u64 v[94:95], s[12:13], 0, v[94:95]
	s_waitcnt lgkmcnt(0)
	v_add_f32_e32 v88, v97, v99
	ds_bpermute_b32 v89, v199, v88
	v_lshl_add_u64 v[94:95], s[62:63], 1, v[94:95]
	v_lshl_add_u64 v[94:95], v[94:95], 0, v[160:161]
	v_cvt_pk_bf16_f32 v93, v100, v101
	global_store_dwordx4 v[94:95], v[90:93], off sc1
	s_and_saveexec_b64 s[8:9], s[4:5]
	s_cbranch_execz .LBB0_1887
	s_waitcnt lgkmcnt(0)
	v_add_f32_e32 v88, v88, v89
	ds_write_b32 v201, v88 offset:2048
; __device__ __forceinline__ unsigned cvt_pk_bf16(float lo, float hi) { unsigned r; asm volatile("v_cvt_pk_bf16_f32 %0, %1, %2" : "=v"(r) : "v"(lo), "v"(hi)); return r; }
; DI float shx(float v, int mask, int lane) { return __int_as_float(__builtin_amdgcn_ds_bpermute((lane ^ mask) << 2, __float_as_int(v))); }
;     DI void operator()(const f32x4 (&acc)[2][2][4][2], const Unit& u, int wr, int wc, int fr, int fq) const {
;     ...
; #pragma unroll
;         for (int ai = 0; ai < 2; ++ai)
; #pragma unroll
;             for (int m = 0; m < 4; ++m) { const int row = row0 + ai * 128 + m * 16; const float s = rs[ai][m];
;                 const f32x4 w0 = acc[ai][1][m][0] * s, w1 = acc[ai][1][m][1] * s; u32x4 w;
;                 w.x = cvt_pk_bf16(w0[0], w0[1]); w.y = cvt_pk_bf16(w0[2], w0[3]); w.z = cvt_pk_bf16(w1[0], w1[1]); w.w = cvt_pk_bf16(w1[2], w1[3]);
;                 *(u32x4*)(V + (size_t)row * 512 + h * 128 + cw) = w;
;                 const f32x4 v0 = acc[ai][0][m][0] * s, v1 = acc[ai][0][m][1] * s;
;                 float ss = ((v0[0] * v0[0] + v0[1] * v0[1]) + (v0[2] * v0[2] + v0[3] * v0[3])) + ((v1[0] * v1[0] + v1[1] * v1[1]) + (v1[2] * v1[2] + v1[3] * v1[3]));
;                 ss += shx(ss, 16, ln); ss += shx(ss, 32, ln);
;                 if (fq == 0) part[(ai * 128 + wr * 64 + m * 16 + fr) * 4 + wc] = ss; }
.LBB0_1887:
	s_or_b64 exec, exec, s[8:9]
	v_mul_f32_e32 v88, 0x4b800000, v98
	v_cndmask_b32_e32 v88, v98, v88, vcc
	v_rsq_f32_e32 v88, v88
	s_waitcnt lgkmcnt(0)
	v_mul_f32_e32 v89, 0x45800000, v88
	v_cndmask_b32_e32 v88, v88, v89, vcc
	v_mul_f32_e32 v84, v84, v88
	v_mul_f32_e32 v85, v85, v88
	v_mul_f32_e32 v90, v82, v88
	v_mul_f32_e32 v91, v83, v88
	v_cvt_pk_bf16_f32 v82, v84, v85
	v_mul_f32_e32 v84, v22, v88
	v_mul_f32_e32 v85, v23, v88
	v_mul_f32_e32 v92, v20, v88
	v_mul_f32_e32 v93, v21, v88
	v_mul_f32_e32 v85, v85, v85
	v_mul_f32_e32 v83, v93, v93
	v_mul_f32_e32 v94, v18, v88
	v_mul_f32_e32 v95, v19, v88
	v_mul_f32_e32 v98, v16, v88
	v_mul_f32_e32 v99, v17, v88
	v_fmac_f32_e32 v83, v92, v92
	v_fmac_f32_e32 v85, v84, v84
	v_add_f32_e32 v83, v83, v85
	v_mul_f32_e32 v84, v99, v99
	v_mul_f32_e32 v85, v95, v95
	v_fmac_f32_e32 v84, v98, v98
	v_fmac_f32_e32 v85, v94, v94
	v_add_f32_e32 v84, v84, v85
	v_mul_f32_e32 v86, v86, v88
	v_mul_f32_e32 v87, v87, v88
	v_mul_f32_e32 v80, v80, v88
	v_mul_f32_e32 v81, v81, v88
	v_add_f32_e32 v89, v83, v84
	ds_bpermute_b32 v92, v198, v89
	v_cvt_pk_bf16_f32 v83, v86, v87
	v_cvt_pk_bf16_f32 v84, v80, v81
	v_lshlrev_b64 v[86:87], 10, v[182:183]
	v_lshl_add_u64 v[86:87], s[12:13], 0, v[86:87]
	s_waitcnt lgkmcnt(0)
	v_add_f32_e32 v80, v89, v92
	ds_bpermute_b32 v81, v199, v80
	v_lshl_add_u64 v[86:87], s[62:63], 1, v[86:87]
	v_lshl_add_u64 v[86:87], v[86:87], 0, v[160:161]
	v_cvt_pk_bf16_f32 v85, v90, v91
	global_store_dwordx4 v[86:87], v[82:85], off sc1
	s_and_saveexec_b64 s[8:9], s[4:5]
	s_cbranch_execz .LBB0_1889
	s_waitcnt lgkmcnt(0)
	v_add_f32_e32 v80, v80, v81
	ds_write_b32 v201, v80 offset:2304
.LBB0_1889:
	s_or_b64 exec, exec, s[8:9]
	v_mov_b32_e32 v80, v133
	s_waitcnt lgkmcnt(0)
	v_mov_b32_e32 v81, v134
	v_mov_b32_e32 v133, v135
	v_mov_b32_e32 v82, v129
	v_mov_b32_e32 v83, v130
	v_mov_b32_e32 v129, v131
	v_add_f32_e32 v80, v80, v132
	v_add_f32_e32 v81, v81, v133
	v_add_f32_e32 v82, v82, v128
	v_add_f32_e32 v83, v83, v129
	v_mov_b32_e32 v85, v80
	v_mov_b32_e32 v84, v82
	v_mov_b32_e32 v80, v83
	v_add_f32_e32 v80, v84, v80
	v_add_f32_e32 v81, v85, v81
	s_nop 0
	v_pk_fma_f32 v[82:83], v[80:81], s[36:37], v[174:175] op_sel_hi:[1,0,0]
	s_nop 0
	v_mul_f32_e32 v80, 0x4b800000, v83
	v_cmp_gt_f32_e64 s[8:9], s87, v83
	v_cmp_gt_f32_e32 vcc, s87, v82
	s_nop 0
	v_cndmask_b32_e64 v80, v83, v80, s[8:9]
	v_rsq_f32_e32 v80, v80
	s_nop 0
	v_mul_f32_e32 v81, 0x45800000, v80
	v_cndmask_b32_e64 v80, v80, v81, s[8:9]
	v_mul_f32_e32 v76, v76, v80
	v_mul_f32_e32 v77, v77, v80
	v_mul_f32_e32 v84, v74, v80
	v_mul_f32_e32 v85, v75, v80
	v_cvt_pk_bf16_f32 v74, v76, v77
	v_mul_f32_e32 v76, v14, v80
	v_mul_f32_e32 v77, v15, v80
	v_mul_f32_e32 v86, v12, v80
	v_mul_f32_e32 v87, v13, v80
	v_mul_f32_e32 v77, v77, v77
	v_mul_f32_e32 v75, v87, v87
	v_mul_f32_e32 v90, v10, v80
	v_mul_f32_e32 v91, v11, v80
	v_mul_f32_e32 v92, v8, v80
	v_mul_f32_e32 v93, v9, v80
	v_fmac_f32_e32 v75, v86, v86
	v_fmac_f32_e32 v77, v76, v76
	v_add_f32_e32 v75, v75, v77
	v_mul_f32_e32 v76, v93, v93
	v_mul_f32_e32 v77, v91, v91
	v_fmac_f32_e32 v76, v92, v92
	v_fmac_f32_e32 v77, v90, v90
	v_add_f32_e32 v76, v76, v77
	v_mul_f32_e32 v78, v78, v80
	v_mul_f32_e32 v79, v79, v80
	v_mul_f32_e32 v72, v72, v80
	v_mul_f32_e32 v73, v73, v80
	v_add_f32_e32 v81, v75, v76
	ds_bpermute_b32 v83, v198, v81
	v_cvt_pk_bf16_f32 v75, v78, v79
	v_cvt_pk_bf16_f32 v76, v72, v73
	v_lshlrev_b64 v[78:79], 10, v[180:181]
	v_lshl_add_u64 v[78:79], s[12:13], 0, v[78:79]
	s_waitcnt lgkmcnt(0)
	v_add_f32_e32 v72, v81, v83
	ds_bpermute_b32 v73, v199, v72
	v_lshl_add_u64 v[78:79], s[62:63], 1, v[78:79]
	v_lshl_add_u64 v[78:79], v[78:79], 0, v[160:161]
	v_cvt_pk_bf16_f32 v77, v84, v85
	global_store_dwordx4 v[78:79], v[74:77], off sc1
	s_and_saveexec_b64 s[8:9], s[4:5]
	s_cbranch_execz .LBB0_1891
	s_waitcnt lgkmcnt(0)
	v_add_f32_e32 v72, v72, v73
	ds_write_b32 v201, v72 offset:2560
.LBB0_1891:
	s_or_b64 exec, exec, s[8:9]
	v_mul_f32_e32 v72, 0x4b800000, v82
	v_cndmask_b32_e32 v72, v82, v72, vcc
	v_rsq_f32_e32 v72, v72
	s_waitcnt lgkmcnt(0)
	v_mul_f32_e32 v73, 0x45800000, v72
	v_cndmask_b32_e32 v76, v72, v73, vcc
	v_mul_f32_e32 v68, v68, v76
	v_mul_f32_e32 v69, v69, v76
	v_mul_f32_e32 v72, v66, v76
	v_mul_f32_e32 v73, v67, v76
	v_cvt_pk_bf16_f32 v66, v68, v69
	v_mul_f32_e32 v68, v6, v76
	v_mul_f32_e32 v69, v7, v76
	v_mul_f32_e32 v74, v4, v76
	v_mul_f32_e32 v75, v5, v76
	v_mul_f32_e32 v69, v69, v69
	v_mul_f32_e32 v67, v75, v75
	v_mul_f32_e32 v78, v2, v76
	v_mul_f32_e32 v79, v3, v76
	v_mul_f32_e32 v82, v0, v76
	v_mul_f32_e32 v83, v1, v76
	v_fmac_f32_e32 v67, v74, v74
	v_fmac_f32_e32 v69, v68, v68
	v_add_f32_e32 v67, v67, v69
	v_mul_f32_e32 v68, v83, v83
	v_mul_f32_e32 v69, v79, v79
	v_fmac_f32_e32 v68, v82, v82
	v_fmac_f32_e32 v69, v78, v78
	v_add_f32_e32 v68, v68, v69
	v_add_f32_e32 v74, v67, v68
	ds_bpermute_b32 v75, v198, v74
	v_mul_f32_e32 v64, v64, v76
	v_mul_f32_e32 v65, v65, v76
	v_mul_f32_e32 v70, v70, v76
	v_mul_f32_e32 v71, v71, v76
	s_nop 0
	v_cvt_pk_bf16_f32 v67, v70, v71
	v_cvt_pk_bf16_f32 v68, v64, v65
	s_waitcnt lgkmcnt(0)
	v_add_f32_e32 v64, v74, v75
	ds_bpermute_b32 v65, v199, v64
	v_lshlrev_b64 v[70:71], 10, v[178:179]
	v_lshl_add_u64 v[70:71], s[12:13], 0, v[70:71]
	v_lshl_add_u64 v[70:71], s[62:63], 1, v[70:71]
	v_lshl_add_u64 v[70:71], v[70:71], 0, v[160:161]
	v_cvt_pk_bf16_f32 v69, v72, v73
	global_store_dwordx4 v[70:71], v[66:69], off sc1
	s_and_saveexec_b64 s[8:9], s[4:5]
	s_cbranch_execz .LBB0_1893
	s_waitcnt lgkmcnt(0)
	v_add_f32_e32 v64, v64, v65
	ds_write_b32 v201, v64 offset:2816
; #define LAS __attribute__((address_space(3)))
; __device__ __forceinline__ unsigned cvt_pk_bf16(float lo, float hi) { unsigned r; asm volatile("v_cvt_pk_bf16_f32 %0, %1, %2" : "=v"(r) : "v"(lo), "v"(hi)); return r; }
;     DI void operator()(const f32x4 (&acc)[2][2][4][2], const Unit& u, int wr, int wc, int fr, int fq) const {
;     ...
;         const f32x4 g0 = *(const f32x4*)(gk + cw), g1 = *(const f32x4*)(gk + cw + 4), gr = *(const f32x4*)(gk + 128 + wc * 16 + fq * 4);
;         asm volatile("s_waitcnt lgkmcnt(0)" ::: "memory"); __builtin_amdgcn_s_barrier(); asm volatile("" ::: "memory");
; #pragma unroll
;         for (int ai = 0; ai < 2; ++ai)
; #pragma unroll
;             for (int m = 0; m < 4; ++m) { const int row = row0 + ai * 128 + m * 16; const f32x4 pp = *(const LAS f32x4*)(part + (ai * 128 + wr * 64 + m * 16 + fr) * 4);
;                 const f32x2_ kr2 = *(const f32x2_*)(sskr2 + (size_t)row * 2);
;                 const float rstd = rsqrtf((((pp[0] + pp[1]) + (pp[2] + pp[3])) + (kr2[0] + kr2[1])) * (1.f / 192.f) + EPS), s = rs[ai][m] * rstd;
;                 const f32x4 v0 = acc[ai][0][m][0] * s * g0, v1 = acc[ai][0][m][1] * s * g1; u32x4 w;
;                 w.x = cvt_pk_bf16(v0[0], v0[1]); w.y = cvt_pk_bf16(v0[2], v0[3]); w.z = cvt_pk_bf16(v1[0], v1[1]); w.w = cvt_pk_bf16(v1[2], v1[3]);
;                 bf16_t* kp = KM + (size_t)row * 768 + h * 192;
;                 *(u32x4*)(kp + cw) = w;
;                 const f32x4 kr = *(const f32x4*)(KR + (size_t)row * 64 + wc * 16 + fq * 4) * rstd * gr; u32x2 r2; r2.x = cvt_pk_bf16(kr[0], kr[1]); r2.y = cvt_pk_bf16(kr[2], kr[3]);
;                 *(u32x2*)(kp + 128 + wc * 16 + fq * 4) = r2; }
.LBB0_1893:
	s_or_b64 exec, exec, s[8:9]
	global_load_dwordx4 v[68:71], v[164:165], off offset:16
	global_load_dwordx4 v[72:75], v[164:165], off
	s_waitcnt lgkmcnt(0)
	global_load_dwordx4 v[64:67], v[166:167], off offset:512
	s_waitcnt lgkmcnt(0)
	s_barrier
	v_lshl_add_u64 v[78:79], v[192:193], 3, s[24:25]
	global_load_dwordx2 v[86:87], v[78:79], off
	ds_read_b128 v[82:85], v200
	s_mul_i32 s0, s92, 0xc0
	v_mov_b64_e32 v[78:79], s[20:21]
	s_ashr_i32 s1, s0, 31
	v_mad_i64_i32 v[92:93], s[2:3], v192, s88, v[78:79]
	s_waitcnt lgkmcnt(0)
	v_add_f32_e32 v77, v84, v85
	v_mov_b32_e32 v84, v82
	s_lshl_b64 s[8:9], s[0:1], 1
	v_lshlrev_b64 v[90:91], 8, v[192:193]
	v_lshl_add_u64 v[90:91], v[162:163], 0, v[90:91]
	v_mov_b32_e32 v177, v161
	s_waitcnt vmcnt(0)
	v_mov_b32_e32 v85, v86
	v_mov_b32_e32 v86, v83
	v_add_f32_e32 v82, v84, v86
	v_add_f32_e32 v83, v85, v87
	s_nop 0
	v_add_f32_e32 v77, v82, v77
	v_add_f32_e32 v77, v77, v83
	v_fmamk_f32 v77, v77, 0x3baaaaab, v174
	v_mul_f32_e32 v81, 0x4b800000, v77
	v_cmp_gt_f32_e32 vcc, s87, v77
	v_lshl_add_u64 v[82:83], v[92:93], 0, s[8:9]
	v_lshl_add_u64 v[84:85], v[82:83], 0, v[160:161]
	v_cndmask_b32_e32 v77, v77, v81, vcc
	v_rsq_f32_e32 v77, v77
	s_nop 0
	v_mul_f32_e32 v81, 0x45800000, v77
	v_cndmask_b32_e32 v86, v77, v81, vcc
	v_mul_f32_e32 v92, v194, v86
	v_mul_f32_e32 v56, v56, v92
	v_mul_f32_e32 v57, v57, v92
	v_mul_f32_e32 v58, v58, v92
	v_mul_f32_e32 v59, v59, v92
	v_mul_f32_e32 v60, v60, v92
	v_mul_f32_e32 v61, v61, v92
	v_mul_f32_e32 v62, v62, v92
	v_mul_f32_e32 v63, v63, v92
	v_mul_f32_e32 v58, v74, v58
	v_mul_f32_e32 v59, v75, v59
	v_mul_f32_e32 v56, v72, v56
	v_mul_f32_e32 v57, v73, v57
	v_mul_f32_e32 v62, v70, v62
	v_mul_f32_e32 v63, v71, v63
	v_mul_f32_e32 v60, v68, v60
	v_mul_f32_e32 v61, v69, v61
	v_cvt_pk_bf16_f32 v56, v56, v57
	v_cvt_pk_bf16_f32 v57, v58, v59
	s_nop 0
	v_cvt_pk_bf16_f32 v58, v60, v61
	v_cvt_pk_bf16_f32 v59, v62, v63
	global_store_dwordx4 v[84:85], v[56:59], off sc1
	global_load_dwordx4 v[56:59], v[90:91], off
	v_lshl_add_u64 v[62:63], v[82:83], 0, s[48:49]
	v_lshl_add_u64 v[62:63], v[62:63], 0, v[176:177]
	v_lshl_add_u64 v[60:61], v[190:191], 3, s[24:25]
	v_mad_i64_i32 v[82:83], s[0:1], v190, s88, v[78:79]
	s_waitcnt vmcnt(0)
	v_mul_f32_e32 v56, v56, v86
	v_mul_f32_e32 v57, v57, v86
	v_mul_f32_e32 v58, v58, v86
	v_mul_f32_e32 v59, v59, v86
	v_mul_f32_e32 v56, v64, v56
	v_mul_f32_e32 v57, v65, v57
	v_mul_f32_e32 v58, v66, v58
	v_mul_f32_e32 v59, v67, v59
	v_cvt_pk_bf16_f32 v56, v56, v57
	s_nop 0
	v_cvt_pk_bf16_f32 v57, v58, v59
	global_store_dwordx2 v[62:63], v[56:57], off offset:256
	global_load_dwordx2 v[60:61], v[60:61], off
	ds_read_b128 v[56:59], v200 offset:256
	v_lshlrev_b64 v[62:63], 8, v[190:191]
	s_waitcnt lgkmcnt(0)
	v_add_f32_e32 v77, v58, v59
	v_mov_b32_e32 v58, v56
	s_waitcnt vmcnt(0)
	v_mov_b32_e32 v59, v60
	v_mov_b32_e32 v60, v57
	v_add_f32_e32 v56, v58, v60
	v_add_f32_e32 v57, v59, v61
	v_lshl_add_u64 v[58:59], v[82:83], 0, s[8:9]
	v_add_f32_e32 v56, v56, v77
	v_add_f32_e32 v56, v56, v57
	v_fmamk_f32 v56, v56, 0x3baaaaab, v174
	v_mul_f32_e32 v57, 0x4b800000, v56
	v_cmp_gt_f32_e32 vcc, s87, v56
	v_lshl_add_u64 v[60:61], v[58:59], 0, v[160:161]
	s_nop 0
	v_cndmask_b32_e32 v56, v56, v57, vcc
	v_rsq_f32_e32 v77, v56
	v_lshl_add_u64 v[56:57], v[162:163], 0, v[62:63]
	v_mul_f32_e32 v62, 0x45800000, v77
	v_cndmask_b32_e32 v62, v77, v62, vcc
	v_mul_f32_e32 v82, v120, v62
	v_mul_f32_e32 v48, v48, v82
	v_mul_f32_e32 v49, v49, v82
	v_mul_f32_e32 v50, v50, v82
	v_mul_f32_e32 v51, v51, v82
	v_mul_f32_e32 v52, v52, v82
	v_mul_f32_e32 v53, v53, v82
	v_mul_f32_e32 v54, v54, v82
	v_mul_f32_e32 v55, v55, v82
	v_mul_f32_e32 v82, v70, v50
	v_mul_f32_e32 v83, v71, v51
	v_mul_f32_e32 v50, v68, v48
	v_mul_f32_e32 v51, v69, v49
	v_mul_f32_e32 v54, v74, v54
	v_mul_f32_e32 v55, v75, v55
	v_mul_f32_e32 v52, v72, v52
	v_mul_f32_e32 v53, v73, v53
	s_nop 0
	v_cvt_pk_bf16_f32 v48, v52, v53
	v_cvt_pk_bf16_f32 v49, v54, v55
	v_cvt_pk_bf16_f32 v50, v50, v51
	v_cvt_pk_bf16_f32 v51, v82, v83
	global_store_dwordx4 v[60:61], v[48:51], off sc1
	global_load_dwordx4 v[48:51], v[56:57], off
	v_lshl_add_u64 v[54:55], v[58:59], 0, s[48:49]
	v_lshl_add_u64 v[54:55], v[54:55], 0, v[176:177]
	v_lshl_add_u64 v[52:53], v[188:189], 3, s[24:25]
	v_mad_i64_i32 v[56:57], s[0:1], v188, s88, v[78:79]
	s_waitcnt vmcnt(0)
	v_mul_f32_e32 v48, v48, v62
	v_mul_f32_e32 v49, v49, v62
	v_mul_f32_e32 v50, v50, v62
	v_mul_f32_e32 v51, v51, v62
	v_mul_f32_e32 v48, v64, v48
	v_mul_f32_e32 v49, v65, v49
	v_mul_f32_e32 v50, v66, v50
	v_mul_f32_e32 v51, v67, v51
	v_cvt_pk_bf16_f32 v48, v48, v49
	s_nop 0
	v_cvt_pk_bf16_f32 v49, v50, v51
	global_store_dwordx2 v[54:55], v[48:49], off offset:256
	global_load_dwordx2 v[52:53], v[52:53], off
	ds_read_b128 v[48:51], v200 offset:512
	v_lshlrev_b64 v[54:55], 8, v[188:189]
	s_waitcnt lgkmcnt(0)
	v_add_f32_e32 v58, v50, v51
	v_mov_b32_e32 v50, v48
	s_waitcnt vmcnt(0)
; #define LAS __attribute__((address_space(3)))
; __device__ __forceinline__ unsigned cvt_pk_bf16(float lo, float hi) { unsigned r; asm volatile("v_cvt_pk_bf16_f32 %0, %1, %2" : "=v"(r) : "v"(lo), "v"(hi)); return r; }
;     DI void operator()(const f32x4 (&acc)[2][2][4][2], const Unit& u, int wr, int wc, int fr, int fq) const {
;     ...
;             for (int m = 0; m < 4; ++m) { const int row = row0 + ai * 128 + m * 16; const f32x4 pp = *(const LAS f32x4*)(part + (ai * 128 + wr * 64 + m * 16 + fr) * 4);
;                 const f32x2_ kr2 = *(const f32x2_*)(sskr2 + (size_t)row * 2);
;                 const float rstd = rsqrtf((((pp[0] + pp[1]) + (pp[2] + pp[3])) + (kr2[0] + kr2[1])) * (1.f / 192.f) + EPS), s = rs[ai][m] * rstd;
;                 const f32x4 v0 = acc[ai][0][m][0] * s * g0, v1 = acc[ai][0][m][1] * s * g1; u32x4 w;
;                 w.x = cvt_pk_bf16(v0[0], v0[1]); w.y = cvt_pk_bf16(v0[2], v0[3]); w.z = cvt_pk_bf16(v1[0], v1[1]); w.w = cvt_pk_bf16(v1[2], v1[3]);
;                 bf16_t* kp = KM + (size_t)row * 768 + h * 192;
;                 *(u32x4*)(kp + cw) = w;
;                 const f32x4 kr = *(const f32x4*)(KR + (size_t)row * 64 + wc * 16 + fq * 4) * rstd * gr; u32x2 r2; r2.x = cvt_pk_bf16(kr[0], kr[1]); r2.y = cvt_pk_bf16(kr[2], kr[3]);
;                 *(u32x2*)(kp + 128 + wc * 16 + fq * 4) = r2; }
	v_mov_b32_e32 v51, v52
	v_mov_b32_e32 v52, v49
	v_add_f32_e32 v48, v50, v52
	v_add_f32_e32 v49, v51, v53
	v_lshl_add_u64 v[50:51], v[56:57], 0, s[8:9]
	v_add_f32_e32 v48, v48, v58
	v_add_f32_e32 v48, v48, v49
	v_fmamk_f32 v48, v48, 0x3baaaaab, v174
	v_mul_f32_e32 v49, 0x4b800000, v48
	v_cmp_gt_f32_e32 vcc, s87, v48
	v_lshl_add_u64 v[52:53], v[50:51], 0, v[160:161]
	s_nop 0
	v_cndmask_b32_e32 v48, v48, v49, vcc
	v_rsq_f32_e32 v58, v48
	v_lshl_add_u64 v[48:49], v[162:163], 0, v[54:55]
	v_mul_f32_e32 v54, 0x45800000, v58
	v_cndmask_b32_e32 v54, v58, v54, vcc
	v_mul_f32_e32 v56, v112, v54
	v_mul_f32_e32 v40, v40, v56
	v_mul_f32_e32 v41, v41, v56
	v_mul_f32_e32 v42, v42, v56
	v_mul_f32_e32 v43, v43, v56
	v_mul_f32_e32 v44, v44, v56
	v_mul_f32_e32 v45, v45, v56
	v_mul_f32_e32 v46, v46, v56
	v_mul_f32_e32 v47, v47, v56
	v_mul_f32_e32 v56, v70, v42
	v_mul_f32_e32 v57, v71, v43
	v_mul_f32_e32 v42, v68, v40
	v_mul_f32_e32 v43, v69, v41
	v_mul_f32_e32 v46, v74, v46
	v_mul_f32_e32 v47, v75, v47
	v_mul_f32_e32 v44, v72, v44
	v_mul_f32_e32 v45, v73, v45
	s_nop 0
	v_cvt_pk_bf16_f32 v40, v44, v45
	v_cvt_pk_bf16_f32 v41, v46, v47
	v_cvt_pk_bf16_f32 v42, v42, v43
	v_cvt_pk_bf16_f32 v43, v56, v57
	global_store_dwordx4 v[52:53], v[40:43], off sc1
	global_load_dwordx4 v[40:43], v[48:49], off
	v_lshl_add_u64 v[46:47], v[50:51], 0, s[48:49]
	v_lshl_add_u64 v[46:47], v[46:47], 0, v[176:177]
	v_lshl_add_u64 v[44:45], v[186:187], 3, s[24:25]
	v_mad_i64_i32 v[48:49], s[0:1], v186, s88, v[78:79]
	s_waitcnt vmcnt(0)
	v_mul_f32_e32 v40, v40, v54
	v_mul_f32_e32 v41, v41, v54
	v_mul_f32_e32 v42, v42, v54
	v_mul_f32_e32 v43, v43, v54
	v_mul_f32_e32 v40, v64, v40
	v_mul_f32_e32 v41, v65, v41
	v_mul_f32_e32 v42, v66, v42
	v_mul_f32_e32 v43, v67, v43
	v_cvt_pk_bf16_f32 v40, v40, v41
	s_nop 0
	v_cvt_pk_bf16_f32 v41, v42, v43
	global_store_dwordx2 v[46:47], v[40:41], off offset:256
	global_load_dwordx2 v[44:45], v[44:45], off
	ds_read_b128 v[40:43], v200 offset:768
	v_lshlrev_b64 v[46:47], 8, v[186:187]
	s_waitcnt lgkmcnt(0)
	v_add_f32_e32 v50, v42, v43
	v_mov_b32_e32 v42, v40
	s_waitcnt vmcnt(0)
	v_mov_b32_e32 v43, v44
	v_mov_b32_e32 v44, v41
	v_add_f32_e32 v40, v42, v44
	v_add_f32_e32 v41, v43, v45
	v_lshl_add_u64 v[42:43], v[48:49], 0, s[8:9]
	v_add_f32_e32 v40, v40, v50
	v_add_f32_e32 v40, v40, v41
	v_fmamk_f32 v40, v40, 0x3baaaaab, v174
	v_mul_f32_e32 v41, 0x4b800000, v40
	v_cmp_gt_f32_e32 vcc, s87, v40
	v_lshl_add_u64 v[44:45], v[42:43], 0, v[160:161]
	s_nop 0
	v_cndmask_b32_e32 v40, v40, v41, vcc
	v_rsq_f32_e32 v50, v40
	v_lshl_add_u64 v[40:41], v[162:163], 0, v[46:47]
	v_mul_f32_e32 v46, 0x45800000, v50
	v_cndmask_b32_e32 v46, v50, v46, vcc
	v_mul_f32_e32 v48, v104, v46
	v_mul_f32_e32 v32, v32, v48
	v_mul_f32_e32 v33, v33, v48
	v_mul_f32_e32 v34, v34, v48
	v_mul_f32_e32 v35, v35, v48
	v_mul_f32_e32 v36, v36, v48
	v_mul_f32_e32 v37, v37, v48
	v_mul_f32_e32 v38, v38, v48
	v_mul_f32_e32 v39, v39, v48
	v_mul_f32_e32 v48, v70, v34
	v_mul_f32_e32 v49, v71, v35
	v_mul_f32_e32 v34, v68, v32
	v_mul_f32_e32 v35, v69, v33
	v_mul_f32_e32 v38, v74, v38
	v_mul_f32_e32 v39, v75, v39
	v_mul_f32_e32 v36, v72, v36
	v_mul_f32_e32 v37, v73, v37
	s_nop 0
	v_cvt_pk_bf16_f32 v32, v36, v37
	v_cvt_pk_bf16_f32 v33, v38, v39
	v_cvt_pk_bf16_f32 v34, v34, v35
	v_cvt_pk_bf16_f32 v35, v48, v49
	global_store_dwordx4 v[44:45], v[32:35], off sc1
	global_load_dwordx4 v[32:35], v[40:41], off
	v_lshl_add_u64 v[38:39], v[42:43], 0, s[48:49]
	v_lshl_add_u64 v[38:39], v[38:39], 0, v[176:177]
	v_lshl_add_u64 v[36:37], v[184:185], 3, s[24:25]
	v_mad_i64_i32 v[40:41], s[0:1], v184, s88, v[78:79]
	s_waitcnt vmcnt(0)
	v_mul_f32_e32 v32, v32, v46
	v_mul_f32_e32 v33, v33, v46
	v_mul_f32_e32 v34, v34, v46
	v_mul_f32_e32 v35, v35, v46
	v_mul_f32_e32 v32, v64, v32
	v_mul_f32_e32 v33, v65, v33
	v_mul_f32_e32 v34, v66, v34
	v_mul_f32_e32 v35, v67, v35
	v_cvt_pk_bf16_f32 v32, v32, v33
	s_nop 0
	v_cvt_pk_bf16_f32 v33, v34, v35
	global_store_dwordx2 v[38:39], v[32:33], off offset:256
	global_load_dwordx2 v[36:37], v[36:37], off
	ds_read_b128 v[32:35], v200 offset:2048
	v_lshlrev_b64 v[38:39], 8, v[184:185]
	s_waitcnt lgkmcnt(0)
	v_add_f32_e32 v42, v34, v35
	v_mov_b32_e32 v34, v32
	s_waitcnt vmcnt(0)
	v_mov_b32_e32 v35, v36
	v_mov_b32_e32 v36, v33
	v_add_f32_e32 v32, v34, v36
	v_add_f32_e32 v33, v35, v37
	v_lshl_add_u64 v[34:35], v[40:41], 0, s[8:9]
	v_add_f32_e32 v32, v32, v42
	v_add_f32_e32 v32, v32, v33
	v_fmamk_f32 v32, v32, 0x3baaaaab, v174
	v_mul_f32_e32 v33, 0x4b800000, v32
	v_cmp_gt_f32_e32 vcc, s87, v32
	v_lshl_add_u64 v[36:37], v[34:35], 0, v[160:161]
	s_nop 0
	v_cndmask_b32_e32 v32, v32, v33, vcc
	v_rsq_f32_e32 v42, v32
	v_lshl_add_u64 v[32:33], v[162:163], 0, v[38:39]
	v_mul_f32_e32 v38, 0x45800000, v42
	v_cndmask_b32_e32 v38, v42, v38, vcc
	v_mul_f32_e32 v40, v96, v38
	v_mul_f32_e32 v24, v24, v40
	v_mul_f32_e32 v25, v25, v40
	v_mul_f32_e32 v26, v26, v40
	v_mul_f32_e32 v27, v27, v40
	v_mul_f32_e32 v28, v28, v40
	v_mul_f32_e32 v29, v29, v40
	v_mul_f32_e32 v30, v30, v40
	v_mul_f32_e32 v31, v31, v40
	v_mul_f32_e32 v40, v70, v26
	v_mul_f32_e32 v41, v71, v27
	v_mul_f32_e32 v26, v68, v24
	v_mul_f32_e32 v27, v69, v25
	v_mul_f32_e32 v30, v74, v30
	v_mul_f32_e32 v31, v75, v31
	v_mul_f32_e32 v28, v72, v28
	v_mul_f32_e32 v29, v73, v29
	s_nop 0
	v_cvt_pk_bf16_f32 v24, v28, v29
	v_cvt_pk_bf16_f32 v25, v30, v31
	v_cvt_pk_bf16_f32 v26, v26, v27
	v_cvt_pk_bf16_f32 v27, v40, v41
	global_store_dwordx4 v[36:37], v[24:27], off sc1
	global_load_dwordx4 v[24:27], v[32:33], off
	v_lshl_add_u64 v[30:31], v[34:35], 0, s[48:49]
	v_lshl_add_u64 v[30:31], v[30:31], 0, v[176:177]
	v_lshl_add_u64 v[28:29], v[182:183], 3, s[24:25]
	v_mad_i64_i32 v[32:33], s[0:1], v182, s88, v[78:79]
	s_waitcnt vmcnt(0)
; #define LAS __attribute__((address_space(3)))
; __device__ __forceinline__ unsigned cvt_pk_bf16(float lo, float hi) { unsigned r; asm volatile("v_cvt_pk_bf16_f32 %0, %1, %2" : "=v"(r) : "v"(lo), "v"(hi)); return r; }
;     DI void operator()(const f32x4 (&acc)[2][2][4][2], const Unit& u, int wr, int wc, int fr, int fq) const {
;     ...
;             for (int m = 0; m < 4; ++m) { const int row = row0 + ai * 128 + m * 16; const f32x4 pp = *(const LAS f32x4*)(part + (ai * 128 + wr * 64 + m * 16 + fr) * 4);
;                 const f32x2_ kr2 = *(const f32x2_*)(sskr2 + (size_t)row * 2);
;                 const float rstd = rsqrtf((((pp[0] + pp[1]) + (pp[2] + pp[3])) + (kr2[0] + kr2[1])) * (1.f / 192.f) + EPS), s = rs[ai][m] * rstd;
;                 const f32x4 v0 = acc[ai][0][m][0] * s * g0, v1 = acc[ai][0][m][1] * s * g1; u32x4 w;
;                 w.x = cvt_pk_bf16(v0[0], v0[1]); w.y = cvt_pk_bf16(v0[2], v0[3]); w.z = cvt_pk_bf16(v1[0], v1[1]); w.w = cvt_pk_bf16(v1[2], v1[3]);
;                 bf16_t* kp = KM + (size_t)row * 768 + h * 192;
;                 *(u32x4*)(kp + cw) = w;
;                 const f32x4 kr = *(const f32x4*)(KR + (size_t)row * 64 + wc * 16 + fq * 4) * rstd * gr; u32x2 r2; r2.x = cvt_pk_bf16(kr[0], kr[1]); r2.y = cvt_pk_bf16(kr[2], kr[3]);
;                 *(u32x2*)(kp + 128 + wc * 16 + fq * 4) = r2; }
	v_mul_f32_e32 v24, v24, v38
	v_mul_f32_e32 v25, v25, v38
	v_mul_f32_e32 v26, v26, v38
	v_mul_f32_e32 v27, v27, v38
	v_mul_f32_e32 v24, v64, v24
	v_mul_f32_e32 v25, v65, v25
	v_mul_f32_e32 v26, v66, v26
	v_mul_f32_e32 v27, v67, v27
	v_cvt_pk_bf16_f32 v24, v24, v25
	s_nop 0
	v_cvt_pk_bf16_f32 v25, v26, v27
	global_store_dwordx2 v[30:31], v[24:25], off offset:256
	global_load_dwordx2 v[28:29], v[28:29], off
	ds_read_b128 v[24:27], v200 offset:2304
	v_lshlrev_b64 v[30:31], 8, v[182:183]
	s_waitcnt lgkmcnt(0)
	v_add_f32_e32 v34, v26, v27
	v_mov_b32_e32 v26, v24
	s_waitcnt vmcnt(0)
	v_mov_b32_e32 v27, v28
	v_mov_b32_e32 v28, v25
	v_add_f32_e32 v24, v26, v28
	v_add_f32_e32 v25, v27, v29
	v_lshl_add_u64 v[26:27], v[32:33], 0, s[8:9]
	v_add_f32_e32 v24, v24, v34
	v_add_f32_e32 v24, v24, v25
	v_fmamk_f32 v24, v24, 0x3baaaaab, v174
	v_mul_f32_e32 v25, 0x4b800000, v24
	v_cmp_gt_f32_e32 vcc, s87, v24
	v_lshl_add_u64 v[28:29], v[26:27], 0, v[160:161]
	s_nop 0
	v_cndmask_b32_e32 v24, v24, v25, vcc
	v_rsq_f32_e32 v34, v24
	v_lshl_add_u64 v[24:25], v[162:163], 0, v[30:31]
	v_mul_f32_e32 v30, 0x45800000, v34
	v_cndmask_b32_e32 v30, v34, v30, vcc
	v_mul_f32_e32 v32, v88, v30
	v_mul_f32_e32 v16, v16, v32
	v_mul_f32_e32 v17, v17, v32
	v_mul_f32_e32 v18, v18, v32
	v_mul_f32_e32 v19, v19, v32
	v_mul_f32_e32 v20, v20, v32
	v_mul_f32_e32 v21, v21, v32
	v_mul_f32_e32 v22, v22, v32
	v_mul_f32_e32 v23, v23, v32
	v_mul_f32_e32 v32, v70, v18
	v_mul_f32_e32 v33, v71, v19
	v_mul_f32_e32 v18, v68, v16
	v_mul_f32_e32 v19, v69, v17
	v_mul_f32_e32 v22, v74, v22
	v_mul_f32_e32 v23, v75, v23
	v_mul_f32_e32 v20, v72, v20
	v_mul_f32_e32 v21, v73, v21
	s_nop 0
	v_cvt_pk_bf16_f32 v16, v20, v21
	v_cvt_pk_bf16_f32 v17, v22, v23
	v_cvt_pk_bf16_f32 v18, v18, v19
	v_cvt_pk_bf16_f32 v19, v32, v33
	global_store_dwordx4 v[28:29], v[16:19], off sc1
	global_load_dwordx4 v[16:19], v[24:25], off
	v_lshl_add_u64 v[22:23], v[26:27], 0, s[48:49]
	v_lshl_add_u64 v[22:23], v[22:23], 0, v[176:177]
	v_lshl_add_u64 v[20:21], v[180:181], 3, s[24:25]
	v_mad_i64_i32 v[24:25], s[0:1], v180, s88, v[78:79]
	s_waitcnt vmcnt(0)
	v_mul_f32_e32 v16, v16, v30
	v_mul_f32_e32 v17, v17, v30
	v_mul_f32_e32 v18, v18, v30
	v_mul_f32_e32 v19, v19, v30
	v_mul_f32_e32 v16, v64, v16
	v_mul_f32_e32 v17, v65, v17
	v_mul_f32_e32 v18, v66, v18
	v_mul_f32_e32 v19, v67, v19
	v_cvt_pk_bf16_f32 v16, v16, v17
	s_nop 0
	v_cvt_pk_bf16_f32 v17, v18, v19
	global_store_dwordx2 v[22:23], v[16:17], off offset:256
	global_load_dwordx2 v[20:21], v[20:21], off
	ds_read_b128 v[16:19], v200 offset:2560
	v_lshlrev_b64 v[22:23], 8, v[180:181]
	s_waitcnt lgkmcnt(0)
	v_add_f32_e32 v26, v18, v19
	v_mov_b32_e32 v18, v16
	s_waitcnt vmcnt(0)
	v_mov_b32_e32 v19, v20
	v_mov_b32_e32 v20, v17
	v_add_f32_e32 v16, v18, v20
	v_add_f32_e32 v17, v19, v21
	v_lshl_add_u64 v[18:19], v[24:25], 0, s[8:9]
	v_add_f32_e32 v16, v16, v26
	v_add_f32_e32 v16, v16, v17
	v_fmamk_f32 v16, v16, 0x3baaaaab, v174
	v_mul_f32_e32 v17, 0x4b800000, v16
	v_cmp_gt_f32_e32 vcc, s87, v16
	v_lshl_add_u64 v[20:21], v[18:19], 0, v[160:161]
	s_nop 0
	v_cndmask_b32_e32 v16, v16, v17, vcc
	v_rsq_f32_e32 v26, v16
	v_lshl_add_u64 v[16:17], v[162:163], 0, v[22:23]
	v_mul_f32_e32 v22, 0x45800000, v26
	v_cndmask_b32_e32 v22, v26, v22, vcc
	v_mul_f32_e32 v24, v80, v22
	v_mul_f32_e32 v8, v8, v24
	v_mul_f32_e32 v9, v9, v24
	v_mul_f32_e32 v10, v10, v24
	v_mul_f32_e32 v11, v11, v24
	v_mul_f32_e32 v12, v12, v24
	v_mul_f32_e32 v13, v13, v24
	v_mul_f32_e32 v14, v14, v24
	v_mul_f32_e32 v15, v15, v24
	v_mul_f32_e32 v24, v70, v10
	v_mul_f32_e32 v25, v71, v11
	v_mul_f32_e32 v10, v68, v8
	v_mul_f32_e32 v11, v69, v9
	v_mul_f32_e32 v14, v74, v14
	v_mul_f32_e32 v15, v75, v15
	v_mul_f32_e32 v12, v72, v12
	v_mul_f32_e32 v13, v73, v13
	s_nop 0
	v_cvt_pk_bf16_f32 v8, v12, v13
	v_cvt_pk_bf16_f32 v9, v14, v15
	v_cvt_pk_bf16_f32 v10, v10, v11
	v_cvt_pk_bf16_f32 v11, v24, v25
	global_store_dwordx4 v[20:21], v[8:11], off sc1
	global_load_dwordx4 v[8:11], v[16:17], off
	v_lshl_add_u64 v[14:15], v[18:19], 0, s[48:49]
	v_lshl_add_u64 v[14:15], v[14:15], 0, v[176:177]
	v_lshl_add_u64 v[12:13], v[178:179], 3, s[24:25]
	v_mad_i64_i32 v[16:17], s[0:1], v178, s88, v[78:79]
	s_waitcnt vmcnt(0)
	v_mul_f32_e32 v8, v8, v22
	v_mul_f32_e32 v9, v9, v22
	v_mul_f32_e32 v10, v10, v22
	v_mul_f32_e32 v11, v11, v22
	v_mul_f32_e32 v8, v64, v8
	v_mul_f32_e32 v9, v65, v9
	v_mul_f32_e32 v10, v66, v10
	v_mul_f32_e32 v11, v67, v11
	v_cvt_pk_bf16_f32 v8, v8, v9
	s_nop 0
	v_cvt_pk_bf16_f32 v9, v10, v11
	global_store_dwordx2 v[14:15], v[8:9], off offset:256
	global_load_dwordx2 v[12:13], v[12:13], off
	ds_read_b128 v[8:11], v200 offset:2816
	v_lshlrev_b64 v[14:15], 8, v[178:179]
	s_waitcnt lgkmcnt(0)
	v_add_f32_e32 v18, v10, v11
	v_mov_b32_e32 v10, v8
	s_waitcnt vmcnt(0)
	v_mov_b32_e32 v11, v12
	v_mov_b32_e32 v12, v9
	v_add_f32_e32 v8, v10, v12
	v_add_f32_e32 v9, v11, v13
	v_lshl_add_u64 v[10:11], v[16:17], 0, s[8:9]
	v_add_f32_e32 v8, v8, v18
	v_add_f32_e32 v8, v8, v9
	v_fmamk_f32 v8, v8, 0x3baaaaab, v174
	v_mul_f32_e32 v9, 0x4b800000, v8
	v_cmp_gt_f32_e32 vcc, s87, v8
	v_lshl_add_u64 v[12:13], v[10:11], 0, v[160:161]
	s_nop 0
	v_cndmask_b32_e32 v8, v8, v9, vcc
	v_rsq_f32_e32 v18, v8
	v_lshl_add_u64 v[8:9], v[162:163], 0, v[14:15]
	v_mul_f32_e32 v14, 0x45800000, v18
	v_cndmask_b32_e32 v14, v18, v14, vcc
	v_mul_f32_e32 v16, v76, v14
	v_mul_f32_e32 v0, v0, v16
	v_mul_f32_e32 v1, v1, v16
	v_mul_f32_e32 v2, v2, v16
	v_mul_f32_e32 v3, v3, v16
	v_mul_f32_e32 v4, v4, v16
	v_mul_f32_e32 v5, v5, v16
	v_mul_f32_e32 v6, v6, v16
	v_mul_f32_e32 v7, v7, v16
	v_mul_f32_e32 v16, v70, v2
	v_mul_f32_e32 v17, v71, v3
	v_mul_f32_e32 v2, v68, v0
	v_mul_f32_e32 v3, v69, v1
	v_mul_f32_e32 v6, v74, v6
	v_mul_f32_e32 v7, v75, v7
	v_mul_f32_e32 v4, v72, v4
	v_mul_f32_e32 v5, v73, v5
	s_and_b64 vcc, exec, s[6:7]
	v_cvt_pk_bf16_f32 v0, v4, v5
	v_cvt_pk_bf16_f32 v1, v6, v7
	v_cvt_pk_bf16_f32 v2, v2, v3
	v_cvt_pk_bf16_f32 v3, v16, v17
	global_store_dwordx4 v[12:13], v[0:3], off sc1
	global_load_dwordx4 v[0:3], v[8:9], off
	v_lshl_add_u64 v[4:5], v[10:11], 0, s[48:49]
	v_lshl_add_u64 v[4:5], v[4:5], 0, v[176:177]
	s_mov_b64 s[6:7], -1
	s_waitcnt vmcnt(0)
	v_mul_f32_e32 v0, v0, v14
	v_mul_f32_e32 v1, v1, v14
	v_mul_f32_e32 v2, v2, v14
	v_mul_f32_e32 v3, v3, v14
	v_mul_f32_e32 v0, v64, v0
	v_mul_f32_e32 v1, v65, v1
	v_mul_f32_e32 v2, v66, v2
	v_mul_f32_e32 v3, v67, v3
	v_cvt_pk_bf16_f32 v0, v0, v1
	s_nop 0
	v_cvt_pk_bf16_f32 v1, v2, v3
	global_store_dwordx2 v[4:5], v[0:1], off offset:256
	s_cbranch_vccnz .LBB0_1865
	s_andn2_b64 vcc, exec, s[52:53]
	s_cbranch_vccnz .LBB0_1864
	s_barrier
	s_branch .LBB0_1864

; __device__ __forceinline__ unsigned cvt_pk_bf16(float lo, float hi) { unsigned r; asm volatile("v_cvt_pk_bf16_f32 %0, %1, %2" : "=v"(r) : "v"(lo), "v"(hi)); return r; }
; DI float shx(float v, int mask, int lane) { return __int_as_float(__builtin_amdgcn_ds_bpermute((lane ^ mask) << 2, __float_as_int(v))); }
;     DI void operator()(const f32x4 (&acc)[2][2][4][2], const Unit& u, int wr, int wc, int fr, int fq) const {
;     ...
;             for (int m = 0; m < 4; ++m) { const int row = row0 + ai * 128 + m * 16; const size_t off = (size_t)row * 1024 + col0; float ss = 0.f;
; #pragma unroll
;                 for (int bj = 0; bj < 2; ++bj) { const size_t o = off + bj * 128; const u32x4 r_ = *(const u32x4*)(x1b + o); f32x4 v0, v1;
;                     v0[0] = __uint_as_float(r_.x << 16); v0[1] = __uint_as_float(r_.x & 0xffff0000u); v0[2] = __uint_as_float(r_.y << 16); v0[3] = __uint_as_float(r_.y & 0xffff0000u);
;                     v1[0] = __uint_as_float(r_.z << 16); v1[1] = __uint_as_float(r_.z & 0xffff0000u); v1[2] = __uint_as_float(r_.w << 16); v1[3] = __uint_as_float(r_.w & 0xffff0000u);
;                     v0 = v0 + acc[ai][bj][m][0]; v1 = v1 + acc[ai][bj][m][1];
;                     ss += ((v0[0] * v0[0] + v0[1] * v0[1]) + (v0[2] * v0[2] + v0[3] * v0[3])) + ((v1[0] * v1[0] + v1[1] * v1[1]) + (v1[2] * v1[2] + v1[3] * v1[3]));
;                     u32x4 w; w.x = cvt_pk_bf16(v0[0], v0[1]); w.y = cvt_pk_bf16(v0[2], v0[3]); w.z = cvt_pk_bf16(v1[0], v1[1]); w.w = cvt_pk_bf16(v1[2], v1[3]); *(u32x4*)(x1b + o) = w; }
;                 { const int ln_ = fq * 16 + fr; ss += shx(ss, 16, ln_); ss += shx(ss, 32, ln_); }
;                 if (fq == 0) unsafeAtomicAdd(ssum2 + row, ss); }
.LBB0_2019:
	v_lshl_add_u32 v146, s28, 8, v148
	v_ashrrev_i32_e32 v147, 31, v146
	v_lshl_or_b32 v144, s36, 8, v152
	v_lshlrev_b64 v[156:157], 11, v[146:147]
	v_ashrrev_i32_e32 v145, 31, v144
	v_lshl_add_u64 v[156:157], s[34:35], 0, v[156:157]
	v_lshl_add_u64 v[160:161], v[144:145], 1, v[156:157]
	global_load_dwordx4 v[156:159], v[160:161], off
	s_waitcnt vmcnt(0)
	v_lshlrev_b32_e32 v162, 16, v156
	v_and_b32_e32 v163, 0xffff0000, v156
	v_lshlrev_b32_e32 v156, 16, v157
	v_and_b32_e32 v157, 0xffff0000, v157
	v_lshlrev_b32_e32 v164, 16, v158
	v_and_b32_e32 v165, 0xffff0000, v158
	v_lshlrev_b32_e32 v158, 16, v159
	v_and_b32_e32 v159, 0xffff0000, v159
	v_add_f32_e32 v156, v126, v156
	v_add_f32_e32 v157, v127, v157
	v_add_f32_e32 v162, v124, v162
	v_add_f32_e32 v163, v125, v163
	v_add_f32_e32 v158, v122, v158
	v_add_f32_e32 v159, v123, v159
	v_add_f32_e32 v164, v120, v164
	v_add_f32_e32 v165, v121, v165
	v_cvt_pk_bf16_f32 v120, v162, v163
	v_cvt_pk_bf16_f32 v121, v156, v157
	v_mul_f32_e32 v163, v163, v163
	v_cvt_pk_bf16_f32 v122, v164, v165
	v_cvt_pk_bf16_f32 v123, v158, v159
	global_load_dwordx4 v[124:127], v[160:161], off offset:256
	v_mul_f32_e32 v157, v157, v157
	v_mul_f32_e32 v165, v165, v165
	v_mul_f32_e32 v159, v159, v159
	v_fmac_f32_e32 v163, v162, v162
	v_fmac_f32_e32 v157, v156, v156
	v_fmac_f32_e32 v165, v164, v164
	v_fmac_f32_e32 v159, v158, v158
	v_add_f32_e32 v156, v163, v157
	v_add_f32_e32 v157, v165, v159
	v_add_f32_e32 v162, v156, v157
	global_store_dwordx4 v[160:161], v[120:123], off sc1
	s_waitcnt vmcnt(1)
	v_lshlrev_b32_e32 v156, 16, v124
	v_and_b32_e32 v157, 0xffff0000, v124
	v_lshlrev_b32_e32 v124, 16, v125
	v_and_b32_e32 v125, 0xffff0000, v125
	v_lshlrev_b32_e32 v158, 16, v126
	v_and_b32_e32 v159, 0xffff0000, v126
	v_lshlrev_b32_e32 v126, 16, v127
	v_and_b32_e32 v127, 0xffff0000, v127
	v_add_f32_e32 v118, v118, v124
	v_add_f32_e32 v119, v119, v125
	v_add_f32_e32 v116, v116, v156
	v_add_f32_e32 v117, v117, v157
	v_add_f32_e32 v124, v114, v126
	v_add_f32_e32 v125, v115, v127
	v_add_f32_e32 v126, v112, v158
	v_add_f32_e32 v127, v113, v159
	v_mul_f32_e32 v112, v117, v117
	v_mul_f32_e32 v113, v119, v119
	v_mul_f32_e32 v114, v127, v127
	v_mul_f32_e32 v115, v125, v125
	v_fmac_f32_e32 v112, v116, v116
	v_fmac_f32_e32 v113, v118, v118
	v_fmac_f32_e32 v114, v126, v126
	v_fmac_f32_e32 v115, v124, v124
	v_add_f32_e32 v112, v112, v113
	v_add_f32_e32 v113, v114, v115
	v_add_f32_e32 v112, v112, v113
	v_add_f32_e32 v112, v162, v112
	ds_bpermute_b32 v113, v150, v112
	v_cvt_pk_bf16_f32 v114, v116, v117
	v_cvt_pk_bf16_f32 v115, v118, v119
	v_cvt_pk_bf16_f32 v116, v126, v127
	v_cvt_pk_bf16_f32 v117, v124, v125
	s_waitcnt lgkmcnt(0)
	v_add_f32_e32 v112, v112, v113
	ds_bpermute_b32 v113, v151, v112
	global_store_dwordx4 v[160:161], v[114:117], off offset:256 sc1
	s_and_saveexec_b64 s[28:29], s[4:5]
	s_cbranch_execz .LBB0_2021
	s_waitcnt lgkmcnt(0)
	v_add_f32_e32 v114, v112, v113
	v_lshl_add_u64 v[112:113], v[146:147], 2, s[16:17]
	global_atomic_add_f32 v[112:113], v114, off
.LBB0_2021:
	s_or_b64 exec, exec, s[28:29]
	v_or_b32_e32 v112, 16, v146
	s_waitcnt lgkmcnt(0)
	v_ashrrev_i32_e32 v113, 31, v112
	v_lshlrev_b64 v[114:115], 11, v[112:113]
	v_lshl_add_u64 v[114:115], s[34:35], 0, v[114:115]
	v_lshl_add_u64 v[118:119], v[144:145], 1, v[114:115]
	global_load_dwordx4 v[114:117], v[118:119], off
	s_waitcnt vmcnt(0)
	v_lshlrev_b32_e32 v120, 16, v114
	v_and_b32_e32 v121, 0xffff0000, v114
	v_lshlrev_b32_e32 v114, 16, v115
	v_and_b32_e32 v115, 0xffff0000, v115
	v_lshlrev_b32_e32 v122, 16, v116
	v_and_b32_e32 v123, 0xffff0000, v116
	v_lshlrev_b32_e32 v116, 16, v117
	v_and_b32_e32 v117, 0xffff0000, v117
	v_add_f32_e32 v114, v110, v114
	v_add_f32_e32 v115, v111, v115
	v_add_f32_e32 v120, v108, v120
	v_add_f32_e32 v121, v109, v121
	v_add_f32_e32 v116, v106, v116
	v_add_f32_e32 v117, v107, v117
	v_add_f32_e32 v122, v104, v122
	v_add_f32_e32 v123, v105, v123
	v_cvt_pk_bf16_f32 v104, v120, v121
	v_cvt_pk_bf16_f32 v105, v114, v115
	v_mul_f32_e32 v121, v121, v121
	v_cvt_pk_bf16_f32 v106, v122, v123
	v_cvt_pk_bf16_f32 v107, v116, v117
	global_load_dwordx4 v[108:111], v[118:119], off offset:256
	v_mul_f32_e32 v115, v115, v115
	v_mul_f32_e32 v123, v123, v123
	v_mul_f32_e32 v117, v117, v117
	v_fmac_f32_e32 v121, v120, v120
	v_fmac_f32_e32 v115, v114, v114
	v_fmac_f32_e32 v123, v122, v122
	v_fmac_f32_e32 v117, v116, v116
	v_add_f32_e32 v114, v121, v115
	v_add_f32_e32 v115, v123, v117
	v_add_f32_e32 v120, v114, v115
	global_store_dwordx4 v[118:119], v[104:107], off sc1
	s_waitcnt vmcnt(1)
	v_lshlrev_b32_e32 v114, 16, v108
	v_and_b32_e32 v115, 0xffff0000, v108
	v_lshlrev_b32_e32 v108, 16, v109
	v_and_b32_e32 v109, 0xffff0000, v109
	v_lshlrev_b32_e32 v116, 16, v110
	v_and_b32_e32 v117, 0xffff0000, v110
	v_lshlrev_b32_e32 v110, 16, v111
	v_and_b32_e32 v111, 0xffff0000, v111
	v_add_f32_e32 v102, v102, v108
	v_add_f32_e32 v103, v103, v109
	v_add_f32_e32 v100, v100, v114
	v_add_f32_e32 v101, v101, v115
	v_add_f32_e32 v108, v98, v110
	v_add_f32_e32 v109, v99, v111
	v_add_f32_e32 v110, v96, v116
	v_add_f32_e32 v111, v97, v117
	v_mul_f32_e32 v96, v101, v101
	v_mul_f32_e32 v97, v103, v103
	v_mul_f32_e32 v98, v111, v111
	v_mul_f32_e32 v99, v109, v109
	v_fmac_f32_e32 v96, v100, v100
	v_fmac_f32_e32 v97, v102, v102
	v_fmac_f32_e32 v98, v110, v110
	v_fmac_f32_e32 v99, v108, v108
	v_add_f32_e32 v96, v96, v97
	v_add_f32_e32 v97, v98, v99
	v_add_f32_e32 v96, v96, v97
	v_add_f32_e32 v96, v120, v96
	ds_bpermute_b32 v97, v150, v96
	v_cvt_pk_bf16_f32 v98, v100, v101
	v_cvt_pk_bf16_f32 v99, v102, v103
	v_cvt_pk_bf16_f32 v100, v110, v111
	v_cvt_pk_bf16_f32 v101, v108, v109
	s_waitcnt lgkmcnt(0)
	v_add_f32_e32 v96, v96, v97
	ds_bpermute_b32 v97, v151, v96
	global_store_dwordx4 v[118:119], v[98:101], off offset:256 sc1
	s_and_saveexec_b64 s[28:29], s[4:5]
	s_cbranch_execz .LBB0_2023
	s_waitcnt lgkmcnt(0)
	v_add_f32_e32 v98, v96, v97
	v_lshl_add_u64 v[96:97], v[112:113], 2, s[16:17]
	global_atomic_add_f32 v[96:97], v98, off
; __device__ __forceinline__ unsigned cvt_pk_bf16(float lo, float hi) { unsigned r; asm volatile("v_cvt_pk_bf16_f32 %0, %1, %2" : "=v"(r) : "v"(lo), "v"(hi)); return r; }
; DI float shx(float v, int mask, int lane) { return __int_as_float(__builtin_amdgcn_ds_bpermute((lane ^ mask) << 2, __float_as_int(v))); }
;     DI void operator()(const f32x4 (&acc)[2][2][4][2], const Unit& u, int wr, int wc, int fr, int fq) const {
;     ...
;             for (int m = 0; m < 4; ++m) { const int row = row0 + ai * 128 + m * 16; const size_t off = (size_t)row * 1024 + col0; float ss = 0.f;
; #pragma unroll
;                 for (int bj = 0; bj < 2; ++bj) { const size_t o = off + bj * 128; const u32x4 r_ = *(const u32x4*)(x1b + o); f32x4 v0, v1;
;                     v0[0] = __uint_as_float(r_.x << 16); v0[1] = __uint_as_float(r_.x & 0xffff0000u); v0[2] = __uint_as_float(r_.y << 16); v0[3] = __uint_as_float(r_.y & 0xffff0000u);
;                     v1[0] = __uint_as_float(r_.z << 16); v1[1] = __uint_as_float(r_.z & 0xffff0000u); v1[2] = __uint_as_float(r_.w << 16); v1[3] = __uint_as_float(r_.w & 0xffff0000u);
;                     v0 = v0 + acc[ai][bj][m][0]; v1 = v1 + acc[ai][bj][m][1];
;                     ss += ((v0[0] * v0[0] + v0[1] * v0[1]) + (v0[2] * v0[2] + v0[3] * v0[3])) + ((v1[0] * v1[0] + v1[1] * v1[1]) + (v1[2] * v1[2] + v1[3] * v1[3]));
;                     u32x4 w; w.x = cvt_pk_bf16(v0[0], v0[1]); w.y = cvt_pk_bf16(v0[2], v0[3]); w.z = cvt_pk_bf16(v1[0], v1[1]); w.w = cvt_pk_bf16(v1[2], v1[3]); *(u32x4*)(x1b + o) = w; }
;                 { const int ln_ = fq * 16 + fr; ss += shx(ss, 16, ln_); ss += shx(ss, 32, ln_); }
;                 if (fq == 0) unsafeAtomicAdd(ssum2 + row, ss); }
.LBB0_2023:
	s_or_b64 exec, exec, s[28:29]
	v_or_b32_e32 v96, 32, v146
	s_waitcnt lgkmcnt(0)
	v_ashrrev_i32_e32 v97, 31, v96
	v_lshlrev_b64 v[98:99], 11, v[96:97]
	v_lshl_add_u64 v[98:99], s[34:35], 0, v[98:99]
	v_lshl_add_u64 v[102:103], v[144:145], 1, v[98:99]
	global_load_dwordx4 v[98:101], v[102:103], off
	s_waitcnt vmcnt(0)
	v_lshlrev_b32_e32 v104, 16, v98
	v_and_b32_e32 v105, 0xffff0000, v98
	v_lshlrev_b32_e32 v98, 16, v99
	v_and_b32_e32 v99, 0xffff0000, v99
	v_lshlrev_b32_e32 v106, 16, v100
	v_and_b32_e32 v107, 0xffff0000, v100
	v_lshlrev_b32_e32 v100, 16, v101
	v_and_b32_e32 v101, 0xffff0000, v101
	v_add_f32_e32 v98, v94, v98
	v_add_f32_e32 v99, v95, v99
	v_add_f32_e32 v104, v92, v104
	v_add_f32_e32 v105, v93, v105
	v_add_f32_e32 v100, v90, v100
	v_add_f32_e32 v101, v91, v101
	v_add_f32_e32 v106, v88, v106
	v_add_f32_e32 v107, v89, v107
	v_cvt_pk_bf16_f32 v88, v104, v105
	v_cvt_pk_bf16_f32 v89, v98, v99
	v_mul_f32_e32 v105, v105, v105
	v_cvt_pk_bf16_f32 v90, v106, v107
	v_cvt_pk_bf16_f32 v91, v100, v101
	global_load_dwordx4 v[92:95], v[102:103], off offset:256
	v_mul_f32_e32 v99, v99, v99
	v_mul_f32_e32 v107, v107, v107
	v_mul_f32_e32 v101, v101, v101
	v_fmac_f32_e32 v105, v104, v104
	v_fmac_f32_e32 v99, v98, v98
	v_fmac_f32_e32 v107, v106, v106
	v_fmac_f32_e32 v101, v100, v100
	v_add_f32_e32 v98, v105, v99
	v_add_f32_e32 v99, v107, v101
	v_add_f32_e32 v104, v98, v99
	global_store_dwordx4 v[102:103], v[88:91], off sc1
	s_waitcnt vmcnt(1)
	v_lshlrev_b32_e32 v98, 16, v92
	v_and_b32_e32 v99, 0xffff0000, v92
	v_lshlrev_b32_e32 v92, 16, v93
	v_and_b32_e32 v93, 0xffff0000, v93
	v_lshlrev_b32_e32 v100, 16, v94
	v_and_b32_e32 v101, 0xffff0000, v94
	v_lshlrev_b32_e32 v94, 16, v95
	v_and_b32_e32 v95, 0xffff0000, v95
	v_add_f32_e32 v86, v86, v92
	v_add_f32_e32 v87, v87, v93
	v_add_f32_e32 v84, v84, v98
	v_add_f32_e32 v85, v85, v99
	v_add_f32_e32 v92, v82, v94
	v_add_f32_e32 v93, v83, v95
	v_add_f32_e32 v94, v80, v100
	v_add_f32_e32 v95, v81, v101
	v_mul_f32_e32 v80, v85, v85
	v_mul_f32_e32 v81, v87, v87
	v_mul_f32_e32 v82, v95, v95
	v_mul_f32_e32 v83, v93, v93
	v_fmac_f32_e32 v80, v84, v84
	v_fmac_f32_e32 v81, v86, v86
	v_fmac_f32_e32 v82, v94, v94
	v_fmac_f32_e32 v83, v92, v92
	v_add_f32_e32 v80, v80, v81
	v_add_f32_e32 v81, v82, v83
	v_add_f32_e32 v80, v80, v81
	v_add_f32_e32 v80, v104, v80
	ds_bpermute_b32 v81, v150, v80
	v_cvt_pk_bf16_f32 v82, v84, v85
	v_cvt_pk_bf16_f32 v83, v86, v87
	v_cvt_pk_bf16_f32 v84, v94, v95
	v_cvt_pk_bf16_f32 v85, v92, v93
	s_waitcnt lgkmcnt(0)
	v_add_f32_e32 v80, v80, v81
	ds_bpermute_b32 v81, v151, v80
	global_store_dwordx4 v[102:103], v[82:85], off offset:256 sc1
	s_and_saveexec_b64 s[28:29], s[4:5]
	s_cbranch_execz .LBB0_2025
	s_waitcnt lgkmcnt(0)
	v_add_f32_e32 v82, v80, v81
	v_lshl_add_u64 v[80:81], v[96:97], 2, s[16:17]
	global_atomic_add_f32 v[80:81], v82, off
.LBB0_2025:
	s_or_b64 exec, exec, s[28:29]
	v_or_b32_e32 v80, 48, v146
	s_waitcnt lgkmcnt(0)
	v_ashrrev_i32_e32 v81, 31, v80
	v_lshlrev_b64 v[82:83], 11, v[80:81]
	v_lshl_add_u64 v[82:83], s[34:35], 0, v[82:83]
	v_lshl_add_u64 v[86:87], v[144:145], 1, v[82:83]
	global_load_dwordx4 v[82:85], v[86:87], off
	s_waitcnt vmcnt(0)
	v_lshlrev_b32_e32 v88, 16, v82
	v_and_b32_e32 v89, 0xffff0000, v82
	v_lshlrev_b32_e32 v82, 16, v83
	v_and_b32_e32 v83, 0xffff0000, v83
	v_lshlrev_b32_e32 v90, 16, v84
	v_and_b32_e32 v91, 0xffff0000, v84
	v_lshlrev_b32_e32 v84, 16, v85
	v_and_b32_e32 v85, 0xffff0000, v85
	v_add_f32_e32 v82, v78, v82
	v_add_f32_e32 v83, v79, v83
	v_add_f32_e32 v88, v76, v88
	v_add_f32_e32 v89, v77, v89
	v_add_f32_e32 v84, v74, v84
	v_add_f32_e32 v85, v75, v85
	v_add_f32_e32 v90, v72, v90
	v_add_f32_e32 v91, v73, v91
	v_cvt_pk_bf16_f32 v72, v88, v89
	v_cvt_pk_bf16_f32 v73, v82, v83
	v_mul_f32_e32 v89, v89, v89
	v_cvt_pk_bf16_f32 v74, v90, v91
	v_cvt_pk_bf16_f32 v75, v84, v85
	global_load_dwordx4 v[76:79], v[86:87], off offset:256
	v_mul_f32_e32 v83, v83, v83
	v_mul_f32_e32 v91, v91, v91
	v_mul_f32_e32 v85, v85, v85
	v_fmac_f32_e32 v89, v88, v88
	v_fmac_f32_e32 v83, v82, v82
	v_fmac_f32_e32 v91, v90, v90
	v_fmac_f32_e32 v85, v84, v84
	v_add_f32_e32 v82, v89, v83
	v_add_f32_e32 v83, v91, v85
	v_add_f32_e32 v88, v82, v83
	global_store_dwordx4 v[86:87], v[72:75], off sc1
	s_waitcnt vmcnt(1)
	v_lshlrev_b32_e32 v82, 16, v76
	v_and_b32_e32 v83, 0xffff0000, v76
	v_lshlrev_b32_e32 v76, 16, v77
	v_and_b32_e32 v77, 0xffff0000, v77
	v_lshlrev_b32_e32 v84, 16, v78
	v_and_b32_e32 v85, 0xffff0000, v78
	v_lshlrev_b32_e32 v78, 16, v79
	v_and_b32_e32 v79, 0xffff0000, v79
	v_add_f32_e32 v70, v70, v76
	v_add_f32_e32 v71, v71, v77
	v_add_f32_e32 v68, v68, v82
	v_add_f32_e32 v69, v69, v83
	v_add_f32_e32 v76, v66, v78
	v_add_f32_e32 v77, v67, v79
	v_add_f32_e32 v78, v64, v84
	v_add_f32_e32 v79, v65, v85
	v_mul_f32_e32 v64, v69, v69
	v_mul_f32_e32 v65, v71, v71
	v_mul_f32_e32 v66, v79, v79
	v_mul_f32_e32 v67, v77, v77
	v_fmac_f32_e32 v64, v68, v68
	v_fmac_f32_e32 v65, v70, v70
	v_fmac_f32_e32 v66, v78, v78
	v_fmac_f32_e32 v67, v76, v76
	v_add_f32_e32 v64, v64, v65
	v_add_f32_e32 v65, v66, v67
	v_add_f32_e32 v64, v64, v65
	v_add_f32_e32 v64, v88, v64
	ds_bpermute_b32 v65, v150, v64
	v_cvt_pk_bf16_f32 v66, v68, v69
	v_cvt_pk_bf16_f32 v67, v70, v71
	v_cvt_pk_bf16_f32 v68, v78, v79
	v_cvt_pk_bf16_f32 v69, v76, v77
	s_waitcnt lgkmcnt(0)
	v_add_f32_e32 v64, v64, v65
	ds_bpermute_b32 v65, v151, v64
	global_store_dwordx4 v[86:87], v[66:69], off offset:256 sc1
	s_and_saveexec_b64 s[28:29], s[4:5]
	s_cbranch_execz .LBB0_2027
	s_waitcnt lgkmcnt(0)
	v_add_f32_e32 v66, v64, v65
	v_lshl_add_u64 v[64:65], v[80:81], 2, s[16:17]
	global_atomic_add_f32 v[64:65], v66, off
; __device__ __forceinline__ unsigned cvt_pk_bf16(float lo, float hi) { unsigned r; asm volatile("v_cvt_pk_bf16_f32 %0, %1, %2" : "=v"(r) : "v"(lo), "v"(hi)); return r; }
; DI float shx(float v, int mask, int lane) { return __int_as_float(__builtin_amdgcn_ds_bpermute((lane ^ mask) << 2, __float_as_int(v))); }
;     DI void operator()(const f32x4 (&acc)[2][2][4][2], const Unit& u, int wr, int wc, int fr, int fq) const {
;     ...
;             for (int m = 0; m < 4; ++m) { const int row = row0 + ai * 128 + m * 16; const size_t off = (size_t)row * 1024 + col0; float ss = 0.f;
; #pragma unroll
;                 for (int bj = 0; bj < 2; ++bj) { const size_t o = off + bj * 128; const u32x4 r_ = *(const u32x4*)(x1b + o); f32x4 v0, v1;
;                     v0[0] = __uint_as_float(r_.x << 16); v0[1] = __uint_as_float(r_.x & 0xffff0000u); v0[2] = __uint_as_float(r_.y << 16); v0[3] = __uint_as_float(r_.y & 0xffff0000u);
;                     v1[0] = __uint_as_float(r_.z << 16); v1[1] = __uint_as_float(r_.z & 0xffff0000u); v1[2] = __uint_as_float(r_.w << 16); v1[3] = __uint_as_float(r_.w & 0xffff0000u);
;                     v0 = v0 + acc[ai][bj][m][0]; v1 = v1 + acc[ai][bj][m][1];
;                     ss += ((v0[0] * v0[0] + v0[1] * v0[1]) + (v0[2] * v0[2] + v0[3] * v0[3])) + ((v1[0] * v1[0] + v1[1] * v1[1]) + (v1[2] * v1[2] + v1[3] * v1[3]));
;                     u32x4 w; w.x = cvt_pk_bf16(v0[0], v0[1]); w.y = cvt_pk_bf16(v0[2], v0[3]); w.z = cvt_pk_bf16(v1[0], v1[1]); w.w = cvt_pk_bf16(v1[2], v1[3]); *(u32x4*)(x1b + o) = w; }
;                 { const int ln_ = fq * 16 + fr; ss += shx(ss, 16, ln_); ss += shx(ss, 32, ln_); }
;                 if (fq == 0) unsafeAtomicAdd(ssum2 + row, ss); }
.LBB0_2027:
	s_or_b64 exec, exec, s[28:29]
	v_add_u32_e32 v64, 0x80, v146
	s_waitcnt lgkmcnt(0)
	v_ashrrev_i32_e32 v65, 31, v64
	v_lshlrev_b64 v[66:67], 11, v[64:65]
	v_lshl_add_u64 v[66:67], s[34:35], 0, v[66:67]
	v_lshl_add_u64 v[70:71], v[144:145], 1, v[66:67]
	global_load_dwordx4 v[66:69], v[70:71], off
	s_waitcnt vmcnt(0)
	v_lshlrev_b32_e32 v72, 16, v66
	v_and_b32_e32 v73, 0xffff0000, v66
	v_lshlrev_b32_e32 v66, 16, v67
	v_and_b32_e32 v67, 0xffff0000, v67
	v_lshlrev_b32_e32 v74, 16, v68
	v_and_b32_e32 v75, 0xffff0000, v68
	v_lshlrev_b32_e32 v68, 16, v69
	v_and_b32_e32 v69, 0xffff0000, v69
	v_add_f32_e32 v66, v62, v66
	v_add_f32_e32 v67, v63, v67
	v_add_f32_e32 v72, v60, v72
	v_add_f32_e32 v73, v61, v73
	v_add_f32_e32 v68, v58, v68
	v_add_f32_e32 v69, v59, v69
	v_add_f32_e32 v74, v56, v74
	v_add_f32_e32 v75, v57, v75
	v_cvt_pk_bf16_f32 v56, v72, v73
	v_cvt_pk_bf16_f32 v57, v66, v67
	v_mul_f32_e32 v73, v73, v73
	v_cvt_pk_bf16_f32 v58, v74, v75
	v_cvt_pk_bf16_f32 v59, v68, v69
	global_load_dwordx4 v[60:63], v[70:71], off offset:256
	v_mul_f32_e32 v67, v67, v67
	v_mul_f32_e32 v75, v75, v75
	v_mul_f32_e32 v69, v69, v69
	v_fmac_f32_e32 v73, v72, v72
	v_fmac_f32_e32 v67, v66, v66
	v_fmac_f32_e32 v75, v74, v74
	v_fmac_f32_e32 v69, v68, v68
	v_add_f32_e32 v66, v73, v67
	v_add_f32_e32 v67, v75, v69
	v_add_f32_e32 v72, v66, v67
	global_store_dwordx4 v[70:71], v[56:59], off sc1
	s_waitcnt vmcnt(1)
	v_lshlrev_b32_e32 v66, 16, v60
	v_and_b32_e32 v67, 0xffff0000, v60
	v_lshlrev_b32_e32 v60, 16, v61
	v_and_b32_e32 v61, 0xffff0000, v61
	v_lshlrev_b32_e32 v68, 16, v62
	v_and_b32_e32 v69, 0xffff0000, v62
	v_lshlrev_b32_e32 v62, 16, v63
	v_and_b32_e32 v63, 0xffff0000, v63
	v_add_f32_e32 v54, v54, v60
	v_add_f32_e32 v55, v55, v61
	v_add_f32_e32 v52, v52, v66
	v_add_f32_e32 v53, v53, v67
	v_add_f32_e32 v60, v50, v62
	v_add_f32_e32 v61, v51, v63
	v_add_f32_e32 v62, v48, v68
	v_add_f32_e32 v63, v49, v69
	v_mul_f32_e32 v48, v53, v53
	v_mul_f32_e32 v49, v55, v55
	v_mul_f32_e32 v50, v63, v63
	v_mul_f32_e32 v51, v61, v61
	v_fmac_f32_e32 v48, v52, v52
	v_fmac_f32_e32 v49, v54, v54
	v_fmac_f32_e32 v50, v62, v62
	v_fmac_f32_e32 v51, v60, v60
	v_add_f32_e32 v48, v48, v49
	v_add_f32_e32 v49, v50, v51
	v_add_f32_e32 v48, v48, v49
	v_add_f32_e32 v48, v72, v48
	ds_bpermute_b32 v49, v150, v48
	v_cvt_pk_bf16_f32 v50, v52, v53
	v_cvt_pk_bf16_f32 v51, v54, v55
	v_cvt_pk_bf16_f32 v52, v62, v63
	v_cvt_pk_bf16_f32 v53, v60, v61
	s_waitcnt lgkmcnt(0)
	v_add_f32_e32 v48, v48, v49
	ds_bpermute_b32 v49, v151, v48
	global_store_dwordx4 v[70:71], v[50:53], off offset:256 sc1
	s_and_saveexec_b64 s[28:29], s[4:5]
	s_cbranch_execz .LBB0_2029
	s_waitcnt lgkmcnt(0)
	v_add_f32_e32 v50, v48, v49
	v_lshl_add_u64 v[48:49], v[64:65], 2, s[16:17]
	global_atomic_add_f32 v[48:49], v50, off
.LBB0_2029:
	s_or_b64 exec, exec, s[28:29]
	v_add_u32_e32 v48, 0x90, v146
	s_waitcnt lgkmcnt(0)
	v_ashrrev_i32_e32 v49, 31, v48
	v_lshlrev_b64 v[50:51], 11, v[48:49]
	v_lshl_add_u64 v[50:51], s[34:35], 0, v[50:51]
	v_lshl_add_u64 v[54:55], v[144:145], 1, v[50:51]
	global_load_dwordx4 v[50:53], v[54:55], off
	s_waitcnt vmcnt(0)
	v_lshlrev_b32_e32 v56, 16, v50
	v_and_b32_e32 v57, 0xffff0000, v50
	v_lshlrev_b32_e32 v50, 16, v51
	v_and_b32_e32 v51, 0xffff0000, v51
	v_lshlrev_b32_e32 v58, 16, v52
	v_and_b32_e32 v59, 0xffff0000, v52
	v_lshlrev_b32_e32 v52, 16, v53
	v_and_b32_e32 v53, 0xffff0000, v53
	v_add_f32_e32 v50, v46, v50
	v_add_f32_e32 v51, v47, v51
	v_add_f32_e32 v56, v44, v56
	v_add_f32_e32 v57, v45, v57
	v_add_f32_e32 v52, v42, v52
	v_add_f32_e32 v53, v43, v53
	v_add_f32_e32 v58, v40, v58
	v_add_f32_e32 v59, v41, v59
	v_cvt_pk_bf16_f32 v40, v56, v57
	v_cvt_pk_bf16_f32 v41, v50, v51
	v_mul_f32_e32 v57, v57, v57
	v_cvt_pk_bf16_f32 v42, v58, v59
	v_cvt_pk_bf16_f32 v43, v52, v53
	global_load_dwordx4 v[44:47], v[54:55], off offset:256
	v_mul_f32_e32 v51, v51, v51
	v_mul_f32_e32 v59, v59, v59
	v_mul_f32_e32 v53, v53, v53
	v_fmac_f32_e32 v57, v56, v56
	v_fmac_f32_e32 v51, v50, v50
	v_fmac_f32_e32 v59, v58, v58
	v_fmac_f32_e32 v53, v52, v52
	v_add_f32_e32 v50, v57, v51
	v_add_f32_e32 v51, v59, v53
	v_add_f32_e32 v56, v50, v51
	global_store_dwordx4 v[54:55], v[40:43], off sc1
	s_waitcnt vmcnt(1)
	v_lshlrev_b32_e32 v50, 16, v44
	v_and_b32_e32 v51, 0xffff0000, v44
	v_lshlrev_b32_e32 v44, 16, v45
	v_and_b32_e32 v45, 0xffff0000, v45
	v_lshlrev_b32_e32 v52, 16, v46
	v_and_b32_e32 v53, 0xffff0000, v46
	v_lshlrev_b32_e32 v46, 16, v47
	v_and_b32_e32 v47, 0xffff0000, v47
	v_add_f32_e32 v38, v38, v44
	v_add_f32_e32 v39, v39, v45
	v_add_f32_e32 v36, v36, v50
	v_add_f32_e32 v37, v37, v51
	v_add_f32_e32 v44, v34, v46
	v_add_f32_e32 v45, v35, v47
	v_add_f32_e32 v46, v32, v52
	v_add_f32_e32 v47, v33, v53
	v_mul_f32_e32 v32, v37, v37
	v_mul_f32_e32 v33, v39, v39
	v_mul_f32_e32 v34, v47, v47
	v_mul_f32_e32 v35, v45, v45
	v_fmac_f32_e32 v32, v36, v36
	v_fmac_f32_e32 v33, v38, v38
	v_fmac_f32_e32 v34, v46, v46
	v_fmac_f32_e32 v35, v44, v44
	v_add_f32_e32 v32, v32, v33
	v_add_f32_e32 v33, v34, v35
	v_add_f32_e32 v32, v32, v33
	v_add_f32_e32 v32, v56, v32
	ds_bpermute_b32 v33, v150, v32
	v_cvt_pk_bf16_f32 v34, v36, v37
	v_cvt_pk_bf16_f32 v35, v38, v39
	v_cvt_pk_bf16_f32 v36, v46, v47
	v_cvt_pk_bf16_f32 v37, v44, v45
	s_waitcnt lgkmcnt(0)
	v_add_f32_e32 v32, v32, v33
	ds_bpermute_b32 v33, v151, v32
	global_store_dwordx4 v[54:55], v[34:37], off offset:256 sc1
	s_and_saveexec_b64 s[28:29], s[4:5]
	s_cbranch_execz .LBB0_2031
	s_waitcnt lgkmcnt(0)
	v_add_f32_e32 v34, v32, v33
	v_lshl_add_u64 v[32:33], v[48:49], 2, s[16:17]
	global_atomic_add_f32 v[32:33], v34, off
; __device__ __forceinline__ unsigned cvt_pk_bf16(float lo, float hi) { unsigned r; asm volatile("v_cvt_pk_bf16_f32 %0, %1, %2" : "=v"(r) : "v"(lo), "v"(hi)); return r; }
; DI float shx(float v, int mask, int lane) { return __int_as_float(__builtin_amdgcn_ds_bpermute((lane ^ mask) << 2, __float_as_int(v))); }
;     DI void operator()(const f32x4 (&acc)[2][2][4][2], const Unit& u, int wr, int wc, int fr, int fq) const {
;     ...
;             for (int m = 0; m < 4; ++m) { const int row = row0 + ai * 128 + m * 16; const size_t off = (size_t)row * 1024 + col0; float ss = 0.f;
; #pragma unroll
;                 for (int bj = 0; bj < 2; ++bj) { const size_t o = off + bj * 128; const u32x4 r_ = *(const u32x4*)(x1b + o); f32x4 v0, v1;
;                     v0[0] = __uint_as_float(r_.x << 16); v0[1] = __uint_as_float(r_.x & 0xffff0000u); v0[2] = __uint_as_float(r_.y << 16); v0[3] = __uint_as_float(r_.y & 0xffff0000u);
;                     v1[0] = __uint_as_float(r_.z << 16); v1[1] = __uint_as_float(r_.z & 0xffff0000u); v1[2] = __uint_as_float(r_.w << 16); v1[3] = __uint_as_float(r_.w & 0xffff0000u);
;                     v0 = v0 + acc[ai][bj][m][0]; v1 = v1 + acc[ai][bj][m][1];
;                     ss += ((v0[0] * v0[0] + v0[1] * v0[1]) + (v0[2] * v0[2] + v0[3] * v0[3])) + ((v1[0] * v1[0] + v1[1] * v1[1]) + (v1[2] * v1[2] + v1[3] * v1[3]));
;                     u32x4 w; w.x = cvt_pk_bf16(v0[0], v0[1]); w.y = cvt_pk_bf16(v0[2], v0[3]); w.z = cvt_pk_bf16(v1[0], v1[1]); w.w = cvt_pk_bf16(v1[2], v1[3]); *(u32x4*)(x1b + o) = w; }
;                 { const int ln_ = fq * 16 + fr; ss += shx(ss, 16, ln_); ss += shx(ss, 32, ln_); }
;                 if (fq == 0) unsafeAtomicAdd(ssum2 + row, ss); }
.LBB0_2031:
	s_or_b64 exec, exec, s[28:29]
	v_add_u32_e32 v32, 0xa0, v146
	s_waitcnt lgkmcnt(0)
	v_ashrrev_i32_e32 v33, 31, v32
	v_lshlrev_b64 v[34:35], 11, v[32:33]
	v_lshl_add_u64 v[34:35], s[34:35], 0, v[34:35]
	v_lshl_add_u64 v[38:39], v[144:145], 1, v[34:35]
	global_load_dwordx4 v[34:37], v[38:39], off
	s_waitcnt vmcnt(0)
	v_lshlrev_b32_e32 v40, 16, v34
	v_and_b32_e32 v41, 0xffff0000, v34
	v_lshlrev_b32_e32 v34, 16, v35
	v_and_b32_e32 v35, 0xffff0000, v35
	v_lshlrev_b32_e32 v42, 16, v36
	v_and_b32_e32 v43, 0xffff0000, v36
	v_lshlrev_b32_e32 v36, 16, v37
	v_and_b32_e32 v37, 0xffff0000, v37
	v_add_f32_e32 v34, v30, v34
	v_add_f32_e32 v35, v31, v35
	v_add_f32_e32 v40, v28, v40
	v_add_f32_e32 v41, v29, v41
	v_add_f32_e32 v36, v26, v36
	v_add_f32_e32 v37, v27, v37
	v_add_f32_e32 v42, v24, v42
	v_add_f32_e32 v43, v25, v43
	v_cvt_pk_bf16_f32 v24, v40, v41
	v_cvt_pk_bf16_f32 v25, v34, v35
	v_mul_f32_e32 v41, v41, v41
	v_cvt_pk_bf16_f32 v26, v42, v43
	v_cvt_pk_bf16_f32 v27, v36, v37
	global_load_dwordx4 v[28:31], v[38:39], off offset:256
	v_mul_f32_e32 v35, v35, v35
	v_mul_f32_e32 v43, v43, v43
	v_mul_f32_e32 v37, v37, v37
	v_fmac_f32_e32 v41, v40, v40
	v_fmac_f32_e32 v35, v34, v34
	v_fmac_f32_e32 v43, v42, v42
	v_fmac_f32_e32 v37, v36, v36
	v_add_f32_e32 v34, v41, v35
	v_add_f32_e32 v35, v43, v37
	v_add_f32_e32 v40, v34, v35
	global_store_dwordx4 v[38:39], v[24:27], off sc1
	s_waitcnt vmcnt(1)
	v_lshlrev_b32_e32 v34, 16, v28
	v_and_b32_e32 v35, 0xffff0000, v28
	v_lshlrev_b32_e32 v28, 16, v29
	v_and_b32_e32 v29, 0xffff0000, v29
	v_lshlrev_b32_e32 v36, 16, v30
	v_and_b32_e32 v37, 0xffff0000, v30
	v_lshlrev_b32_e32 v30, 16, v31
	v_and_b32_e32 v31, 0xffff0000, v31
	v_add_f32_e32 v22, v22, v28
	v_add_f32_e32 v23, v23, v29
	v_add_f32_e32 v20, v20, v34
	v_add_f32_e32 v21, v21, v35
	v_add_f32_e32 v28, v18, v30
	v_add_f32_e32 v29, v19, v31
	v_add_f32_e32 v30, v16, v36
	v_add_f32_e32 v31, v17, v37
	v_mul_f32_e32 v16, v21, v21
	v_mul_f32_e32 v17, v23, v23
	v_mul_f32_e32 v18, v31, v31
	v_mul_f32_e32 v19, v29, v29
	v_fmac_f32_e32 v16, v20, v20
	v_fmac_f32_e32 v17, v22, v22
	v_fmac_f32_e32 v18, v30, v30
	v_fmac_f32_e32 v19, v28, v28
	v_add_f32_e32 v16, v16, v17
	v_add_f32_e32 v17, v18, v19
	v_add_f32_e32 v16, v16, v17
	v_add_f32_e32 v16, v40, v16
	ds_bpermute_b32 v17, v150, v16
	v_cvt_pk_bf16_f32 v18, v20, v21
	v_cvt_pk_bf16_f32 v19, v22, v23
	v_cvt_pk_bf16_f32 v20, v30, v31
	v_cvt_pk_bf16_f32 v21, v28, v29
	s_waitcnt lgkmcnt(0)
	v_add_f32_e32 v16, v16, v17
	ds_bpermute_b32 v17, v151, v16
	global_store_dwordx4 v[38:39], v[18:21], off offset:256 sc1
	s_and_saveexec_b64 s[28:29], s[4:5]
	s_cbranch_execz .LBB0_2033
	s_waitcnt lgkmcnt(0)
	v_add_f32_e32 v18, v16, v17
	v_lshl_add_u64 v[16:17], v[32:33], 2, s[16:17]
	global_atomic_add_f32 v[16:17], v18, off
.LBB0_2033:
	s_or_b64 exec, exec, s[28:29]
	v_add_u32_e32 v16, 0xb0, v146
	s_waitcnt lgkmcnt(0)
	v_ashrrev_i32_e32 v17, 31, v16
	v_lshlrev_b64 v[18:19], 11, v[16:17]
	v_lshl_add_u64 v[18:19], s[34:35], 0, v[18:19]
	v_lshl_add_u64 v[22:23], v[144:145], 1, v[18:19]
	global_load_dwordx4 v[18:21], v[22:23], off
	s_waitcnt vmcnt(0)
	v_lshlrev_b32_e32 v24, 16, v18
	v_and_b32_e32 v25, 0xffff0000, v18
	v_lshlrev_b32_e32 v18, 16, v19
	v_and_b32_e32 v19, 0xffff0000, v19
	v_lshlrev_b32_e32 v26, 16, v20
	v_and_b32_e32 v27, 0xffff0000, v20
	v_lshlrev_b32_e32 v20, 16, v21
	v_and_b32_e32 v21, 0xffff0000, v21
	v_add_f32_e32 v18, v14, v18
	v_add_f32_e32 v19, v15, v19
	v_add_f32_e32 v24, v12, v24
	v_add_f32_e32 v25, v13, v25
	v_add_f32_e32 v20, v10, v20
	v_add_f32_e32 v21, v11, v21
	v_add_f32_e32 v26, v8, v26
	v_add_f32_e32 v27, v9, v27
	v_cvt_pk_bf16_f32 v8, v24, v25
	v_cvt_pk_bf16_f32 v9, v18, v19
	v_mul_f32_e32 v25, v25, v25
	v_cvt_pk_bf16_f32 v10, v26, v27
	v_cvt_pk_bf16_f32 v11, v20, v21
	global_load_dwordx4 v[12:15], v[22:23], off offset:256
	v_mul_f32_e32 v19, v19, v19
	v_mul_f32_e32 v27, v27, v27
	v_mul_f32_e32 v21, v21, v21
	v_fmac_f32_e32 v25, v24, v24
	v_fmac_f32_e32 v19, v18, v18
	v_fmac_f32_e32 v27, v26, v26
	v_fmac_f32_e32 v21, v20, v20
	v_add_f32_e32 v18, v25, v19
	v_add_f32_e32 v19, v27, v21
	v_add_f32_e32 v24, v18, v19
	global_store_dwordx4 v[22:23], v[8:11], off sc1
	s_waitcnt vmcnt(1)
	v_lshlrev_b32_e32 v18, 16, v12
	v_and_b32_e32 v19, 0xffff0000, v12
	v_lshlrev_b32_e32 v12, 16, v13
	v_and_b32_e32 v13, 0xffff0000, v13
	v_lshlrev_b32_e32 v20, 16, v14
	v_and_b32_e32 v21, 0xffff0000, v14
	v_lshlrev_b32_e32 v14, 16, v15
	v_and_b32_e32 v15, 0xffff0000, v15
	v_add_f32_e32 v6, v6, v12
	v_add_f32_e32 v7, v7, v13
	v_add_f32_e32 v4, v4, v18
	v_add_f32_e32 v5, v5, v19
	v_add_f32_e32 v12, v2, v14
	v_add_f32_e32 v13, v3, v15
	v_add_f32_e32 v14, v0, v20
	v_add_f32_e32 v15, v1, v21
	v_mul_f32_e32 v0, v5, v5
	v_mul_f32_e32 v1, v7, v7
	v_mul_f32_e32 v2, v15, v15
	v_mul_f32_e32 v3, v13, v13
	v_fmac_f32_e32 v0, v4, v4
	v_fmac_f32_e32 v1, v6, v6
	v_fmac_f32_e32 v2, v14, v14
	v_fmac_f32_e32 v3, v12, v12
	v_add_f32_e32 v0, v0, v1
	v_add_f32_e32 v1, v2, v3
	v_add_f32_e32 v0, v0, v1
	v_add_f32_e32 v0, v24, v0
	ds_bpermute_b32 v1, v150, v0
	v_cvt_pk_bf16_f32 v2, v4, v5
	v_cvt_pk_bf16_f32 v3, v6, v7
	v_cvt_pk_bf16_f32 v4, v14, v15
	v_cvt_pk_bf16_f32 v5, v12, v13
	s_waitcnt lgkmcnt(0)
	v_add_f32_e32 v0, v0, v1
	ds_bpermute_b32 v1, v151, v0
	global_store_dwordx4 v[22:23], v[2:5], off offset:256 sc1
	s_and_saveexec_b64 s[28:29], s[4:5]
	s_cbranch_execz .LBB0_2035
	s_waitcnt lgkmcnt(0)
	v_add_f32_e32 v2, v0, v1
	v_lshl_add_u64 v[0:1], v[16:17], 2, s[16:17]
	global_atomic_add_f32 v[0:1], v2, off
